# plus GLA log-decay cache: M1 stores bc[24] (f32) per wave-item into the idle H buffer, M3 loads it; select->mov + dead-code elimination of the recomputation
# speedup vs baseline: 1.0350x; 1.0052x over previous
; template <bool PHC>
; __device__ __forceinline__ void gla_pair(const KPD& kp, int l, int pair, unsigned char* lds, int tid, int lane, int wave, v4u& pz0, v4u& pz1, v4u& pw0, v4u& pw1, int next_pair) {
;     const int half = wave >> 2, w4 = wave & 3, t4 = tid & 255;
;     const int item = 2 * pair + half;
;     const int h = item & 3, sc = item >> 2; int b, n, rowbase; chunk_coords(sc, b, n, rowbase);
;     unsigned char* L = lds + half * 69632;
;     const bf16* P = (const bf16*)(kp.ws() + WS_P);
;     float* ST = (float*)(kp.ws() + WS_ST); float* DEC = (float*)(kp.ws() + WS_DEC);
;     const int dir = w4 >> 1, d0 = 24 * (w4 & 1);
;     const bf16* prow = P + (size_t)(rowbase + lane) * INP;
;     v4u vpre[3];
; #pragma unroll
;     for (int i = 0; i < 3; ++i) { const int idx = t4 + 256 * i; vpre[i] = *(const v4u*)(P + (size_t)(rowbase + idx / 12) * INP + C_GV + h * 96 + 8 * (idx % 12)); }
;     v2u spre[9];
;     if constexpr (PHC) { const bf16* SI = (const bf16*)(kp.ws() + WS_SI);
; #pragma unroll
;         for (int i = 0; i < 9; ++i) { const int idx = t4 + 256 * i; const int dd = idx / 1152, e = (idx % 1152) * 4;
;             spre[i] = *(const v2u*)(SI + ((size_t)((dd * 4 + b) * NCH + n) * 4 + h) * 4608 + e); }
;     }
;     float z[16];
;     { const v4u z0 = pz0, z1 = pz1;
;       z[0] = lo16(z0.x); z[1] = hi16(z0.x); z[2] = lo16(z0.y); z[3] = hi16(z0.y); z[4] = lo16(z0.z); z[5] = hi16(z0.z); z[6] = lo16(z0.w); z[7] = hi16(z0.w);
;       z[8] = lo16(z1.x); z[9] = hi16(z1.x); z[10] = lo16(z1.y); z[11] = hi16(z1.y); z[12] = lo16(z1.z); z[13] = hi16(z1.z); z[14] = lo16(z1.w); z[15] = hi16(z1.w); }
;     v4u qraw[3], kraw[3];
; #pragma unroll
;     for (int i = 0; i < 3; ++i) { qraw[i] = *((const v4u*)(prow + C_GQ + h * 48 + d0) + i); kraw[i] = *((const v4u*)(prow + C_GK + h * 48 + d0) + i); }
;     const int wvv[6] = {(int)pw0.x, (int)pw0.y, (int)pw0.z, (int)pw0.w, (int)pw1.x, (int)pw1.y};
;     const int bvv = (int)pw1.z;
;     float bc[24], tot[24];
; #pragma unroll
;     for (int c = 0; c < 24; ++c) {
;         float pre = __int_as_float(__builtin_amdgcn_readlane(bvv, c));
; #pragma unroll
;         for (int r = 0; r < 16; ++r) pre += z[r] * __int_as_float(__builtin_amdgcn_readlane(wvv[(24 * r + c) >> 6], (24 * r + c) & 63));
;         const float la = (fminf(pre, 0.f) - __logf(1.f + __expf(-fabsf(pre)))) * (1.f / 16.f);
.LBB0_264:
	ds_read_b64 v[250:251], v204
	v_readfirstlane_b32 vcc_lo, v225
	s_lshl_b32 vcc_hi, s10, 2
	s_lshr_b32 vcc_lo, vcc_lo, 6
	s_and_b32 vcc_lo, vcc_lo, 3
	s_add_i32 vcc_lo, vcc_lo, vcc_hi
	s_mul_i32 vcc_lo, vcc_lo, 0x1800
	s_waitcnt lgkmcnt(0)
	v_readfirstlane_b32 s100, v250
	v_readfirstlane_b32 s101, v251
	v_mbcnt_lo_u32_b32 v250, -1, 0
	v_mbcnt_hi_u32_b32 v250, -1, v250
	s_add_u32 s100, s100, 0x3400000
	s_addc_u32 s101, s101, 0
	s_add_u32 s100, s100, vcc_lo
	s_addc_u32 s101, s101, 0
	v_lshlrev_b32_e32 v250, 2, v250
	v_add_u32_e32 v251, 0x1000, v250
	ds_read_b64 v[2:3], v204
	s_lshl_b32 s2, s12, 6
	s_and_b32 s46, s10, 3
	s_add_i32 s10, s11, s2
	v_add_u32_e32 v16, s10, v120
	s_waitcnt lgkmcnt(0)
	v_readfirstlane_b32 s3, v3
	v_readfirstlane_b32 s2, v2
	ds_read_b64 v[2:3], v204
	s_add_u32 s2, s2, 0x7800000
	s_addc_u32 s3, s3, 0
	v_mov_b64_e32 v[14:15], s[2:3]
	v_add_u32_e32 v6, s10, v37
	s_waitcnt lgkmcnt(0)
	v_readfirstlane_b32 s47, v3
	v_readfirstlane_b32 s48, v2
	ds_read_b64 v[2:3], v204
	v_add_u32_e32 v10, s10, v121
	v_mad_i64_i32 v[6:7], s[2:3], v6, s33, v[14:15]
	v_mad_i64_i32 v[10:11], s[2:3], v10, s33, v[14:15]
	s_waitcnt lgkmcnt(0)
	v_readfirstlane_b32 s50, v2
	v_add_u32_e32 v2, s10, v33
	v_readfirstlane_b32 s49, v3
	v_mad_i64_i32 v[2:3], s[2:3], v2, s33, v[14:15]
	v_mad_i64_i32 v[14:15], s[2:3], v16, s33, v[14:15]
	s_waitcnt vmcnt(0)
	v_readlane_b32 s2, v32, 0
	v_lshlrev_b32_e32 v64, 16, v18
	v_readlane_b32 s3, v26, 0
	v_mov_b32_e32 v38, s2
	v_and_b32_e32 v63, 0xffff0000, v18
	v_fmac_f32_e32 v38, s3, v64
	v_readlane_b32 s2, v26, 24
	v_lshlrev_b32_e32 v62, 16, v19
	v_and_b32_e32 v61, 0xffff0000, v19
	v_fmac_f32_e32 v38, s2, v63
	v_readlane_b32 s2, v26, 48
	v_lshlrev_b32_e32 v60, 16, v20
	v_and_b32_e32 v59, 0xffff0000, v20
	v_fmac_f32_e32 v38, s2, v62
	v_readlane_b32 s2, v27, 8
	v_lshlrev_b32_e32 v58, 16, v21
	v_and_b32_e32 v57, 0xffff0000, v21
	v_fmac_f32_e32 v38, s2, v61
	v_readlane_b32 s2, v27, 32
	v_lshlrev_b32_e32 v56, 16, v22
	v_and_b32_e32 v55, 0xffff0000, v22
	v_fmac_f32_e32 v38, s2, v60
	v_readlane_b32 s2, v27, 56
	v_lshlrev_b32_e32 v54, 16, v23
	v_and_b32_e32 v53, 0xffff0000, v23
	v_fmac_f32_e32 v38, s2, v59
	v_readlane_b32 s2, v28, 16
	v_lshlrev_b32_e32 v52, 16, v24
	v_and_b32_e32 v34, 0xffff0000, v24
	v_fmac_f32_e32 v38, s2, v58
	v_readlane_b32 s2, v28, 40
	v_readlane_b32 s10, v31, 16
	v_readlane_b32 s11, v31, 40
	v_fmac_f32_e32 v38, s2, v57
	v_readlane_b32 s2, v29, 0
	v_lshlrev_b32_e32 v50, 16, v25
	v_and_b32_e32 v51, 0xffff0000, v25
	v_fmac_f32_e32 v38, s2, v56
	v_readlane_b32 s2, v29, 24
	v_pk_mul_f32 v[66:67], v[50:51], s[10:11]
	s_mov_b32 s72, 0xbfb8aa3b
	v_fmac_f32_e32 v38, s2, v55
	v_readlane_b32 s2, v29, 48
	s_mul_i32 s78, s46, 0xc0
	s_mul_i32 s51, s46, 48
	v_fmac_f32_e32 v38, s2, v54
	v_readlane_b32 s2, v30, 8
	v_lshl_add_u64 v[2:3], v[2:3], 0, s[78:79]
	v_lshl_add_u64 v[6:7], v[6:7], 0, s[78:79]
	v_fmac_f32_e32 v38, s2, v53
	v_readlane_b32 s2, v30, 32
	v_lshl_add_u64 v[10:11], v[10:11], 0, s[78:79]
	s_lshl_b32 s78, s51, 1
	v_fmac_f32_e32 v38, s2, v52
	v_readlane_b32 s2, v30, 56
	v_lshl_add_u64 v[14:15], v[14:15], 0, s[78:79]
	s_lshl_b32 s78, s40, 1
	v_fmac_f32_e32 v38, s2, v34
	v_add_f32_e32 v38, v38, v66
	v_add_f32_e32 v38, v38, v67
	v_min_f32_e32 v65, 0, v38
	v_mul_f32_e64 v38, |v38|, s72
	v_exp_f32_e32 v38, v38
	v_lshl_add_u64 v[46:47], v[14:15], 0, s[78:79]
	s_mov_b32 s78, 0x800000
	s_mov_b32 s87, 0x3f317217
	v_add_f32_e32 v38, 1.0, v38
	v_cmp_gt_f32_e32 vcc, s78, v38
	s_mov_b32 s97, 0x7f800000
	v_readlane_b32 s2, v32, 1
	v_cndmask_b32_e64 v66, 0, 32, vcc
	v_ldexp_f32 v38, v38, v66
	v_log_f32_e32 v38, v38
	v_readlane_b32 s3, v26, 1
	v_mov_b32_e32 v39, s2
	v_readlane_b32 s2, v26, 25
	v_mul_f32_e32 v66, 0x3f317217, v38
	v_fma_f32 v66, v38, s87, -v66
	v_fmac_f32_e32 v66, 0x3377d1cf, v38
	v_fmac_f32_e32 v66, 0x3f317217, v38
	v_cmp_lt_f32_e64 s[10:11], |v38|, s97
	v_fmac_f32_e32 v39, s3, v64
	v_fmac_f32_e32 v39, s2, v63
	v_cndmask_b32_e64 v38, v38, v66, s[10:11]
	v_cndmask_b32_e32 v66, 0, v222, vcc
	v_sub_f32_e32 v38, v38, v66
	v_sub_f32_e32 v38, v65, v38
	v_mul_f32_e32 v65, 0x3d800000, v38
	v_readlane_b32 s2, v26, 49
	v_mov_b32_e32 v66, v35
	v_mov_b32_dpp v65, v65 row_shr:1 row_mask:0xf bank_mask:0xf bound_ctrl:1
	v_fmac_f32_e32 v39, s2, v62
	v_readlane_b32 s2, v27, 9
	v_fmac_f32_e32 v65, 0x3d800000, v38
	v_readlane_b32 s36, v31, 17
	v_fmac_f32_e32 v39, s2, v61
	v_readlane_b32 s2, v27, 33
	v_add_f32_dpp v65, v65, v65 row_shr:2 row_mask:0xf bank_mask:0xf bound_ctrl:1
	v_readlane_b32 s37, v31, 41
	v_fmac_f32_e32 v39, s2, v60
	v_readlane_b32 s2, v27, 57
	v_add_f32_dpp v65, v65, v65 row_shr:4 row_mask:0xf bank_mask:0xf bound_ctrl:1
	v_readlane_b32 s3, v26, 2
	v_fmac_f32_e32 v39, s2, v59
	v_readlane_b32 s2, v28, 17
	v_add_f32_dpp v65, v65, v65 row_shr:8 row_mask:0xf bank_mask:0xf bound_ctrl:1
	v_readlane_b32 s34, v31, 18
	v_fmac_f32_e32 v39, s2, v58
	v_readlane_b32 s2, v28, 41
	v_mov_b32_dpp v66, v65 row_bcast:15 row_mask:0xa bank_mask:0xf
	v_add_f32_e32 v65, v65, v66
	v_fmac_f32_e32 v39, s2, v57
	v_readlane_b32 s2, v29, 1
	v_mov_b32_e32 v66, v35
	v_readlane_b32 s35, v31, 42
	v_fmac_f32_e32 v39, s2, v56
	v_readlane_b32 s2, v29, 25
	v_mov_b32_dpp v66, v65 row_bcast:31 row_mask:0xc bank_mask:0xf
	v_add_f32_e32 v65, v65, v66
	v_fmac_f32_e32 v39, s2, v55
	v_readlane_b32 s2, v29, 49
	v_readlane_b32 s54, v65, 63
	v_pk_mul_f32 v[94:95], v[50:51], s[34:35]
	v_fmac_f32_e32 v39, s2, v54
	v_readlane_b32 s2, v30, 9
	v_sub_f32_e32 v66, s54, v65
	v_fmac_f32_e32 v66, 0x3d800000, v38
	v_fmac_f32_e32 v39, s2, v53
	v_readlane_b32 s2, v30, 33
	v_cndmask_b32_e64 v65, v66, v65, s[0:1]
	global_store_dword v250, v65, s[100:101]
;     __device__ __forceinline__ unsigned char* ws() const { return (unsigned char*)(__attribute__((address_space(1))) unsigned char*)ld(23); }
; __device__ __forceinline__ float lo16(unsigned w) { return __uint_as_float(w << 16); }
; __device__ __forceinline__ float hi16(unsigned w) { return __uint_as_float(w & 0xffff0000u); }
; template <bool PHC>
; __device__ __forceinline__ void gla_pair(const KPD& kp, int l, int pair, unsigned char* lds, int tid, int lane, int wave, v4u& pz0, v4u& pz1, v4u& pw0, v4u& pw1, int next_pair) {
;     ...
;     for (int i = 0; i < 3; ++i) { const int idx = t4 + 256 * i; vpre[i] = *(const v4u*)(P + (size_t)(rowbase + idx / 12) * INP + C_GV + h * 96 + 8 * (idx % 12)); }
;     v2u spre[9];
;     if constexpr (PHC) { const bf16* SI = (const bf16*)(kp.ws() + WS_SI);
; #pragma unroll
;         for (int i = 0; i < 9; ++i) { const int idx = t4 + 256 * i; const int dd = idx / 1152, e = (idx % 1152) * 4;
;             spre[i] = *(const v2u*)(SI + ((size_t)((dd * 4 + b) * NCH + n) * 4 + h) * 4608 + e); }
;     }
;     float z[16];
;     { const v4u z0 = pz0, z1 = pz1;
;       z[0] = lo16(z0.x); z[1] = hi16(z0.x); z[2] = lo16(z0.y); z[3] = hi16(z0.y); z[4] = lo16(z0.z); z[5] = hi16(z0.z); z[6] = lo16(z0.w); z[7] = hi16(z0.w);
;       z[8] = lo16(z1.x); z[9] = hi16(z1.x); z[10] = lo16(z1.y); z[11] = hi16(z1.y); z[12] = lo16(z1.z); z[13] = hi16(z1.z); z[14] = lo16(z1.w); z[15] = hi16(z1.w); }
;     v4u qraw[3], kraw[3];
; #pragma unroll
;     for (int i = 0; i < 3; ++i) { qraw[i] = *((const v4u*)(prow + C_GQ + h * 48 + d0) + i); kraw[i] = *((const v4u*)(prow + C_GK + h * 48 + d0) + i); }
;     ...
; #pragma unroll
;     for (int c = 0; c < 24; ++c) {
;         float pre = __int_as_float(__builtin_amdgcn_readlane(bvv, c));
; #pragma unroll
;         for (int r = 0; r < 16; ++r) pre += z[r] * __int_as_float(__builtin_amdgcn_readlane(wvv[(24 * r + c) >> 6], (24 * r + c) & 63));
;         const float la = (fminf(pre, 0.f) - __logf(1.f + __expf(-fabsf(pre)))) * (1.f / 16.f);
;         const float inc = wave_incl_scan(la);
;         const float total = __int_as_float(__builtin_amdgcn_readlane(__float_as_int(inc), 63));
;         bc[c] = dir ? (total - inc + la) : inc; tot[c] = total;
	v_pk_mul_f32 v[66:67], v[50:51], s[36:37]
	v_fmac_f32_e32 v39, s2, v52
	v_readlane_b32 s2, v30, 57
	v_readlane_b32 s30, v31, 19
	v_readlane_b32 s31, v31, 43
	v_fmac_f32_e32 v39, s2, v34
	v_add_f32_e32 v38, v39, v66
	v_add_f32_e32 v38, v38, v67
	v_min_f32_e32 v39, 0, v38
	v_mul_f32_e64 v38, |v38|, s72
	v_exp_f32_e32 v38, v38
	v_readlane_b32 s2, v32, 2
	v_readlane_b32 s28, v31, 20
	v_readlane_b32 s29, v31, 44
	v_add_f32_e32 v38, 1.0, v38
	v_cmp_gt_f32_e32 vcc, s78, v38
	v_mov_b32_e32 v40, s2
	v_fmac_f32_e32 v40, s3, v64
	v_cndmask_b32_e64 v66, 0, 32, vcc
	v_ldexp_f32 v38, v38, v66
	v_log_f32_e32 v38, v38
	v_readlane_b32 s2, v26, 26
	v_readlane_b32 s3, v26, 3
	v_mov_b32_e32 v79, v35
	v_mul_f32_e32 v66, 0x3f317217, v38
	v_fma_f32 v66, v38, s87, -v66
	v_fmac_f32_e32 v66, 0x3377d1cf, v38
	v_fmac_f32_e32 v66, 0x3f317217, v38
	v_cmp_lt_f32_e64 s[10:11], |v38|, s97
	v_fmac_f32_e32 v40, s2, v63
	v_readlane_b32 s2, v26, 50
	v_cndmask_b32_e64 v38, v38, v66, s[10:11]
	v_cndmask_b32_e32 v66, 0, v222, vcc
	v_sub_f32_e32 v38, v38, v66
	v_sub_f32_e32 v38, v39, v38
	v_fmac_f32_e32 v40, s2, v62
	v_readlane_b32 s2, v27, 10
	v_mul_f32_e32 v39, 0x3d800000, v38
	v_mov_b32_e32 v66, v35
	v_fmac_f32_e32 v40, s2, v61
	v_readlane_b32 s2, v27, 34
	v_mov_b32_dpp v39, v39 row_shr:1 row_mask:0xf bank_mask:0xf bound_ctrl:1
	v_fmac_f32_e32 v39, 0x3d800000, v38
	v_fmac_f32_e32 v40, s2, v60
	v_readlane_b32 s2, v27, 58
	v_add_f32_dpp v39, v39, v39 row_shr:2 row_mask:0xf bank_mask:0xf bound_ctrl:1
	v_lshl_add_u64 v[2:3], v[2:3], 0, v[78:79]
	v_fmac_f32_e32 v40, s2, v59
	v_readlane_b32 s2, v28, 18
	v_add_f32_dpp v39, v39, v39 row_shr:4 row_mask:0xf bank_mask:0xf bound_ctrl:1
	v_readlane_b32 s12, v31, 21
	v_fmac_f32_e32 v40, s2, v58
	v_readlane_b32 s2, v28, 42
	v_add_f32_dpp v39, v39, v39 row_shr:8 row_mask:0xf bank_mask:0xf bound_ctrl:1
	v_readlane_b32 s13, v31, 45
	v_fmac_f32_e32 v40, s2, v57
	v_readlane_b32 s2, v29, 2
	v_mov_b32_dpp v66, v39 row_bcast:15 row_mask:0xa bank_mask:0xf
	v_add_f32_e32 v39, v39, v66
	v_fmac_f32_e32 v40, s2, v56
	v_readlane_b32 s2, v29, 26
	v_mov_b32_e32 v66, v35
	v_mov_b32_e32 v81, v35
	v_fmac_f32_e32 v40, s2, v55
	v_readlane_b32 s2, v29, 50
	v_mov_b32_dpp v66, v39 row_bcast:31 row_mask:0xc bank_mask:0xf
	v_add_f32_e32 v39, v39, v66
	v_fmac_f32_e32 v40, s2, v54
	v_readlane_b32 s2, v30, 10
	v_readlane_b32 s36, v39, 63
	v_lshl_add_u64 v[6:7], v[6:7], 0, v[80:81]
	v_fmac_f32_e32 v40, s2, v53
	v_readlane_b32 s2, v30, 34
	v_sub_f32_e32 v66, s36, v39
	v_fmac_f32_e32 v66, 0x3d800000, v38
	v_fmac_f32_e32 v40, s2, v52
	v_readlane_b32 s2, v30, 58
	v_cndmask_b32_e64 v66, v66, v39, s[0:1]
	global_store_dword v250, v66, s[100:101] offset:256
	v_mov_b32_e32 v83, v35
	v_fmac_f32_e32 v40, s2, v34
	v_add_f32_e32 v38, v40, v94
	v_add_f32_e32 v38, v38, v95
	v_min_f32_e32 v39, 0, v38
	v_mul_f32_e64 v38, |v38|, s72
	v_exp_f32_e32 v38, v38
	v_readlane_b32 s2, v32, 3
	v_pk_mul_f32 v[94:95], v[50:51], s[30:31]
	v_lshl_add_u64 v[10:11], v[10:11], 0, v[82:83]
	v_add_f32_e32 v38, 1.0, v38
	v_cmp_gt_f32_e32 vcc, s78, v38
	v_mov_b32_e32 v41, s2
	v_fmac_f32_e32 v41, s3, v64
	v_cndmask_b32_e64 v40, 0, 32, vcc
	v_ldexp_f32 v38, v38, v40
	v_log_f32_e32 v38, v38
	v_readlane_b32 s2, v26, 27
	v_readlane_b32 s3, v26, 4
	global_load_dwordx4 v[2:5], v[2:3], off offset:768
	v_mul_f32_e32 v40, 0x3f317217, v38
	v_fma_f32 v40, v38, s87, -v40
	v_fmac_f32_e32 v40, 0x3377d1cf, v38
	v_fmac_f32_e32 v40, 0x3f317217, v38
	v_cmp_lt_f32_e64 s[10:11], |v38|, s97
	v_fmac_f32_e32 v41, s2, v63
	v_readlane_b32 s2, v26, 51
	v_cndmask_b32_e64 v38, v38, v40, s[10:11]
	v_cndmask_b32_e32 v40, 0, v222, vcc
	v_sub_f32_e32 v38, v38, v40
	v_sub_f32_e32 v38, v39, v38
	v_fmac_f32_e32 v41, s2, v62
	v_readlane_b32 s2, v27, 11
	v_mul_f32_e32 v39, 0x3d800000, v38
	v_mov_b32_e32 v40, v35
	v_fmac_f32_e32 v41, s2, v61
	v_readlane_b32 s2, v27, 35
	v_mov_b32_dpp v39, v39 row_shr:1 row_mask:0xf bank_mask:0xf bound_ctrl:1
	v_fmac_f32_e32 v39, 0x3d800000, v38
	v_fmac_f32_e32 v41, s2, v60
	v_readlane_b32 s2, v27, 59
	v_add_f32_dpp v39, v39, v39 row_shr:2 row_mask:0xf bank_mask:0xf bound_ctrl:1
	global_load_dwordx4 v[6:9], v[6:7], off offset:768
	v_fmac_f32_e32 v41, s2, v59
	v_readlane_b32 s2, v28, 19
	v_add_f32_dpp v39, v39, v39 row_shr:4 row_mask:0xf bank_mask:0xf bound_ctrl:1
	global_load_dwordx4 v[10:13], v[10:11], off offset:768
	v_fmac_f32_e32 v41, s2, v58
	v_readlane_b32 s2, v28, 43
	v_add_f32_dpp v39, v39, v39 row_shr:8 row_mask:0xf bank_mask:0xf bound_ctrl:1
	global_load_dwordx4 v[14:17], v[46:47], off offset:416
	global_load_dwordx4 v[42:45], v[46:47], off offset:400
	s_nop 0
	global_load_dwordx4 v[46:49], v[46:47], off offset:384
	v_fmac_f32_e32 v41, s2, v57
	v_readlane_b32 s2, v29, 3
	v_mov_b32_dpp v40, v39 row_bcast:15 row_mask:0xa bank_mask:0xf
	v_add_f32_e32 v39, v39, v40
	v_fmac_f32_e32 v41, s2, v56
	v_readlane_b32 s2, v29, 27
	v_mov_b32_e32 v40, v35
	s_nop 0
	v_fmac_f32_e32 v41, s2, v55
	v_readlane_b32 s2, v29, 51
	v_mov_b32_dpp v40, v39 row_bcast:31 row_mask:0xc bank_mask:0xf
	v_add_f32_e32 v39, v39, v40
	v_fmac_f32_e32 v41, s2, v54
	v_readlane_b32 s2, v30, 11
	v_readlane_b32 s34, v39, 63
	s_nop 0
	v_fmac_f32_e32 v41, s2, v53
	v_readlane_b32 s2, v30, 35
	v_sub_f32_e32 v40, s34, v39
	v_fmac_f32_e32 v40, 0x3d800000, v38
	v_fmac_f32_e32 v41, s2, v52
	v_readlane_b32 s2, v30, 59
	v_cndmask_b32_e64 v67, v40, v39, s[0:1]
	global_store_dword v250, v67, s[100:101] offset:512
	s_nop 0
	v_fmac_f32_e32 v41, s2, v34
	v_add_f32_e32 v38, v41, v94
	v_add_f32_e32 v38, v38, v95
	v_min_f32_e32 v39, 0, v38
	v_mul_f32_e64 v38, |v38|, s72
	v_exp_f32_e32 v38, v38
	v_readlane_b32 s2, v32, 4
	v_pk_mul_f32 v[94:95], v[50:51], s[28:29]
	v_add_f32_e32 v38, 1.0, v38
	v_cmp_gt_f32_e32 vcc, s78, v38
	v_mov_b32_e32 v69, s2
	v_fmac_f32_e32 v69, s3, v64
	v_cndmask_b32_e64 v40, 0, 32, vcc
	v_ldexp_f32 v38, v38, v40
	v_log_f32_e32 v38, v38
	v_readlane_b32 s2, v26, 28
	v_readlane_b32 s3, v26, 5
	v_mul_f32_e32 v40, 0x3f317217, v38
	v_fma_f32 v40, v38, s87, -v40
	v_fmac_f32_e32 v40, 0x3377d1cf, v38
	v_fmac_f32_e32 v40, 0x3f317217, v38
	v_cmp_lt_f32_e64 s[10:11], |v38|, s97
	v_fmac_f32_e32 v69, s2, v63
	v_readlane_b32 s2, v26, 52
	v_cndmask_b32_e64 v38, v38, v40, s[10:11]
	v_cndmask_b32_e32 v40, 0, v222, vcc
	v_sub_f32_e32 v38, v38, v40
	v_sub_f32_e32 v38, v39, v38
	v_fmac_f32_e32 v69, s2, v62
	v_readlane_b32 s2, v27, 12
	v_mul_f32_e32 v39, 0x3d800000, v38
	v_mov_b32_e32 v40, v35
	v_fmac_f32_e32 v69, s2, v61
	v_readlane_b32 s2, v27, 36
	v_mov_b32_dpp v39, v39 row_shr:1 row_mask:0xf bank_mask:0xf bound_ctrl:1
	v_fmac_f32_e32 v39, 0x3d800000, v38
	v_fmac_f32_e32 v69, s2, v60
	v_readlane_b32 s2, v27, 60
	v_add_f32_dpp v39, v39, v39 row_shr:2 row_mask:0xf bank_mask:0xf bound_ctrl:1
	s_waitcnt vmcnt(0)
; template <bool PHC>
; __device__ __forceinline__ void gla_pair(const KPD& kp, int l, int pair, unsigned char* lds, int tid, int lane, int wave, v4u& pz0, v4u& pz1, v4u& pw0, v4u& pw1, int next_pair) {
;     ...
; #pragma unroll
;     for (int c = 0; c < 24; ++c) {
;         float pre = __int_as_float(__builtin_amdgcn_readlane(bvv, c));
; #pragma unroll
;         for (int r = 0; r < 16; ++r) pre += z[r] * __int_as_float(__builtin_amdgcn_readlane(wvv[(24 * r + c) >> 6], (24 * r + c) & 63));
;         const float la = (fminf(pre, 0.f) - __logf(1.f + __expf(-fabsf(pre)))) * (1.f / 16.f);
;         const float inc = wave_incl_scan(la);
;         const float total = __int_as_float(__builtin_amdgcn_readlane(__float_as_int(inc), 63));
;         bc[c] = dir ? (total - inc + la) : inc; tot[c] = total;
	v_lshlrev_b32_e32 v41, 16, v47
	v_fmac_f32_e32 v69, s2, v59
	v_readlane_b32 s2, v28, 20
	v_add_f32_dpp v39, v39, v39 row_shr:4 row_mask:0xf bank_mask:0xf bound_ctrl:1
	s_nop 0
	v_fmac_f32_e32 v69, s2, v58
	v_readlane_b32 s2, v28, 44
	v_add_f32_dpp v39, v39, v39 row_shr:8 row_mask:0xf bank_mask:0xf bound_ctrl:1
	s_nop 0
	v_fmac_f32_e32 v69, s2, v57
	v_readlane_b32 s2, v29, 4
	v_mov_b32_dpp v40, v39 row_bcast:15 row_mask:0xa bank_mask:0xf
	v_add_f32_e32 v39, v39, v40
	v_fmac_f32_e32 v69, s2, v56
	v_readlane_b32 s2, v29, 28
	v_mov_b32_e32 v40, v35
	s_nop 0
	v_fmac_f32_e32 v69, s2, v55
	v_readlane_b32 s2, v29, 52
	v_mov_b32_dpp v40, v39 row_bcast:31 row_mask:0xc bank_mask:0xf
	v_add_f32_e32 v39, v39, v40
	v_fmac_f32_e32 v69, s2, v54
	v_readlane_b32 s2, v30, 12
	v_readlane_b32 s30, v39, 63
	s_nop 0
	v_fmac_f32_e32 v69, s2, v53
	v_readlane_b32 s2, v30, 36
	v_sub_f32_e32 v40, s30, v39
	v_fmac_f32_e32 v40, 0x3d800000, v38
	v_fmac_f32_e32 v69, s2, v52
	v_readlane_b32 s2, v30, 60
	v_cndmask_b32_e64 v68, v40, v39, s[0:1]
	global_store_dword v250, v68, s[100:101] offset:768
	s_nop 0
	v_fmac_f32_e32 v69, s2, v34
	v_add_f32_e32 v38, v69, v94
	v_add_f32_e32 v38, v38, v95
	v_min_f32_e32 v39, 0, v38
	v_mul_f32_e64 v38, |v38|, s72
	v_exp_f32_e32 v38, v38
	v_readlane_b32 s2, v32, 5
	v_pk_mul_f32 v[94:95], v[50:51], s[12:13]
	v_add_f32_e32 v38, 1.0, v38
	v_cmp_gt_f32_e32 vcc, s78, v38
	v_mov_b32_e32 v79, s2
	v_fmac_f32_e32 v79, s3, v64
	v_cndmask_b32_e64 v40, 0, 32, vcc
	v_ldexp_f32 v38, v38, v40
	v_log_f32_e32 v38, v38
	v_readlane_b32 s2, v26, 29
	v_readlane_b32 s3, v26, 6
	v_mul_f32_e32 v40, 0x3f317217, v38
	v_fma_f32 v40, v38, s87, -v40
	v_fmac_f32_e32 v40, 0x3377d1cf, v38
	v_fmac_f32_e32 v40, 0x3f317217, v38
	v_cmp_lt_f32_e64 s[10:11], |v38|, s97
	v_fmac_f32_e32 v79, s2, v63
	v_readlane_b32 s2, v26, 53
	v_cndmask_b32_e64 v38, v38, v40, s[10:11]
	v_cndmask_b32_e32 v40, 0, v222, vcc
	v_sub_f32_e32 v38, v38, v40
	v_sub_f32_e32 v38, v39, v38
	v_fmac_f32_e32 v79, s2, v62
	v_readlane_b32 s2, v27, 13
	v_mul_f32_e32 v39, 0x3d800000, v38
	v_mov_b32_e32 v40, v35
	v_fmac_f32_e32 v79, s2, v61
	v_readlane_b32 s2, v27, 37
	v_mov_b32_dpp v39, v39 row_shr:1 row_mask:0xf bank_mask:0xf bound_ctrl:1
	v_fmac_f32_e32 v39, 0x3d800000, v38
	v_fmac_f32_e32 v79, s2, v60
	v_readlane_b32 s2, v27, 61
	v_add_f32_dpp v39, v39, v39 row_shr:2 row_mask:0xf bank_mask:0xf bound_ctrl:1
	s_nop 0
	v_fmac_f32_e32 v79, s2, v59
	v_readlane_b32 s2, v28, 21
	v_add_f32_dpp v39, v39, v39 row_shr:4 row_mask:0xf bank_mask:0xf bound_ctrl:1
	s_nop 0
	v_fmac_f32_e32 v79, s2, v58
	v_readlane_b32 s2, v28, 45
	v_add_f32_dpp v39, v39, v39 row_shr:8 row_mask:0xf bank_mask:0xf bound_ctrl:1
	s_nop 0
	v_fmac_f32_e32 v79, s2, v57
	v_readlane_b32 s2, v29, 5
	v_mov_b32_dpp v40, v39 row_bcast:15 row_mask:0xa bank_mask:0xf
	v_add_f32_e32 v39, v39, v40
	v_fmac_f32_e32 v79, s2, v56
	v_readlane_b32 s2, v29, 29
	v_mov_b32_e32 v40, v35
	s_nop 0
	v_fmac_f32_e32 v79, s2, v55
	v_readlane_b32 s2, v29, 53
	v_mov_b32_dpp v40, v39 row_bcast:31 row_mask:0xc bank_mask:0xf
	v_add_f32_e32 v39, v39, v40
	v_fmac_f32_e32 v79, s2, v54
	v_readlane_b32 s2, v30, 13
	v_readlane_b32 s28, v39, 63
	s_nop 0
	v_fmac_f32_e32 v79, s2, v53
	v_readlane_b32 s2, v30, 37
	v_sub_f32_e32 v40, s28, v39
	v_fmac_f32_e32 v40, 0x3d800000, v38
	v_fmac_f32_e32 v79, s2, v52
	v_readlane_b32 s2, v30, 61
	v_cndmask_b32_e64 v69, v40, v39, s[0:1]
	global_store_dword v250, v69, s[100:101] offset:1024
	s_nop 0
	v_fmac_f32_e32 v79, s2, v34
	v_add_f32_e32 v38, v79, v94
	v_add_f32_e32 v38, v38, v95
	v_min_f32_e32 v39, 0, v38
	v_mul_f32_e64 v38, |v38|, s72
	v_exp_f32_e32 v38, v38
	v_readlane_b32 s2, v32, 6
	v_add_f32_e32 v38, 1.0, v38
	v_cmp_gt_f32_e32 vcc, s78, v38
	v_mov_b32_e32 v81, s2
	v_fmac_f32_e32 v81, s3, v64
	v_cndmask_b32_e64 v40, 0, 32, vcc
	v_ldexp_f32 v38, v38, v40
	v_log_f32_e32 v38, v38
	v_readlane_b32 s2, v26, 30
	v_readlane_b32 s3, v31, 46
	v_mul_f32_e32 v40, 0x3f317217, v38
	v_fma_f32 v40, v38, s87, -v40
	v_fmac_f32_e32 v40, 0x3377d1cf, v38
	v_fmac_f32_e32 v40, 0x3f317217, v38
	v_cmp_lt_f32_e64 s[10:11], |v38|, s97
	v_fmac_f32_e32 v81, s2, v63
	v_readlane_b32 s2, v26, 54
	v_cndmask_b32_e64 v38, v38, v40, s[10:11]
	v_cndmask_b32_e32 v40, 0, v222, vcc
	v_sub_f32_e32 v38, v38, v40
	v_fmac_f32_e32 v81, s2, v62
	v_readlane_b32 s2, v27, 14
	v_sub_f32_e32 v38, v39, v38
	v_mul_f32_e32 v39, 0x3d800000, v38
	v_fmac_f32_e32 v81, s2, v61
	v_readlane_b32 s2, v27, 38
	v_mov_b32_dpp v39, v39 row_shr:1 row_mask:0xf bank_mask:0xf bound_ctrl:1
	v_fmac_f32_e32 v39, 0x3d800000, v38
	v_fmac_f32_e32 v81, s2, v60
	v_readlane_b32 s2, v27, 62
	v_add_f32_dpp v39, v39, v39 row_shr:2 row_mask:0xf bank_mask:0xf bound_ctrl:1
	v_mov_b32_e32 v40, v35
	v_fmac_f32_e32 v81, s2, v59
	v_readlane_b32 s2, v28, 22
	v_add_f32_dpp v39, v39, v39 row_shr:4 row_mask:0xf bank_mask:0xf bound_ctrl:1
	s_nop 0
	v_fmac_f32_e32 v81, s2, v58
	v_readlane_b32 s2, v28, 46
	v_add_f32_dpp v39, v39, v39 row_shr:8 row_mask:0xf bank_mask:0xf bound_ctrl:1
	s_nop 0
	v_fmac_f32_e32 v81, s2, v57
	v_readlane_b32 s2, v29, 6
	v_mov_b32_dpp v40, v39 row_bcast:15 row_mask:0xa bank_mask:0xf
	v_add_f32_e32 v39, v39, v40
	v_fmac_f32_e32 v81, s2, v56
	v_readlane_b32 s2, v29, 30
	v_mov_b32_e32 v40, v35
	s_nop 0
	v_fmac_f32_e32 v81, s2, v55
	v_readlane_b32 s2, v29, 54
	v_mov_b32_dpp v40, v39 row_bcast:31 row_mask:0xc bank_mask:0xf
	v_add_f32_e32 v39, v39, v40
	v_fmac_f32_e32 v81, s2, v54
	v_readlane_b32 s2, v30, 14
	v_readlane_b32 s29, v39, 63
	s_nop 0
	v_fmac_f32_e32 v81, s2, v53
	v_readlane_b32 s2, v30, 38
	v_sub_f32_e32 v40, s29, v39
	v_fmac_f32_e32 v40, 0x3d800000, v38
	v_fmac_f32_e32 v81, s2, v52
	v_readlane_b32 s2, v30, 62
; template <bool PHC>
; __device__ __forceinline__ void gla_pair(const KPD& kp, int l, int pair, unsigned char* lds, int tid, int lane, int wave, v4u& pz0, v4u& pz1, v4u& pw0, v4u& pw1, int next_pair) {
;     ...
; #pragma unroll
;     for (int c = 0; c < 24; ++c) {
;         float pre = __int_as_float(__builtin_amdgcn_readlane(bvv, c));
; #pragma unroll
;         for (int r = 0; r < 16; ++r) pre += z[r] * __int_as_float(__builtin_amdgcn_readlane(wvv[(24 * r + c) >> 6], (24 * r + c) & 63));
;         const float la = (fminf(pre, 0.f) - __logf(1.f + __expf(-fabsf(pre)))) * (1.f / 16.f);
;         const float inc = wave_incl_scan(la);
;         const float total = __int_as_float(__builtin_amdgcn_readlane(__float_as_int(inc), 63));
;         bc[c] = dir ? (total - inc + la) : inc; tot[c] = total;
	v_cndmask_b32_e64 v79, v40, v39, s[0:1]
	global_store_dword v250, v79, s[100:101] offset:1280
	s_nop 0
	v_fmac_f32_e32 v81, s2, v34
	v_readlane_b32 s2, v31, 22
	s_nop 1
	v_pk_mul_f32 v[94:95], v[50:51], s[2:3]
	v_readlane_b32 s2, v32, 7
	v_add_f32_e32 v38, v81, v94
	v_add_f32_e32 v38, v38, v95
	v_min_f32_e32 v39, 0, v38
	v_mul_f32_e64 v38, |v38|, s72
	v_exp_f32_e32 v38, v38
	v_readlane_b32 s3, v26, 7
	v_add_f32_e32 v38, 1.0, v38
	v_cmp_gt_f32_e32 vcc, s78, v38
	s_nop 1
	v_cndmask_b32_e64 v40, 0, 32, vcc
	v_ldexp_f32 v38, v38, v40
	v_log_f32_e32 v38, v38
	s_nop 0
	v_mul_f32_e32 v40, 0x3f317217, v38
	v_fma_f32 v40, v38, s87, -v40
	v_fmac_f32_e32 v40, 0x3377d1cf, v38
	v_fmac_f32_e32 v40, 0x3f317217, v38
	v_cmp_lt_f32_e64 s[10:11], |v38|, s97
	s_nop 1
	v_cndmask_b32_e64 v38, v38, v40, s[10:11]
	v_cndmask_b32_e32 v40, 0, v222, vcc
	v_sub_f32_e32 v38, v38, v40
	v_sub_f32_e32 v38, v39, v38
	v_mul_f32_e32 v39, 0x3d800000, v38
	v_mov_b32_e32 v40, v35
	s_nop 0
	v_mov_b32_dpp v39, v39 row_shr:1 row_mask:0xf bank_mask:0xf bound_ctrl:1
	v_fmac_f32_e32 v39, 0x3d800000, v38
	s_nop 1
	v_add_f32_dpp v39, v39, v39 row_shr:2 row_mask:0xf bank_mask:0xf bound_ctrl:1
	s_nop 1
	v_add_f32_dpp v39, v39, v39 row_shr:4 row_mask:0xf bank_mask:0xf bound_ctrl:1
	s_nop 1
	v_add_f32_dpp v39, v39, v39 row_shr:8 row_mask:0xf bank_mask:0xf bound_ctrl:1
	s_nop 1
	v_mov_b32_dpp v40, v39 row_bcast:15 row_mask:0xa bank_mask:0xf
	v_add_f32_e32 v39, v39, v40
	v_mov_b32_e32 v40, v35
	s_nop 1
	v_mov_b32_dpp v40, v39 row_bcast:31 row_mask:0xc bank_mask:0xf
	v_add_f32_e32 v39, v39, v40
	s_nop 0
	v_readlane_b32 s31, v39, 63
	s_nop 1
	v_sub_f32_e32 v40, s31, v39
	v_fmac_f32_e32 v40, 0x3d800000, v38
	v_mov_b32_e32 v38, s2
	v_fmac_f32_e32 v38, s3, v64
	v_readlane_b32 s2, v26, 31
	v_readlane_b32 s3, v31, 47
	v_cndmask_b32_e64 v81, v40, v39, s[0:1]
	global_store_dword v250, v81, s[100:101] offset:1536
	v_fmac_f32_e32 v38, s2, v63
	v_readlane_b32 s2, v26, 55
	s_nop 1
	v_fmac_f32_e32 v38, s2, v62
	v_readlane_b32 s2, v27, 15
	s_nop 1
	v_fmac_f32_e32 v38, s2, v61
	v_readlane_b32 s2, v27, 39
	s_nop 1
	v_fmac_f32_e32 v38, s2, v60
	v_readlane_b32 s2, v27, 63
	s_nop 1
	v_fmac_f32_e32 v38, s2, v59
	v_readlane_b32 s2, v28, 23
	s_nop 1
	v_fmac_f32_e32 v38, s2, v58
	v_readlane_b32 s2, v28, 47
	s_nop 1
	v_fmac_f32_e32 v38, s2, v57
	v_readlane_b32 s2, v29, 7
	s_nop 1
	v_fmac_f32_e32 v38, s2, v56
	v_readlane_b32 s2, v29, 31
	s_nop 1
	v_fmac_f32_e32 v38, s2, v55
	v_readlane_b32 s2, v29, 55
	s_nop 1
	v_fmac_f32_e32 v38, s2, v54
	v_readlane_b32 s2, v30, 15
	s_nop 1
	v_fmac_f32_e32 v38, s2, v53
	v_readlane_b32 s2, v30, 39
	s_nop 1
	v_fmac_f32_e32 v38, s2, v52
	v_readlane_b32 s2, v30, 63
	s_nop 1
	v_fmac_f32_e32 v38, s2, v34
	v_readlane_b32 s2, v31, 23
	s_nop 1
	v_pk_mul_f32 v[94:95], v[50:51], s[2:3]
	v_readlane_b32 s2, v32, 8
	v_add_f32_e32 v38, v38, v94
	v_add_f32_e32 v38, v38, v95
	v_min_f32_e32 v39, 0, v38
	v_mul_f32_e64 v38, |v38|, s72
	v_exp_f32_e32 v38, v38
	v_readlane_b32 s3, v26, 8
	v_add_f32_e32 v38, 1.0, v38
	v_cmp_gt_f32_e32 vcc, s78, v38
	s_nop 1
	v_cndmask_b32_e64 v40, 0, 32, vcc
	v_ldexp_f32 v38, v38, v40
	v_log_f32_e32 v38, v38
	s_nop 0
	v_mul_f32_e32 v40, 0x3f317217, v38
	v_fma_f32 v40, v38, s87, -v40
	v_fmac_f32_e32 v40, 0x3377d1cf, v38
	v_fmac_f32_e32 v40, 0x3f317217, v38
	v_cmp_lt_f32_e64 s[10:11], |v38|, s97
	s_nop 1
	v_cndmask_b32_e64 v38, v38, v40, s[10:11]
	v_cndmask_b32_e32 v40, 0, v222, vcc
	v_sub_f32_e32 v38, v38, v40
	v_sub_f32_e32 v38, v39, v38
	v_mul_f32_e32 v39, 0x3d800000, v38
	v_mov_b32_e32 v40, v35
	s_nop 0
	v_mov_b32_dpp v39, v39 row_shr:1 row_mask:0xf bank_mask:0xf bound_ctrl:1
	v_fmac_f32_e32 v39, 0x3d800000, v38
	s_nop 1
	v_add_f32_dpp v39, v39, v39 row_shr:2 row_mask:0xf bank_mask:0xf bound_ctrl:1
	s_nop 1
	v_add_f32_dpp v39, v39, v39 row_shr:4 row_mask:0xf bank_mask:0xf bound_ctrl:1
	s_nop 1
	v_add_f32_dpp v39, v39, v39 row_shr:8 row_mask:0xf bank_mask:0xf bound_ctrl:1
	s_nop 1
	v_mov_b32_dpp v40, v39 row_bcast:15 row_mask:0xa bank_mask:0xf
	v_add_f32_e32 v39, v39, v40
	v_mov_b32_e32 v40, v35
	s_nop 1
	v_mov_b32_dpp v40, v39 row_bcast:31 row_mask:0xc bank_mask:0xf
	v_add_f32_e32 v39, v39, v40
	s_nop 0
	v_readlane_b32 s35, v39, 63
	s_nop 1
	v_sub_f32_e32 v40, s35, v39
	v_fmac_f32_e32 v40, 0x3d800000, v38
	v_mov_b32_e32 v38, s2
	v_fmac_f32_e32 v38, s3, v64
	v_readlane_b32 s2, v26, 32
	v_readlane_b32 s3, v31, 48
	v_cndmask_b32_e64 v83, v40, v39, s[0:1]
	global_store_dword v250, v83, s[100:101] offset:1792
	v_fmac_f32_e32 v38, s2, v63
	v_readlane_b32 s2, v26, 56
	s_nop 1
	v_fmac_f32_e32 v38, s2, v62
	v_readlane_b32 s2, v27, 16
	s_nop 1
	v_fmac_f32_e32 v38, s2, v61
	v_readlane_b32 s2, v27, 40
	s_nop 1
	v_fmac_f32_e32 v38, s2, v60
	v_readlane_b32 s2, v28, 0
	s_nop 1
	v_fmac_f32_e32 v38, s2, v59
	v_readlane_b32 s2, v28, 24
	s_nop 1
	v_fmac_f32_e32 v38, s2, v58
	v_readlane_b32 s2, v28, 48
	s_nop 1
	v_fmac_f32_e32 v38, s2, v57
	v_readlane_b32 s2, v29, 8
	s_nop 1
	v_fmac_f32_e32 v38, s2, v56
	v_readlane_b32 s2, v29, 32
	s_nop 1
	v_fmac_f32_e32 v38, s2, v55
	v_readlane_b32 s2, v29, 56
	s_nop 1
	v_fmac_f32_e32 v38, s2, v54
	v_readlane_b32 s2, v30, 16
	s_nop 1
	v_fmac_f32_e32 v38, s2, v53
	v_readlane_b32 s2, v30, 40
	s_nop 1
	v_fmac_f32_e32 v38, s2, v52
	v_readlane_b32 s2, v31, 0
	s_nop 1
	v_fmac_f32_e32 v38, s2, v34
	v_readlane_b32 s2, v31, 24
	s_nop 1
	v_pk_mul_f32 v[94:95], v[50:51], s[2:3]
	v_readlane_b32 s2, v32, 9
	v_add_f32_e32 v38, v38, v94
	v_add_f32_e32 v38, v38, v95
	v_min_f32_e32 v39, 0, v38
	v_mul_f32_e64 v38, |v38|, s72
	v_exp_f32_e32 v38, v38
	v_readlane_b32 s3, v26, 9
	v_add_f32_e32 v38, 1.0, v38
	v_cmp_gt_f32_e32 vcc, s78, v38
	s_nop 1
	v_cndmask_b32_e64 v40, 0, 32, vcc
; template <bool PHC>
; __device__ __forceinline__ void gla_pair(const KPD& kp, int l, int pair, unsigned char* lds, int tid, int lane, int wave, v4u& pz0, v4u& pz1, v4u& pw0, v4u& pw1, int next_pair) {
;     ...
; #pragma unroll
;     for (int c = 0; c < 24; ++c) {
;         float pre = __int_as_float(__builtin_amdgcn_readlane(bvv, c));
; #pragma unroll
;         for (int r = 0; r < 16; ++r) pre += z[r] * __int_as_float(__builtin_amdgcn_readlane(wvv[(24 * r + c) >> 6], (24 * r + c) & 63));
;         const float la = (fminf(pre, 0.f) - __logf(1.f + __expf(-fabsf(pre)))) * (1.f / 16.f);
;         const float inc = wave_incl_scan(la);
;         const float total = __int_as_float(__builtin_amdgcn_readlane(__float_as_int(inc), 63));
;         bc[c] = dir ? (total - inc + la) : inc; tot[c] = total;
	v_ldexp_f32 v38, v38, v40
	v_log_f32_e32 v38, v38
	s_nop 0
	v_mul_f32_e32 v40, 0x3f317217, v38
	v_fma_f32 v40, v38, s87, -v40
	v_fmac_f32_e32 v40, 0x3377d1cf, v38
	v_fmac_f32_e32 v40, 0x3f317217, v38
	v_cmp_lt_f32_e64 s[10:11], |v38|, s97
	s_nop 1
	v_cndmask_b32_e64 v38, v38, v40, s[10:11]
	v_cndmask_b32_e32 v40, 0, v222, vcc
	v_sub_f32_e32 v38, v38, v40
	v_sub_f32_e32 v38, v39, v38
	v_mul_f32_e32 v39, 0x3d800000, v38
	v_mov_b32_e32 v40, v35
	s_nop 0
	v_mov_b32_dpp v39, v39 row_shr:1 row_mask:0xf bank_mask:0xf bound_ctrl:1
	v_fmac_f32_e32 v39, 0x3d800000, v38
	s_nop 1
	v_add_f32_dpp v39, v39, v39 row_shr:2 row_mask:0xf bank_mask:0xf bound_ctrl:1
	s_nop 1
	v_add_f32_dpp v39, v39, v39 row_shr:4 row_mask:0xf bank_mask:0xf bound_ctrl:1
	s_nop 1
	v_add_f32_dpp v39, v39, v39 row_shr:8 row_mask:0xf bank_mask:0xf bound_ctrl:1
	s_nop 1
	v_mov_b32_dpp v40, v39 row_bcast:15 row_mask:0xa bank_mask:0xf
	v_add_f32_e32 v39, v39, v40
	v_mov_b32_e32 v40, v35
	s_nop 1
	v_mov_b32_dpp v40, v39 row_bcast:31 row_mask:0xc bank_mask:0xf
	v_add_f32_e32 v39, v39, v40
	s_nop 0
	v_readlane_b32 s37, v39, 63
	s_nop 1
	v_sub_f32_e32 v40, s37, v39
	v_fmac_f32_e32 v40, 0x3d800000, v38
	v_mov_b32_e32 v38, s2
	v_fmac_f32_e32 v38, s3, v64
	v_readlane_b32 s2, v26, 33
	v_readlane_b32 s3, v31, 49
	v_cndmask_b32_e64 v85, v40, v39, s[0:1]
	global_store_dword v250, v85, s[100:101] offset:2048
	v_fmac_f32_e32 v38, s2, v63
	v_readlane_b32 s2, v26, 57
	s_nop 1
	v_fmac_f32_e32 v38, s2, v62
	v_readlane_b32 s2, v27, 17
	s_nop 1
	v_fmac_f32_e32 v38, s2, v61
	v_readlane_b32 s2, v27, 41
	s_nop 1
	v_fmac_f32_e32 v38, s2, v60
	v_readlane_b32 s2, v28, 1
	s_nop 1
	v_fmac_f32_e32 v38, s2, v59
	v_readlane_b32 s2, v28, 25
	s_nop 1
	v_fmac_f32_e32 v38, s2, v58
	v_readlane_b32 s2, v28, 49
	s_nop 1
	v_fmac_f32_e32 v38, s2, v57
	v_readlane_b32 s2, v29, 9
	s_nop 1
	v_fmac_f32_e32 v38, s2, v56
	v_readlane_b32 s2, v29, 33
	s_nop 1
	v_fmac_f32_e32 v38, s2, v55
	v_readlane_b32 s2, v29, 57
	s_nop 1
	v_fmac_f32_e32 v38, s2, v54
	v_readlane_b32 s2, v30, 17
	s_nop 1
	v_fmac_f32_e32 v38, s2, v53
	v_readlane_b32 s2, v30, 41
	s_nop 1
	v_fmac_f32_e32 v38, s2, v52
	v_readlane_b32 s2, v31, 1
	s_nop 1
	v_fmac_f32_e32 v38, s2, v34
	v_readlane_b32 s2, v31, 25
	s_nop 1
	v_pk_mul_f32 v[94:95], v[50:51], s[2:3]
	v_readlane_b32 s2, v32, 10
	v_add_f32_e32 v38, v38, v94
	v_add_f32_e32 v38, v38, v95
	v_min_f32_e32 v39, 0, v38
	v_mul_f32_e64 v38, |v38|, s72
	v_exp_f32_e32 v38, v38
	v_readlane_b32 s3, v26, 10
	v_add_f32_e32 v38, 1.0, v38
	v_cmp_gt_f32_e32 vcc, s78, v38
	s_nop 1
	v_cndmask_b32_e64 v40, 0, 32, vcc
	v_ldexp_f32 v38, v38, v40
	v_log_f32_e32 v38, v38
	s_nop 0
	v_mul_f32_e32 v40, 0x3f317217, v38
	v_fma_f32 v40, v38, s87, -v40
	v_fmac_f32_e32 v40, 0x3377d1cf, v38
	v_fmac_f32_e32 v40, 0x3f317217, v38
	v_cmp_lt_f32_e64 s[10:11], |v38|, s97
	s_nop 1
	v_cndmask_b32_e64 v38, v38, v40, s[10:11]
	v_cndmask_b32_e32 v40, 0, v222, vcc
	v_sub_f32_e32 v38, v38, v40
	v_sub_f32_e32 v38, v39, v38
	v_mul_f32_e32 v39, 0x3d800000, v38
	v_mov_b32_e32 v40, v35
	s_nop 0
	v_mov_b32_dpp v39, v39 row_shr:1 row_mask:0xf bank_mask:0xf bound_ctrl:1
	v_fmac_f32_e32 v39, 0x3d800000, v38
	s_nop 1
	v_add_f32_dpp v39, v39, v39 row_shr:2 row_mask:0xf bank_mask:0xf bound_ctrl:1
	s_nop 1
	v_add_f32_dpp v39, v39, v39 row_shr:4 row_mask:0xf bank_mask:0xf bound_ctrl:1
	s_nop 1
	v_add_f32_dpp v39, v39, v39 row_shr:8 row_mask:0xf bank_mask:0xf bound_ctrl:1
	s_nop 1
	v_mov_b32_dpp v40, v39 row_bcast:15 row_mask:0xa bank_mask:0xf
	v_add_f32_e32 v39, v39, v40
	v_mov_b32_e32 v40, v35
	s_nop 1
	v_mov_b32_dpp v40, v39 row_bcast:31 row_mask:0xc bank_mask:0xf
	v_add_f32_e32 v39, v39, v40
	s_nop 0
	v_readlane_b32 s55, v39, 63
	s_nop 1
	v_sub_f32_e32 v40, s55, v39
	v_fmac_f32_e32 v40, 0x3d800000, v38
	v_mov_b32_e32 v38, s2
	v_fmac_f32_e32 v38, s3, v64
	v_readlane_b32 s2, v26, 34
	v_readlane_b32 s3, v31, 50
	v_cndmask_b32_e64 v87, v40, v39, s[0:1]
	global_store_dword v250, v87, s[100:101] offset:2304
	v_fmac_f32_e32 v38, s2, v63
	v_readlane_b32 s2, v26, 58
	s_nop 1
	v_fmac_f32_e32 v38, s2, v62
	v_readlane_b32 s2, v27, 18
	s_nop 1
	v_fmac_f32_e32 v38, s2, v61
	v_readlane_b32 s2, v27, 42
	s_nop 1
	v_fmac_f32_e32 v38, s2, v60
	v_readlane_b32 s2, v28, 2
	s_nop 1
	v_fmac_f32_e32 v38, s2, v59
	v_readlane_b32 s2, v28, 26
	s_nop 1
	v_fmac_f32_e32 v38, s2, v58
	v_readlane_b32 s2, v28, 50
	s_nop 1
	v_fmac_f32_e32 v38, s2, v57
	v_readlane_b32 s2, v29, 10
	s_nop 1
	v_fmac_f32_e32 v38, s2, v56
	v_readlane_b32 s2, v29, 34
	s_nop 1
	v_fmac_f32_e32 v38, s2, v55
	v_readlane_b32 s2, v29, 58
	s_nop 1
	v_fmac_f32_e32 v38, s2, v54
	v_readlane_b32 s2, v30, 18
	s_nop 1
	v_fmac_f32_e32 v38, s2, v53
	v_readlane_b32 s2, v30, 42
	s_nop 1
	v_fmac_f32_e32 v38, s2, v52
	v_readlane_b32 s2, v31, 2
	s_nop 1
	v_fmac_f32_e32 v38, s2, v34
	v_readlane_b32 s2, v31, 26
	s_nop 1
	v_pk_mul_f32 v[94:95], v[50:51], s[2:3]
	v_readlane_b32 s2, v32, 11
	v_add_f32_e32 v38, v38, v94
	v_add_f32_e32 v38, v38, v95
	v_min_f32_e32 v39, 0, v38
	v_mul_f32_e64 v38, |v38|, s72
	v_exp_f32_e32 v38, v38
	v_readlane_b32 s3, v26, 11
	v_add_f32_e32 v38, 1.0, v38
	v_cmp_gt_f32_e32 vcc, s78, v38
	s_nop 1
	v_cndmask_b32_e64 v40, 0, 32, vcc
	v_ldexp_f32 v38, v38, v40
	v_log_f32_e32 v38, v38
	s_nop 0
	v_mul_f32_e32 v40, 0x3f317217, v38
	v_fma_f32 v40, v38, s87, -v40
	v_fmac_f32_e32 v40, 0x3377d1cf, v38
	v_fmac_f32_e32 v40, 0x3f317217, v38
	v_cmp_lt_f32_e64 s[10:11], |v38|, s97
	s_nop 1
	v_cndmask_b32_e64 v38, v38, v40, s[10:11]
	v_cndmask_b32_e32 v40, 0, v222, vcc
	v_sub_f32_e32 v38, v38, v40
	v_sub_f32_e32 v38, v39, v38
	v_mul_f32_e32 v39, 0x3d800000, v38
	v_mov_b32_e32 v40, v35
	s_nop 0
	v_mov_b32_dpp v39, v39 row_shr:1 row_mask:0xf bank_mask:0xf bound_ctrl:1
; template <bool PHC>
; __device__ __forceinline__ void gla_pair(const KPD& kp, int l, int pair, unsigned char* lds, int tid, int lane, int wave, v4u& pz0, v4u& pz1, v4u& pw0, v4u& pw1, int next_pair) {
;     ...
; #pragma unroll
;     for (int c = 0; c < 24; ++c) {
;         float pre = __int_as_float(__builtin_amdgcn_readlane(bvv, c));
; #pragma unroll
;         for (int r = 0; r < 16; ++r) pre += z[r] * __int_as_float(__builtin_amdgcn_readlane(wvv[(24 * r + c) >> 6], (24 * r + c) & 63));
;         const float la = (fminf(pre, 0.f) - __logf(1.f + __expf(-fabsf(pre)))) * (1.f / 16.f);
;         const float inc = wave_incl_scan(la);
;         const float total = __int_as_float(__builtin_amdgcn_readlane(__float_as_int(inc), 63));
;         bc[c] = dir ? (total - inc + la) : inc; tot[c] = total;
;     }
	v_fmac_f32_e32 v39, 0x3d800000, v38
	s_nop 1
	v_add_f32_dpp v39, v39, v39 row_shr:2 row_mask:0xf bank_mask:0xf bound_ctrl:1
	s_nop 1
	v_add_f32_dpp v39, v39, v39 row_shr:4 row_mask:0xf bank_mask:0xf bound_ctrl:1
	s_nop 1
	v_add_f32_dpp v39, v39, v39 row_shr:8 row_mask:0xf bank_mask:0xf bound_ctrl:1
	s_nop 1
	v_mov_b32_dpp v40, v39 row_bcast:15 row_mask:0xa bank_mask:0xf
	v_add_f32_e32 v39, v39, v40
	v_mov_b32_e32 v40, v35
	s_nop 1
	v_mov_b32_dpp v40, v39 row_bcast:31 row_mask:0xc bank_mask:0xf
	v_add_f32_e32 v39, v39, v40
	s_nop 0
	v_readlane_b32 s56, v39, 63
	s_nop 1
	v_sub_f32_e32 v40, s56, v39
	v_fmac_f32_e32 v40, 0x3d800000, v38
	v_mov_b32_e32 v38, s2
	v_fmac_f32_e32 v38, s3, v64
	v_readlane_b32 s2, v26, 35
	v_readlane_b32 s3, v31, 51
	v_cndmask_b32_e64 v89, v40, v39, s[0:1]
	global_store_dword v250, v89, s[100:101] offset:2560
	v_fmac_f32_e32 v38, s2, v63
	v_readlane_b32 s2, v26, 59
	s_nop 1
	v_fmac_f32_e32 v38, s2, v62
	v_readlane_b32 s2, v27, 19
	s_nop 1
	v_fmac_f32_e32 v38, s2, v61
	v_readlane_b32 s2, v27, 43
	s_nop 1
	v_fmac_f32_e32 v38, s2, v60
	v_readlane_b32 s2, v28, 3
	s_nop 1
	v_fmac_f32_e32 v38, s2, v59
	v_readlane_b32 s2, v28, 27
	s_nop 1
	v_fmac_f32_e32 v38, s2, v58
	v_readlane_b32 s2, v28, 51
	s_nop 1
	v_fmac_f32_e32 v38, s2, v57
	v_readlane_b32 s2, v29, 11
	s_nop 1
	v_fmac_f32_e32 v38, s2, v56
	v_readlane_b32 s2, v29, 35
	s_nop 1
	v_fmac_f32_e32 v38, s2, v55
	v_readlane_b32 s2, v29, 59
	s_nop 1
	v_fmac_f32_e32 v38, s2, v54
	v_readlane_b32 s2, v30, 19
	s_nop 1
	v_fmac_f32_e32 v38, s2, v53
	v_readlane_b32 s2, v30, 43
	s_nop 1
	v_fmac_f32_e32 v38, s2, v52
	v_readlane_b32 s2, v31, 3
	s_nop 1
	v_fmac_f32_e32 v38, s2, v34
	v_readlane_b32 s2, v31, 27
	s_nop 1
	v_pk_mul_f32 v[94:95], v[50:51], s[2:3]
	v_readlane_b32 s2, v32, 12
	v_add_f32_e32 v38, v38, v94
	v_add_f32_e32 v38, v38, v95
	v_min_f32_e32 v39, 0, v38
	v_mul_f32_e64 v38, |v38|, s72
	v_exp_f32_e32 v38, v38
	v_readlane_b32 s3, v26, 12
	v_add_f32_e32 v38, 1.0, v38
	v_cmp_gt_f32_e32 vcc, s78, v38
	s_nop 1
	v_cndmask_b32_e64 v40, 0, 32, vcc
	v_ldexp_f32 v38, v38, v40
	v_log_f32_e32 v38, v38
	s_nop 0
	v_mul_f32_e32 v40, 0x3f317217, v38
	v_fma_f32 v40, v38, s87, -v40
	v_fmac_f32_e32 v40, 0x3377d1cf, v38
	v_fmac_f32_e32 v40, 0x3f317217, v38
	v_cmp_lt_f32_e64 s[10:11], |v38|, s97
	s_nop 1
	v_cndmask_b32_e64 v38, v38, v40, s[10:11]
	v_cndmask_b32_e32 v40, 0, v222, vcc
	v_sub_f32_e32 v38, v38, v40
	v_sub_f32_e32 v38, v39, v38
	v_mul_f32_e32 v39, 0x3d800000, v38
	v_mov_b32_e32 v40, v35
	s_nop 0
	v_mov_b32_dpp v39, v39 row_shr:1 row_mask:0xf bank_mask:0xf bound_ctrl:1
	v_fmac_f32_e32 v39, 0x3d800000, v38
	s_nop 1
	v_add_f32_dpp v39, v39, v39 row_shr:2 row_mask:0xf bank_mask:0xf bound_ctrl:1
	s_nop 1
	v_add_f32_dpp v39, v39, v39 row_shr:4 row_mask:0xf bank_mask:0xf bound_ctrl:1
	s_nop 1
	v_add_f32_dpp v39, v39, v39 row_shr:8 row_mask:0xf bank_mask:0xf bound_ctrl:1
	s_nop 1
	v_mov_b32_dpp v40, v39 row_bcast:15 row_mask:0xa bank_mask:0xf
	v_add_f32_e32 v39, v39, v40
	v_mov_b32_e32 v40, v35
	s_nop 1
	v_mov_b32_dpp v40, v39 row_bcast:31 row_mask:0xc bank_mask:0xf
	v_add_f32_e32 v39, v39, v40
	s_nop 0
	v_readlane_b32 s57, v39, 63
	s_nop 1
	v_sub_f32_e32 v40, s57, v39
	v_fmac_f32_e32 v40, 0x3d800000, v38
	v_mov_b32_e32 v38, s2
	v_fmac_f32_e32 v38, s3, v64
	v_readlane_b32 s2, v26, 36
	v_readlane_b32 s3, v31, 52
	v_cndmask_b32_e64 v91, v40, v39, s[0:1]
	global_store_dword v250, v91, s[100:101] offset:2816
	v_fmac_f32_e32 v38, s2, v63
	v_readlane_b32 s2, v26, 60
	s_nop 1
	v_fmac_f32_e32 v38, s2, v62
	v_readlane_b32 s2, v27, 20
	s_nop 1
	v_fmac_f32_e32 v38, s2, v61
	v_readlane_b32 s2, v27, 44
	s_nop 1
	v_fmac_f32_e32 v38, s2, v60
	v_readlane_b32 s2, v28, 4
	s_nop 1
	v_fmac_f32_e32 v38, s2, v59
	v_readlane_b32 s2, v28, 28
	s_nop 1
	v_fmac_f32_e32 v38, s2, v58
	v_readlane_b32 s2, v28, 52
	s_nop 1
	v_fmac_f32_e32 v38, s2, v57
	v_readlane_b32 s2, v29, 12
	s_nop 1
	v_fmac_f32_e32 v38, s2, v56
	v_readlane_b32 s2, v29, 36
	s_nop 1
	v_fmac_f32_e32 v38, s2, v55
	v_readlane_b32 s2, v29, 60
	s_nop 1
	v_fmac_f32_e32 v38, s2, v54
	v_readlane_b32 s2, v30, 20
	s_nop 1
	v_fmac_f32_e32 v38, s2, v53
	v_readlane_b32 s2, v30, 44
	s_nop 1
	v_fmac_f32_e32 v38, s2, v52
	v_readlane_b32 s2, v31, 4
	s_nop 1
	v_fmac_f32_e32 v38, s2, v34
	v_readlane_b32 s2, v31, 28
	s_nop 1
	v_pk_mul_f32 v[94:95], v[50:51], s[2:3]
	v_readlane_b32 s2, v32, 13
	v_add_f32_e32 v38, v38, v94
	v_add_f32_e32 v38, v38, v95
	v_min_f32_e32 v39, 0, v38
	v_mul_f32_e64 v38, |v38|, s72
	v_exp_f32_e32 v38, v38
	v_readlane_b32 s3, v26, 13
	v_add_f32_e32 v38, 1.0, v38
	v_cmp_gt_f32_e32 vcc, s78, v38
	s_nop 1
	v_cndmask_b32_e64 v40, 0, 32, vcc
	v_ldexp_f32 v38, v38, v40
	v_log_f32_e32 v38, v38
	s_nop 0
	v_mul_f32_e32 v40, 0x3f317217, v38
	v_fma_f32 v40, v38, s87, -v40
	v_fmac_f32_e32 v40, 0x3377d1cf, v38
	v_fmac_f32_e32 v40, 0x3f317217, v38
	v_cmp_lt_f32_e64 s[10:11], |v38|, s97
	s_nop 1
	v_cndmask_b32_e64 v38, v38, v40, s[10:11]
	v_cndmask_b32_e32 v40, 0, v222, vcc
	v_sub_f32_e32 v38, v38, v40
	v_sub_f32_e32 v38, v39, v38
	v_mul_f32_e32 v39, 0x3d800000, v38
	v_mov_b32_e32 v40, v35
	s_nop 0
	v_mov_b32_dpp v39, v39 row_shr:1 row_mask:0xf bank_mask:0xf bound_ctrl:1
	v_fmac_f32_e32 v39, 0x3d800000, v38
	s_nop 1
	v_add_f32_dpp v39, v39, v39 row_shr:2 row_mask:0xf bank_mask:0xf bound_ctrl:1
	s_nop 1
	v_add_f32_dpp v39, v39, v39 row_shr:4 row_mask:0xf bank_mask:0xf bound_ctrl:1
	s_nop 1
	v_add_f32_dpp v39, v39, v39 row_shr:8 row_mask:0xf bank_mask:0xf bound_ctrl:1
	s_nop 1
	v_mov_b32_dpp v40, v39 row_bcast:15 row_mask:0xa bank_mask:0xf
	v_add_f32_e32 v39, v39, v40
	v_mov_b32_e32 v40, v35
	s_nop 1
	v_mov_b32_dpp v40, v39 row_bcast:31 row_mask:0xc bank_mask:0xf
; template <bool PHC>
; __device__ __forceinline__ void gla_pair(const KPD& kp, int l, int pair, unsigned char* lds, int tid, int lane, int wave, v4u& pz0, v4u& pz1, v4u& pw0, v4u& pw1, int next_pair) {
;     ...
; #pragma unroll
;     for (int c = 0; c < 24; ++c) {
;         float pre = __int_as_float(__builtin_amdgcn_readlane(bvv, c));
; #pragma unroll
;         for (int r = 0; r < 16; ++r) pre += z[r] * __int_as_float(__builtin_amdgcn_readlane(wvv[(24 * r + c) >> 6], (24 * r + c) & 63));
;         const float la = (fminf(pre, 0.f) - __logf(1.f + __expf(-fabsf(pre)))) * (1.f / 16.f);
;         const float inc = wave_incl_scan(la);
;         const float total = __int_as_float(__builtin_amdgcn_readlane(__float_as_int(inc), 63));
;         bc[c] = dir ? (total - inc + la) : inc; tot[c] = total;
;     }
	v_add_f32_e32 v39, v39, v40
	s_nop 0
	v_readlane_b32 s59, v39, 63
	s_nop 1
	v_sub_f32_e32 v40, s59, v39
	v_fmac_f32_e32 v40, 0x3d800000, v38
	v_mov_b32_e32 v38, s2
	v_fmac_f32_e32 v38, s3, v64
	v_readlane_b32 s2, v26, 37
	v_readlane_b32 s3, v31, 53
	v_cndmask_b32_e64 v93, v40, v39, s[0:1]
	global_store_dword v250, v93, s[100:101] offset:3072
	v_fmac_f32_e32 v38, s2, v63
	v_readlane_b32 s2, v26, 61
	s_nop 1
	v_fmac_f32_e32 v38, s2, v62
	v_readlane_b32 s2, v27, 21
	s_nop 1
	v_fmac_f32_e32 v38, s2, v61
	v_readlane_b32 s2, v27, 45
	s_nop 1
	v_fmac_f32_e32 v38, s2, v60
	v_readlane_b32 s2, v28, 5
	s_nop 1
	v_fmac_f32_e32 v38, s2, v59
	v_readlane_b32 s2, v28, 29
	s_nop 1
	v_fmac_f32_e32 v38, s2, v58
	v_readlane_b32 s2, v28, 53
	s_nop 1
	v_fmac_f32_e32 v38, s2, v57
	v_readlane_b32 s2, v29, 13
	s_nop 1
	v_fmac_f32_e32 v38, s2, v56
	v_readlane_b32 s2, v29, 37
	s_nop 1
	v_fmac_f32_e32 v38, s2, v55
	v_readlane_b32 s2, v29, 61
	s_nop 1
	v_fmac_f32_e32 v38, s2, v54
	v_readlane_b32 s2, v30, 21
	s_nop 1
	v_fmac_f32_e32 v38, s2, v53
	v_readlane_b32 s2, v30, 45
	s_nop 1
	v_fmac_f32_e32 v38, s2, v52
	v_readlane_b32 s2, v31, 5
	s_nop 1
	v_fmac_f32_e32 v38, s2, v34
	v_readlane_b32 s2, v31, 29
	s_nop 1
	v_pk_mul_f32 v[94:95], v[50:51], s[2:3]
	v_readlane_b32 s2, v32, 14
	v_add_f32_e32 v38, v38, v94
	v_add_f32_e32 v38, v38, v95
	v_min_f32_e32 v39, 0, v38
	v_mul_f32_e64 v38, |v38|, s72
	v_exp_f32_e32 v38, v38
	v_readlane_b32 s3, v26, 14
	v_add_f32_e32 v38, 1.0, v38
	v_cmp_gt_f32_e32 vcc, s78, v38
	s_nop 1
	v_cndmask_b32_e64 v40, 0, 32, vcc
	v_ldexp_f32 v38, v38, v40
	v_log_f32_e32 v38, v38
	s_nop 0
	v_mul_f32_e32 v40, 0x3f317217, v38
	v_fma_f32 v40, v38, s87, -v40
	v_fmac_f32_e32 v40, 0x3377d1cf, v38
	v_fmac_f32_e32 v40, 0x3f317217, v38
	v_cmp_lt_f32_e64 s[10:11], |v38|, s97
	s_nop 1
	v_cndmask_b32_e64 v38, v38, v40, s[10:11]
	v_cndmask_b32_e32 v40, 0, v222, vcc
	v_sub_f32_e32 v38, v38, v40
	v_sub_f32_e32 v38, v39, v38
	v_mul_f32_e32 v39, 0x3d800000, v38
	v_mov_b32_e32 v40, v35
	s_nop 0
	v_mov_b32_dpp v39, v39 row_shr:1 row_mask:0xf bank_mask:0xf bound_ctrl:1
	v_fmac_f32_e32 v39, 0x3d800000, v38
	s_nop 1
	v_add_f32_dpp v39, v39, v39 row_shr:2 row_mask:0xf bank_mask:0xf bound_ctrl:1
	s_nop 1
	v_add_f32_dpp v39, v39, v39 row_shr:4 row_mask:0xf bank_mask:0xf bound_ctrl:1
	s_nop 1
	v_add_f32_dpp v39, v39, v39 row_shr:8 row_mask:0xf bank_mask:0xf bound_ctrl:1
	s_nop 1
	v_mov_b32_dpp v40, v39 row_bcast:15 row_mask:0xa bank_mask:0xf
	v_add_f32_e32 v39, v39, v40
	v_mov_b32_e32 v40, v35
	s_nop 1
	v_mov_b32_dpp v40, v39 row_bcast:31 row_mask:0xc bank_mask:0xf
	v_add_f32_e32 v39, v39, v40
	s_nop 0
	v_readlane_b32 s60, v39, 63
	s_nop 1
	v_sub_f32_e32 v40, s60, v39
	v_fmac_f32_e32 v40, 0x3d800000, v38
	v_mov_b32_e32 v38, s2
	v_fmac_f32_e32 v38, s3, v64
	v_readlane_b32 s2, v26, 38
	v_readlane_b32 s3, v31, 54
	v_cndmask_b32_e64 v94, v40, v39, s[0:1]
	global_store_dword v250, v94, s[100:101] offset:3328
	v_fmac_f32_e32 v38, s2, v63
	v_readlane_b32 s2, v26, 62
	s_nop 1
	v_fmac_f32_e32 v38, s2, v62
	v_readlane_b32 s2, v27, 22
	s_nop 1
	v_fmac_f32_e32 v38, s2, v61
	v_readlane_b32 s2, v27, 46
	s_nop 1
	v_fmac_f32_e32 v38, s2, v60
	v_readlane_b32 s2, v28, 6
	s_nop 1
	v_fmac_f32_e32 v38, s2, v59
	v_readlane_b32 s2, v28, 30
	s_nop 1
	v_fmac_f32_e32 v38, s2, v58
	v_readlane_b32 s2, v28, 54
	s_nop 1
	v_fmac_f32_e32 v38, s2, v57
	v_readlane_b32 s2, v29, 14
	s_nop 1
	v_fmac_f32_e32 v38, s2, v56
	v_readlane_b32 s2, v29, 38
	s_nop 1
	v_fmac_f32_e32 v38, s2, v55
	v_readlane_b32 s2, v29, 62
	s_nop 1
	v_fmac_f32_e32 v38, s2, v54
	v_readlane_b32 s2, v30, 22
	s_nop 1
	v_fmac_f32_e32 v38, s2, v53
	v_readlane_b32 s2, v30, 46
	s_nop 1
	v_fmac_f32_e32 v38, s2, v52
	v_readlane_b32 s2, v31, 6
	s_nop 1
	v_fmac_f32_e32 v38, s2, v34
	v_readlane_b32 s2, v31, 30
	s_nop 1
	v_pk_mul_f32 v[96:97], v[50:51], s[2:3]
	v_readlane_b32 s2, v32, 15
	v_add_f32_e32 v38, v38, v96
	v_add_f32_e32 v38, v38, v97
	v_min_f32_e32 v39, 0, v38
	v_mul_f32_e64 v38, |v38|, s72
	v_exp_f32_e32 v38, v38
	v_readlane_b32 s3, v26, 15
	v_add_f32_e32 v38, 1.0, v38
	v_cmp_gt_f32_e32 vcc, s78, v38
	s_nop 1
	v_cndmask_b32_e64 v40, 0, 32, vcc
	v_ldexp_f32 v38, v38, v40
	v_log_f32_e32 v38, v38
	s_nop 0
	v_mul_f32_e32 v40, 0x3f317217, v38
	v_fma_f32 v40, v38, s87, -v40
	v_fmac_f32_e32 v40, 0x3377d1cf, v38
	v_fmac_f32_e32 v40, 0x3f317217, v38
	v_cmp_lt_f32_e64 s[10:11], |v38|, s97
	s_nop 1
	v_cndmask_b32_e64 v38, v38, v40, s[10:11]
	v_cndmask_b32_e32 v40, 0, v222, vcc
	v_sub_f32_e32 v38, v38, v40
	v_sub_f32_e32 v38, v39, v38
	v_mul_f32_e32 v39, 0x3d800000, v38
	v_mov_b32_e32 v40, v35
	s_nop 0
	v_mov_b32_dpp v39, v39 row_shr:1 row_mask:0xf bank_mask:0xf bound_ctrl:1
	v_fmac_f32_e32 v39, 0x3d800000, v38
	s_nop 1
	v_add_f32_dpp v39, v39, v39 row_shr:2 row_mask:0xf bank_mask:0xf bound_ctrl:1
	s_nop 1
	v_add_f32_dpp v39, v39, v39 row_shr:4 row_mask:0xf bank_mask:0xf bound_ctrl:1
	s_nop 1
	v_add_f32_dpp v39, v39, v39 row_shr:8 row_mask:0xf bank_mask:0xf bound_ctrl:1
	s_nop 1
	v_mov_b32_dpp v40, v39 row_bcast:15 row_mask:0xa bank_mask:0xf
	v_add_f32_e32 v39, v39, v40
	v_mov_b32_e32 v40, v35
	s_nop 1
	v_mov_b32_dpp v40, v39 row_bcast:31 row_mask:0xc bank_mask:0xf
	v_add_f32_e32 v39, v39, v40
	s_nop 0
	v_readlane_b32 s61, v39, 63
	s_nop 1
	v_sub_f32_e32 v40, s61, v39
	v_fmac_f32_e32 v40, 0x3d800000, v38
	v_mov_b32_e32 v38, s2
	v_fmac_f32_e32 v38, s3, v64
	v_readlane_b32 s2, v26, 39
	v_readlane_b32 s3, v31, 55
	v_cndmask_b32_e64 v95, v40, v39, s[0:1]
	global_store_dword v250, v95, s[100:101] offset:3584
	v_fmac_f32_e32 v38, s2, v63
	v_readlane_b32 s2, v26, 63
	s_nop 1
	v_fmac_f32_e32 v38, s2, v62
	v_readlane_b32 s2, v27, 23
	s_nop 1
	v_fmac_f32_e32 v38, s2, v61
; template <bool PHC>
; __device__ __forceinline__ void gla_pair(const KPD& kp, int l, int pair, unsigned char* lds, int tid, int lane, int wave, v4u& pz0, v4u& pz1, v4u& pw0, v4u& pw1, int next_pair) {
;     ...
; #pragma unroll
;     for (int c = 0; c < 24; ++c) {
;         float pre = __int_as_float(__builtin_amdgcn_readlane(bvv, c));
; #pragma unroll
;         for (int r = 0; r < 16; ++r) pre += z[r] * __int_as_float(__builtin_amdgcn_readlane(wvv[(24 * r + c) >> 6], (24 * r + c) & 63));
;         const float la = (fminf(pre, 0.f) - __logf(1.f + __expf(-fabsf(pre)))) * (1.f / 16.f);
;         const float inc = wave_incl_scan(la);
;         const float total = __int_as_float(__builtin_amdgcn_readlane(__float_as_int(inc), 63));
;         bc[c] = dir ? (total - inc + la) : inc; tot[c] = total;
;     }
	v_readlane_b32 s2, v27, 47
	s_nop 1
	v_fmac_f32_e32 v38, s2, v60
	v_readlane_b32 s2, v28, 7
	s_nop 1
	v_fmac_f32_e32 v38, s2, v59
	v_readlane_b32 s2, v28, 31
	s_nop 1
	v_fmac_f32_e32 v38, s2, v58
	v_readlane_b32 s2, v28, 55
	s_nop 1
	v_fmac_f32_e32 v38, s2, v57
	v_readlane_b32 s2, v29, 15
	s_nop 1
	v_fmac_f32_e32 v38, s2, v56
	v_readlane_b32 s2, v29, 39
	s_nop 1
	v_fmac_f32_e32 v38, s2, v55
	v_readlane_b32 s2, v29, 63
	s_nop 1
	v_fmac_f32_e32 v38, s2, v54
	v_readlane_b32 s2, v30, 23
	s_nop 1
	v_fmac_f32_e32 v38, s2, v53
	v_readlane_b32 s2, v30, 47
	s_nop 1
	v_fmac_f32_e32 v38, s2, v52
	v_readlane_b32 s2, v31, 7
	s_nop 1
	v_fmac_f32_e32 v38, s2, v34
	v_readlane_b32 s2, v31, 31
	s_nop 1
	v_pk_mul_f32 v[96:97], v[50:51], s[2:3]
	v_readlane_b32 s2, v32, 16
	v_add_f32_e32 v38, v38, v96
	v_add_f32_e32 v38, v38, v97
	v_min_f32_e32 v39, 0, v38
	v_mul_f32_e64 v38, |v38|, s72
	v_exp_f32_e32 v38, v38
	v_readlane_b32 s3, v26, 16
	v_add_f32_e32 v38, 1.0, v38
	v_cmp_gt_f32_e32 vcc, s78, v38
	s_nop 1
	v_cndmask_b32_e64 v40, 0, 32, vcc
	v_ldexp_f32 v38, v38, v40
	v_log_f32_e32 v38, v38
	s_nop 0
	v_mul_f32_e32 v40, 0x3f317217, v38
	v_fma_f32 v40, v38, s87, -v40
	v_fmac_f32_e32 v40, 0x3377d1cf, v38
	v_fmac_f32_e32 v40, 0x3f317217, v38
	v_cmp_lt_f32_e64 s[10:11], |v38|, s97
	s_nop 1
	v_cndmask_b32_e64 v38, v38, v40, s[10:11]
	v_cndmask_b32_e32 v40, 0, v222, vcc
	v_sub_f32_e32 v38, v38, v40
	v_sub_f32_e32 v38, v39, v38
	v_mul_f32_e32 v39, 0x3d800000, v38
	v_mov_b32_e32 v40, v35
	s_nop 0
	v_mov_b32_dpp v39, v39 row_shr:1 row_mask:0xf bank_mask:0xf bound_ctrl:1
	v_fmac_f32_e32 v39, 0x3d800000, v38
	s_nop 1
	v_add_f32_dpp v39, v39, v39 row_shr:2 row_mask:0xf bank_mask:0xf bound_ctrl:1
	s_nop 1
	v_add_f32_dpp v39, v39, v39 row_shr:4 row_mask:0xf bank_mask:0xf bound_ctrl:1
	s_nop 1
	v_add_f32_dpp v39, v39, v39 row_shr:8 row_mask:0xf bank_mask:0xf bound_ctrl:1
	s_nop 1
	v_mov_b32_dpp v40, v39 row_bcast:15 row_mask:0xa bank_mask:0xf
	v_add_f32_e32 v39, v39, v40
	v_mov_b32_e32 v40, v35
	s_nop 1
	v_mov_b32_dpp v40, v39 row_bcast:31 row_mask:0xc bank_mask:0xf
	v_add_f32_e32 v39, v39, v40
	s_nop 0
	v_readlane_b32 s62, v39, 63
	s_nop 1
	v_sub_f32_e32 v40, s62, v39
	v_fmac_f32_e32 v40, 0x3d800000, v38
	v_mov_b32_e32 v38, s2
	v_fmac_f32_e32 v38, s3, v64
	v_readlane_b32 s2, v26, 40
	v_readlane_b32 s3, v31, 56
	v_cndmask_b32_e64 v96, v40, v39, s[0:1]
	global_store_dword v250, v96, s[100:101] offset:3840
	v_fmac_f32_e32 v38, s2, v63
	v_readlane_b32 s2, v27, 0
	s_nop 1
	v_fmac_f32_e32 v38, s2, v62
	v_readlane_b32 s2, v27, 24
	s_nop 1
	v_fmac_f32_e32 v38, s2, v61
	v_readlane_b32 s2, v27, 48
	s_nop 1
	v_fmac_f32_e32 v38, s2, v60
	v_readlane_b32 s2, v28, 8
	s_nop 1
	v_fmac_f32_e32 v38, s2, v59
	v_readlane_b32 s2, v28, 32
	s_nop 1
	v_fmac_f32_e32 v38, s2, v58
	v_readlane_b32 s2, v28, 56
	s_nop 1
	v_fmac_f32_e32 v38, s2, v57
	v_readlane_b32 s2, v29, 16
	s_nop 1
	v_fmac_f32_e32 v38, s2, v56
	v_readlane_b32 s2, v29, 40
	s_nop 1
	v_fmac_f32_e32 v38, s2, v55
	v_readlane_b32 s2, v30, 0
	s_nop 1
	v_fmac_f32_e32 v38, s2, v54
	v_readlane_b32 s2, v30, 24
	s_nop 1
	v_fmac_f32_e32 v38, s2, v53
	v_readlane_b32 s2, v30, 48
	s_nop 1
	v_fmac_f32_e32 v38, s2, v52
	v_readlane_b32 s2, v31, 8
	s_nop 1
	v_fmac_f32_e32 v38, s2, v34
	v_readlane_b32 s2, v31, 32
	s_nop 1
	v_pk_mul_f32 v[98:99], v[50:51], s[2:3]
	v_readlane_b32 s2, v32, 17
	v_add_f32_e32 v38, v38, v98
	v_add_f32_e32 v38, v38, v99
	v_min_f32_e32 v39, 0, v38
	v_mul_f32_e64 v38, |v38|, s72
	v_exp_f32_e32 v38, v38
	v_readlane_b32 s3, v26, 17
	v_add_f32_e32 v38, 1.0, v38
	v_cmp_gt_f32_e32 vcc, s78, v38
	s_nop 1
	v_cndmask_b32_e64 v40, 0, 32, vcc
	v_ldexp_f32 v38, v38, v40
	v_log_f32_e32 v38, v38
	s_nop 0
	v_mul_f32_e32 v40, 0x3f317217, v38
	v_fma_f32 v40, v38, s87, -v40
	v_fmac_f32_e32 v40, 0x3377d1cf, v38
	v_fmac_f32_e32 v40, 0x3f317217, v38
	v_cmp_lt_f32_e64 s[10:11], |v38|, s97
	s_nop 1
	v_cndmask_b32_e64 v38, v38, v40, s[10:11]
	v_cndmask_b32_e32 v40, 0, v222, vcc
	v_sub_f32_e32 v38, v38, v40
	v_sub_f32_e32 v38, v39, v38
	v_mul_f32_e32 v39, 0x3d800000, v38
	v_mov_b32_e32 v40, v35
	s_nop 0
	v_mov_b32_dpp v39, v39 row_shr:1 row_mask:0xf bank_mask:0xf bound_ctrl:1
	v_fmac_f32_e32 v39, 0x3d800000, v38
	s_nop 1
	v_add_f32_dpp v39, v39, v39 row_shr:2 row_mask:0xf bank_mask:0xf bound_ctrl:1
	s_nop 1
	v_add_f32_dpp v39, v39, v39 row_shr:4 row_mask:0xf bank_mask:0xf bound_ctrl:1
	s_nop 1
	v_add_f32_dpp v39, v39, v39 row_shr:8 row_mask:0xf bank_mask:0xf bound_ctrl:1
	s_nop 1
	v_mov_b32_dpp v40, v39 row_bcast:15 row_mask:0xa bank_mask:0xf
	v_add_f32_e32 v39, v39, v40
	v_mov_b32_e32 v40, v35
	s_nop 1
	v_mov_b32_dpp v40, v39 row_bcast:31 row_mask:0xc bank_mask:0xf
	v_add_f32_e32 v39, v39, v40
	s_nop 0
	v_readlane_b32 s63, v39, 63
	s_nop 1
	v_sub_f32_e32 v40, s63, v39
	v_fmac_f32_e32 v40, 0x3d800000, v38
	v_mov_b32_e32 v38, s2
	v_fmac_f32_e32 v38, s3, v64
	v_readlane_b32 s2, v26, 41
	v_readlane_b32 s3, v31, 57
	v_cndmask_b32_e64 v97, v40, v39, s[0:1]
	global_store_dword v251, v97, s[100:101]
	v_fmac_f32_e32 v38, s2, v63
	v_readlane_b32 s2, v27, 1
	s_nop 1
	v_fmac_f32_e32 v38, s2, v62
	v_readlane_b32 s2, v27, 25
	s_nop 1
	v_fmac_f32_e32 v38, s2, v61
	v_readlane_b32 s2, v27, 49
	s_nop 1
	v_fmac_f32_e32 v38, s2, v60
	v_readlane_b32 s2, v28, 9
	s_nop 1
	v_fmac_f32_e32 v38, s2, v59
	v_readlane_b32 s2, v28, 33
	s_nop 1
	v_fmac_f32_e32 v38, s2, v58
	v_readlane_b32 s2, v28, 57
	s_nop 1
	v_fmac_f32_e32 v38, s2, v57
	v_readlane_b32 s2, v29, 17
	s_nop 1
	v_fmac_f32_e32 v38, s2, v56
	v_readlane_b32 s2, v29, 41
	s_nop 1
	v_fmac_f32_e32 v38, s2, v55
	v_readlane_b32 s2, v30, 1
	s_nop 1
	v_fmac_f32_e32 v38, s2, v54
	v_readlane_b32 s2, v30, 25
	s_nop 1
; template <bool PHC>
; __device__ __forceinline__ void gla_pair(const KPD& kp, int l, int pair, unsigned char* lds, int tid, int lane, int wave, v4u& pz0, v4u& pz1, v4u& pw0, v4u& pw1, int next_pair) {
;     ...
; #pragma unroll
;     for (int c = 0; c < 24; ++c) {
;         float pre = __int_as_float(__builtin_amdgcn_readlane(bvv, c));
; #pragma unroll
;         for (int r = 0; r < 16; ++r) pre += z[r] * __int_as_float(__builtin_amdgcn_readlane(wvv[(24 * r + c) >> 6], (24 * r + c) & 63));
;         const float la = (fminf(pre, 0.f) - __logf(1.f + __expf(-fabsf(pre)))) * (1.f / 16.f);
;         const float inc = wave_incl_scan(la);
;         const float total = __int_as_float(__builtin_amdgcn_readlane(__float_as_int(inc), 63));
;         bc[c] = dir ? (total - inc + la) : inc; tot[c] = total;
;     }
	v_fmac_f32_e32 v38, s2, v53
	v_readlane_b32 s2, v30, 49
	s_nop 1
	v_fmac_f32_e32 v38, s2, v52
	v_readlane_b32 s2, v31, 9
	s_nop 1
	v_fmac_f32_e32 v38, s2, v34
	v_readlane_b32 s2, v31, 33
	s_nop 1
	v_pk_mul_f32 v[98:99], v[50:51], s[2:3]
	v_readlane_b32 s2, v32, 18
	v_add_f32_e32 v38, v38, v98
	v_add_f32_e32 v38, v38, v99
	v_min_f32_e32 v39, 0, v38
	v_mul_f32_e64 v38, |v38|, s72
	v_exp_f32_e32 v38, v38
	v_readlane_b32 s3, v26, 18
	v_add_f32_e32 v38, 1.0, v38
	v_cmp_gt_f32_e32 vcc, s78, v38
	s_nop 1
	v_cndmask_b32_e64 v40, 0, 32, vcc
	v_ldexp_f32 v38, v38, v40
	v_log_f32_e32 v38, v38
	s_nop 0
	v_mul_f32_e32 v40, 0x3f317217, v38
	v_fma_f32 v40, v38, s87, -v40
	v_fmac_f32_e32 v40, 0x3377d1cf, v38
	v_fmac_f32_e32 v40, 0x3f317217, v38
	v_cmp_lt_f32_e64 s[10:11], |v38|, s97
	s_nop 1
	v_cndmask_b32_e64 v38, v38, v40, s[10:11]
	v_cndmask_b32_e32 v40, 0, v222, vcc
	v_sub_f32_e32 v38, v38, v40
	v_sub_f32_e32 v38, v39, v38
	v_mul_f32_e32 v39, 0x3d800000, v38
	v_mov_b32_e32 v40, v35
	s_nop 0
	v_mov_b32_dpp v39, v39 row_shr:1 row_mask:0xf bank_mask:0xf bound_ctrl:1
	v_fmac_f32_e32 v39, 0x3d800000, v38
	s_nop 1
	v_add_f32_dpp v39, v39, v39 row_shr:2 row_mask:0xf bank_mask:0xf bound_ctrl:1
	s_nop 1
	v_add_f32_dpp v39, v39, v39 row_shr:4 row_mask:0xf bank_mask:0xf bound_ctrl:1
	s_nop 1
	v_add_f32_dpp v39, v39, v39 row_shr:8 row_mask:0xf bank_mask:0xf bound_ctrl:1
	s_nop 1
	v_mov_b32_dpp v40, v39 row_bcast:15 row_mask:0xa bank_mask:0xf
	v_add_f32_e32 v39, v39, v40
	v_mov_b32_e32 v40, v35
	s_nop 1
	v_mov_b32_dpp v40, v39 row_bcast:31 row_mask:0xc bank_mask:0xf
	v_add_f32_e32 v39, v39, v40
	s_nop 0
	v_readlane_b32 s64, v39, 63
	s_nop 1
	v_sub_f32_e32 v40, s64, v39
	v_fmac_f32_e32 v40, 0x3d800000, v38
	v_mov_b32_e32 v38, s2
	v_fmac_f32_e32 v38, s3, v64
	v_readlane_b32 s2, v26, 42
	v_readlane_b32 s3, v31, 58
	v_cndmask_b32_e64 v98, v40, v39, s[0:1]
	global_store_dword v251, v98, s[100:101] offset:256
	v_fmac_f32_e32 v38, s2, v63
	v_readlane_b32 s2, v27, 2
	s_nop 1
	v_fmac_f32_e32 v38, s2, v62
	v_readlane_b32 s2, v27, 26
	s_nop 1
	v_fmac_f32_e32 v38, s2, v61
	v_readlane_b32 s2, v27, 50
	s_nop 1
	v_fmac_f32_e32 v38, s2, v60
	v_readlane_b32 s2, v28, 10
	s_nop 1
	v_fmac_f32_e32 v38, s2, v59
	v_readlane_b32 s2, v28, 34
	s_nop 1
	v_fmac_f32_e32 v38, s2, v58
	v_readlane_b32 s2, v28, 58
	s_nop 1
	v_fmac_f32_e32 v38, s2, v57
	v_readlane_b32 s2, v29, 18
	s_nop 1
	v_fmac_f32_e32 v38, s2, v56
	v_readlane_b32 s2, v29, 42
	s_nop 1
	v_fmac_f32_e32 v38, s2, v55
	v_readlane_b32 s2, v30, 2
	s_nop 1
	v_fmac_f32_e32 v38, s2, v54
	v_readlane_b32 s2, v30, 26
	s_nop 1
	v_fmac_f32_e32 v38, s2, v53
	v_readlane_b32 s2, v30, 50
	s_nop 1
	v_fmac_f32_e32 v38, s2, v52
	v_readlane_b32 s2, v31, 10
	s_nop 1
	v_fmac_f32_e32 v38, s2, v34
	v_readlane_b32 s2, v31, 34
	s_nop 1
	v_pk_mul_f32 v[100:101], v[50:51], s[2:3]
	v_readlane_b32 s2, v32, 19
	v_add_f32_e32 v38, v38, v100
	v_add_f32_e32 v38, v38, v101
	v_min_f32_e32 v39, 0, v38
	v_mul_f32_e64 v38, |v38|, s72
	v_exp_f32_e32 v38, v38
	v_readlane_b32 s3, v26, 19
	v_add_f32_e32 v38, 1.0, v38
	v_cmp_gt_f32_e32 vcc, s78, v38
	s_nop 1
	v_cndmask_b32_e64 v40, 0, 32, vcc
	v_ldexp_f32 v38, v38, v40
	v_log_f32_e32 v38, v38
	s_nop 0
	v_mul_f32_e32 v40, 0x3f317217, v38
	v_fma_f32 v40, v38, s87, -v40
	v_fmac_f32_e32 v40, 0x3377d1cf, v38
	v_fmac_f32_e32 v40, 0x3f317217, v38
	v_cmp_lt_f32_e64 s[10:11], |v38|, s97
	s_nop 1
	v_cndmask_b32_e64 v38, v38, v40, s[10:11]
	v_cndmask_b32_e32 v40, 0, v222, vcc
	v_sub_f32_e32 v38, v38, v40
	v_sub_f32_e32 v38, v39, v38
	v_mul_f32_e32 v39, 0x3d800000, v38
	v_mov_b32_e32 v40, v35
	s_nop 0
	v_mov_b32_dpp v39, v39 row_shr:1 row_mask:0xf bank_mask:0xf bound_ctrl:1
	v_fmac_f32_e32 v39, 0x3d800000, v38
	s_nop 1
	v_add_f32_dpp v39, v39, v39 row_shr:2 row_mask:0xf bank_mask:0xf bound_ctrl:1
	s_nop 1
	v_add_f32_dpp v39, v39, v39 row_shr:4 row_mask:0xf bank_mask:0xf bound_ctrl:1
	s_nop 1
	v_add_f32_dpp v39, v39, v39 row_shr:8 row_mask:0xf bank_mask:0xf bound_ctrl:1
	s_nop 1
	v_mov_b32_dpp v40, v39 row_bcast:15 row_mask:0xa bank_mask:0xf
	v_add_f32_e32 v39, v39, v40
	v_mov_b32_e32 v40, v35
	s_nop 1
	v_mov_b32_dpp v40, v39 row_bcast:31 row_mask:0xc bank_mask:0xf
	v_add_f32_e32 v39, v39, v40
	s_nop 0
	v_readlane_b32 s65, v39, 63
	s_nop 1
	v_sub_f32_e32 v40, s65, v39
	v_fmac_f32_e32 v40, 0x3d800000, v38
	v_mov_b32_e32 v38, s2
	v_fmac_f32_e32 v38, s3, v64
	v_readlane_b32 s2, v26, 43
	v_readlane_b32 s3, v31, 59
	v_cndmask_b32_e64 v99, v40, v39, s[0:1]
	global_store_dword v251, v99, s[100:101] offset:512
	v_fmac_f32_e32 v38, s2, v63
	v_readlane_b32 s2, v27, 3
	s_nop 1
	v_fmac_f32_e32 v38, s2, v62
	v_readlane_b32 s2, v27, 27
	s_nop 1
	v_fmac_f32_e32 v38, s2, v61
	v_readlane_b32 s2, v27, 51
	s_nop 1
	v_fmac_f32_e32 v38, s2, v60
	v_readlane_b32 s2, v28, 11
	s_nop 1
	v_fmac_f32_e32 v38, s2, v59
	v_readlane_b32 s2, v28, 35
	s_nop 1
	v_fmac_f32_e32 v38, s2, v58
	v_readlane_b32 s2, v28, 59
	s_nop 1
	v_fmac_f32_e32 v38, s2, v57
	v_readlane_b32 s2, v29, 19
	s_nop 1
	v_fmac_f32_e32 v38, s2, v56
	v_readlane_b32 s2, v29, 43
	s_nop 1
	v_fmac_f32_e32 v38, s2, v55
	v_readlane_b32 s2, v30, 3
	s_nop 1
	v_fmac_f32_e32 v38, s2, v54
	v_readlane_b32 s2, v30, 27
	s_nop 1
	v_fmac_f32_e32 v38, s2, v53
	v_readlane_b32 s2, v30, 51
	s_nop 1
	v_fmac_f32_e32 v38, s2, v52
	v_readlane_b32 s2, v31, 11
	s_nop 1
	v_fmac_f32_e32 v38, s2, v34
	v_readlane_b32 s2, v31, 35
	s_nop 1
	v_pk_mul_f32 v[100:101], v[50:51], s[2:3]
	v_readlane_b32 s2, v32, 20
	v_add_f32_e32 v38, v38, v100
	v_add_f32_e32 v38, v38, v101
	v_min_f32_e32 v39, 0, v38
	v_mul_f32_e64 v38, |v38|, s72
	v_exp_f32_e32 v38, v38
	v_readlane_b32 s3, v26, 20
	v_add_f32_e32 v38, 1.0, v38
	v_cmp_gt_f32_e32 vcc, s78, v38
; template <bool PHC>
; __device__ __forceinline__ void gla_pair(const KPD& kp, int l, int pair, unsigned char* lds, int tid, int lane, int wave, v4u& pz0, v4u& pz1, v4u& pw0, v4u& pw1, int next_pair) {
;     ...
; #pragma unroll
;     for (int c = 0; c < 24; ++c) {
;         float pre = __int_as_float(__builtin_amdgcn_readlane(bvv, c));
; #pragma unroll
;         for (int r = 0; r < 16; ++r) pre += z[r] * __int_as_float(__builtin_amdgcn_readlane(wvv[(24 * r + c) >> 6], (24 * r + c) & 63));
;         const float la = (fminf(pre, 0.f) - __logf(1.f + __expf(-fabsf(pre)))) * (1.f / 16.f);
;         const float inc = wave_incl_scan(la);
;         const float total = __int_as_float(__builtin_amdgcn_readlane(__float_as_int(inc), 63));
;         bc[c] = dir ? (total - inc + la) : inc; tot[c] = total;
;     }
	s_nop 1
	v_cndmask_b32_e64 v40, 0, 32, vcc
	v_ldexp_f32 v38, v38, v40
	v_log_f32_e32 v38, v38
	s_nop 0
	v_mul_f32_e32 v40, 0x3f317217, v38
	v_fma_f32 v40, v38, s87, -v40
	v_fmac_f32_e32 v40, 0x3377d1cf, v38
	v_fmac_f32_e32 v40, 0x3f317217, v38
	v_cmp_lt_f32_e64 s[10:11], |v38|, s97
	s_nop 1
	v_cndmask_b32_e64 v38, v38, v40, s[10:11]
	v_cndmask_b32_e32 v40, 0, v222, vcc
	v_sub_f32_e32 v38, v38, v40
	v_sub_f32_e32 v38, v39, v38
	v_mul_f32_e32 v39, 0x3d800000, v38
	v_mov_b32_e32 v40, v35
	s_nop 0
	v_mov_b32_dpp v39, v39 row_shr:1 row_mask:0xf bank_mask:0xf bound_ctrl:1
	v_fmac_f32_e32 v39, 0x3d800000, v38
	s_nop 1
	v_add_f32_dpp v39, v39, v39 row_shr:2 row_mask:0xf bank_mask:0xf bound_ctrl:1
	s_nop 1
	v_add_f32_dpp v39, v39, v39 row_shr:4 row_mask:0xf bank_mask:0xf bound_ctrl:1
	s_nop 1
	v_add_f32_dpp v39, v39, v39 row_shr:8 row_mask:0xf bank_mask:0xf bound_ctrl:1
	s_nop 1
	v_mov_b32_dpp v40, v39 row_bcast:15 row_mask:0xa bank_mask:0xf
	v_add_f32_e32 v39, v39, v40
	v_mov_b32_e32 v40, v35
	s_nop 1
	v_mov_b32_dpp v40, v39 row_bcast:31 row_mask:0xc bank_mask:0xf
	v_add_f32_e32 v39, v39, v40
	s_nop 0
	v_readlane_b32 s66, v39, 63
	s_nop 1
	v_sub_f32_e32 v40, s66, v39
	v_fmac_f32_e32 v40, 0x3d800000, v38
	v_mov_b32_e32 v38, s2
	v_fmac_f32_e32 v38, s3, v64
	v_readlane_b32 s2, v26, 44
	v_readlane_b32 s3, v31, 60
	v_cndmask_b32_e64 v100, v40, v39, s[0:1]
	global_store_dword v251, v100, s[100:101] offset:768
	v_fmac_f32_e32 v38, s2, v63
	v_readlane_b32 s2, v27, 4
	s_nop 1
	v_fmac_f32_e32 v38, s2, v62
	v_readlane_b32 s2, v27, 28
	s_nop 1
	v_fmac_f32_e32 v38, s2, v61
	v_readlane_b32 s2, v27, 52
	s_nop 1
	v_fmac_f32_e32 v38, s2, v60
	v_readlane_b32 s2, v28, 12
	s_nop 1
	v_fmac_f32_e32 v38, s2, v59
	v_readlane_b32 s2, v28, 36
	s_nop 1
	v_fmac_f32_e32 v38, s2, v58
	v_readlane_b32 s2, v28, 60
	s_nop 1
	v_fmac_f32_e32 v38, s2, v57
	v_readlane_b32 s2, v29, 20
	s_nop 1
	v_fmac_f32_e32 v38, s2, v56
	v_readlane_b32 s2, v29, 44
	s_nop 1
	v_fmac_f32_e32 v38, s2, v55
	v_readlane_b32 s2, v30, 4
	s_nop 1
	v_fmac_f32_e32 v38, s2, v54
	v_readlane_b32 s2, v30, 28
	s_nop 1
	v_fmac_f32_e32 v38, s2, v53
	v_readlane_b32 s2, v30, 52
	s_nop 1
	v_fmac_f32_e32 v38, s2, v52
	v_readlane_b32 s2, v31, 12
	s_nop 1
	v_fmac_f32_e32 v38, s2, v34
	v_readlane_b32 s2, v31, 36
	s_nop 1
	v_pk_mul_f32 v[102:103], v[50:51], s[2:3]
	v_readlane_b32 s2, v32, 21
	v_add_f32_e32 v38, v38, v102
	v_add_f32_e32 v38, v38, v103
	v_min_f32_e32 v39, 0, v38
	v_mul_f32_e64 v38, |v38|, s72
	v_exp_f32_e32 v38, v38
	v_readlane_b32 s3, v26, 21
	v_add_f32_e32 v38, 1.0, v38
	v_cmp_gt_f32_e32 vcc, s78, v38
	s_nop 1
	v_cndmask_b32_e64 v40, 0, 32, vcc
	v_ldexp_f32 v38, v38, v40
	v_log_f32_e32 v38, v38
	s_nop 0
	v_mul_f32_e32 v40, 0x3f317217, v38
	v_fma_f32 v40, v38, s87, -v40
	v_fmac_f32_e32 v40, 0x3377d1cf, v38
	v_fmac_f32_e32 v40, 0x3f317217, v38
	v_cmp_lt_f32_e64 s[10:11], |v38|, s97
	s_nop 1
	v_cndmask_b32_e64 v38, v38, v40, s[10:11]
	v_cndmask_b32_e32 v40, 0, v222, vcc
	v_sub_f32_e32 v38, v38, v40
	v_sub_f32_e32 v38, v39, v38
	v_mul_f32_e32 v39, 0x3d800000, v38
	v_mov_b32_e32 v40, v35
	s_nop 0
	v_mov_b32_dpp v39, v39 row_shr:1 row_mask:0xf bank_mask:0xf bound_ctrl:1
	v_fmac_f32_e32 v39, 0x3d800000, v38
	s_nop 1
	v_add_f32_dpp v39, v39, v39 row_shr:2 row_mask:0xf bank_mask:0xf bound_ctrl:1
	s_nop 1
	v_add_f32_dpp v39, v39, v39 row_shr:4 row_mask:0xf bank_mask:0xf bound_ctrl:1
	s_nop 1
	v_add_f32_dpp v39, v39, v39 row_shr:8 row_mask:0xf bank_mask:0xf bound_ctrl:1
	s_nop 1
	v_mov_b32_dpp v40, v39 row_bcast:15 row_mask:0xa bank_mask:0xf
	v_add_f32_e32 v39, v39, v40
	v_mov_b32_e32 v40, v35
	s_nop 1
	v_mov_b32_dpp v40, v39 row_bcast:31 row_mask:0xc bank_mask:0xf
	v_add_f32_e32 v39, v39, v40
	s_nop 0
	v_readlane_b32 s67, v39, 63
	s_nop 1
	v_sub_f32_e32 v40, s67, v39
	v_fmac_f32_e32 v40, 0x3d800000, v38
	v_mov_b32_e32 v38, s2
	v_fmac_f32_e32 v38, s3, v64
	v_readlane_b32 s2, v26, 45
	v_readlane_b32 s3, v31, 61
	v_cndmask_b32_e64 v101, v40, v39, s[0:1]
	global_store_dword v251, v101, s[100:101] offset:1024
	v_fmac_f32_e32 v38, s2, v63
	v_readlane_b32 s2, v27, 5
	s_nop 1
	v_fmac_f32_e32 v38, s2, v62
	v_readlane_b32 s2, v27, 29
	s_nop 1
	v_fmac_f32_e32 v38, s2, v61
	v_readlane_b32 s2, v27, 53
	s_nop 1
	v_fmac_f32_e32 v38, s2, v60
	v_readlane_b32 s2, v28, 13
	s_nop 1
	v_fmac_f32_e32 v38, s2, v59
	v_readlane_b32 s2, v28, 37
	s_nop 1
	v_fmac_f32_e32 v38, s2, v58
	v_readlane_b32 s2, v28, 61
	s_nop 1
	v_fmac_f32_e32 v38, s2, v57
	v_readlane_b32 s2, v29, 21
	s_nop 1
	v_fmac_f32_e32 v38, s2, v56
	v_readlane_b32 s2, v29, 45
	s_nop 1
	v_fmac_f32_e32 v38, s2, v55
	v_readlane_b32 s2, v30, 5
	s_nop 1
	v_fmac_f32_e32 v38, s2, v54
	v_readlane_b32 s2, v30, 29
	s_nop 1
	v_fmac_f32_e32 v38, s2, v53
	v_readlane_b32 s2, v30, 53
	s_nop 1
	v_fmac_f32_e32 v38, s2, v52
	v_readlane_b32 s2, v31, 13
	s_nop 1
	v_fmac_f32_e32 v38, s2, v34
	v_readlane_b32 s2, v31, 37
	s_nop 1
	v_pk_mul_f32 v[102:103], v[50:51], s[2:3]
	v_readlane_b32 s2, v32, 22
	v_add_f32_e32 v38, v38, v102
	v_add_f32_e32 v38, v38, v103
	v_min_f32_e32 v39, 0, v38
	v_mul_f32_e64 v38, |v38|, s72
	v_exp_f32_e32 v38, v38
	v_readlane_b32 s3, v26, 22
	v_add_f32_e32 v38, 1.0, v38
	v_cmp_gt_f32_e32 vcc, s78, v38
	s_nop 1
	v_cndmask_b32_e64 v40, 0, 32, vcc
	v_ldexp_f32 v38, v38, v40
	v_log_f32_e32 v38, v38
	s_nop 0
	v_mul_f32_e32 v40, 0x3f317217, v38
	v_fma_f32 v40, v38, s87, -v40
	v_fmac_f32_e32 v40, 0x3377d1cf, v38
	v_fmac_f32_e32 v40, 0x3f317217, v38
	v_cmp_lt_f32_e64 s[10:11], |v38|, s97
	s_nop 1
	v_cndmask_b32_e64 v38, v38, v40, s[10:11]
	v_cndmask_b32_e32 v40, 0, v222, vcc
	v_sub_f32_e32 v38, v38, v40
	v_sub_f32_e32 v38, v39, v38
	v_mul_f32_e32 v39, 0x3d800000, v38
	v_mov_b32_e32 v40, v35
; template <bool PHC>
; __device__ __forceinline__ void gla_pair(const KPD& kp, int l, int pair, unsigned char* lds, int tid, int lane, int wave, v4u& pz0, v4u& pz1, v4u& pw0, v4u& pw1, int next_pair) {
;     ...
; #pragma unroll
;     for (int c = 0; c < 24; ++c) {
;         float pre = __int_as_float(__builtin_amdgcn_readlane(bvv, c));
; #pragma unroll
;         for (int r = 0; r < 16; ++r) pre += z[r] * __int_as_float(__builtin_amdgcn_readlane(wvv[(24 * r + c) >> 6], (24 * r + c) & 63));
;         const float la = (fminf(pre, 0.f) - __logf(1.f + __expf(-fabsf(pre)))) * (1.f / 16.f);
;         const float inc = wave_incl_scan(la);
;         const float total = __int_as_float(__builtin_amdgcn_readlane(__float_as_int(inc), 63));
;         bc[c] = dir ? (total - inc + la) : inc; tot[c] = total;
;     }
	s_nop 0
	v_mov_b32_dpp v39, v39 row_shr:1 row_mask:0xf bank_mask:0xf bound_ctrl:1
	v_fmac_f32_e32 v39, 0x3d800000, v38
	s_nop 1
	v_add_f32_dpp v39, v39, v39 row_shr:2 row_mask:0xf bank_mask:0xf bound_ctrl:1
	s_nop 1
	v_add_f32_dpp v39, v39, v39 row_shr:4 row_mask:0xf bank_mask:0xf bound_ctrl:1
	s_nop 1
	v_add_f32_dpp v39, v39, v39 row_shr:8 row_mask:0xf bank_mask:0xf bound_ctrl:1
	s_nop 1
	v_mov_b32_dpp v40, v39 row_bcast:15 row_mask:0xa bank_mask:0xf
	v_add_f32_e32 v39, v39, v40
	v_mov_b32_e32 v40, v35
	s_nop 1
	v_mov_b32_dpp v40, v39 row_bcast:31 row_mask:0xc bank_mask:0xf
	v_add_f32_e32 v39, v39, v40
	s_nop 0
	v_readlane_b32 s68, v39, 63
	s_nop 1
	v_sub_f32_e32 v40, s68, v39
	v_fmac_f32_e32 v40, 0x3d800000, v38
	v_mov_b32_e32 v38, s2
	v_fmac_f32_e32 v38, s3, v64
	v_readlane_b32 s2, v26, 46
	v_readlane_b32 s3, v31, 62
	v_cndmask_b32_e64 v102, v40, v39, s[0:1]
	global_store_dword v251, v102, s[100:101] offset:1280
	v_fmac_f32_e32 v38, s2, v63
	v_readlane_b32 s2, v27, 6
	s_nop 1
	v_fmac_f32_e32 v38, s2, v62
	v_readlane_b32 s2, v27, 30
	s_nop 1
	v_fmac_f32_e32 v38, s2, v61
	v_readlane_b32 s2, v27, 54
	s_nop 1
	v_fmac_f32_e32 v38, s2, v60
	v_readlane_b32 s2, v28, 14
	s_nop 1
	v_fmac_f32_e32 v38, s2, v59
	v_readlane_b32 s2, v28, 38
	s_nop 1
	v_fmac_f32_e32 v38, s2, v58
	v_readlane_b32 s2, v28, 62
	s_nop 1
	v_fmac_f32_e32 v38, s2, v57
	v_readlane_b32 s2, v29, 22
	s_nop 1
	v_fmac_f32_e32 v38, s2, v56
	v_readlane_b32 s2, v29, 46
	s_nop 1
	v_fmac_f32_e32 v38, s2, v55
	v_readlane_b32 s2, v30, 6
	s_nop 1
	v_fmac_f32_e32 v38, s2, v54
	v_readlane_b32 s2, v30, 30
	s_nop 1
	v_fmac_f32_e32 v38, s2, v53
	v_readlane_b32 s2, v30, 54
	s_nop 1
	v_fmac_f32_e32 v38, s2, v52
	v_readlane_b32 s2, v31, 14
	s_nop 1
	v_fmac_f32_e32 v38, s2, v34
	v_readlane_b32 s2, v31, 38
	s_nop 1
	v_pk_mul_f32 v[104:105], v[50:51], s[2:3]
	v_readlane_b32 s2, v32, 23
	v_add_f32_e32 v38, v38, v104
	v_add_f32_e32 v38, v38, v105
	v_min_f32_e32 v39, 0, v38
	v_mul_f32_e64 v38, |v38|, s72
	v_exp_f32_e32 v38, v38
	v_readlane_b32 s3, v26, 23
	v_add_f32_e32 v38, 1.0, v38
	v_cmp_gt_f32_e32 vcc, s78, v38
	s_nop 1
	v_cndmask_b32_e64 v40, 0, 32, vcc
	v_ldexp_f32 v38, v38, v40
	v_log_f32_e32 v38, v38
	s_nop 0
	v_mul_f32_e32 v40, 0x3f317217, v38
	v_fma_f32 v40, v38, s87, -v40
	v_fmac_f32_e32 v40, 0x3377d1cf, v38
	v_fmac_f32_e32 v40, 0x3f317217, v38
	v_cmp_lt_f32_e64 s[10:11], |v38|, s97
	s_nop 1
	v_cndmask_b32_e64 v38, v38, v40, s[10:11]
	v_cndmask_b32_e32 v40, 0, v222, vcc
	v_sub_f32_e32 v38, v38, v40
	v_sub_f32_e32 v38, v39, v38
	v_mul_f32_e32 v39, 0x3d800000, v38
	v_mov_b32_e32 v40, v35
	s_nop 0
	v_mov_b32_dpp v39, v39 row_shr:1 row_mask:0xf bank_mask:0xf bound_ctrl:1
	v_fmac_f32_e32 v39, 0x3d800000, v38
	s_nop 1
	v_add_f32_dpp v39, v39, v39 row_shr:2 row_mask:0xf bank_mask:0xf bound_ctrl:1
	s_nop 1
	v_add_f32_dpp v39, v39, v39 row_shr:4 row_mask:0xf bank_mask:0xf bound_ctrl:1
	s_nop 1
	v_add_f32_dpp v39, v39, v39 row_shr:8 row_mask:0xf bank_mask:0xf bound_ctrl:1
	s_nop 1
	v_mov_b32_dpp v40, v39 row_bcast:15 row_mask:0xa bank_mask:0xf
	v_add_f32_e32 v39, v39, v40
	v_mov_b32_e32 v40, v35
	s_nop 1
	v_mov_b32_dpp v40, v39 row_bcast:31 row_mask:0xc bank_mask:0xf
	v_add_f32_e32 v39, v39, v40
	s_nop 0
	v_readlane_b32 s69, v39, 63
	s_nop 1
	v_sub_f32_e32 v40, s69, v39
	v_fmac_f32_e32 v40, 0x3d800000, v38
	v_cndmask_b32_e64 v38, v40, v39, s[0:1]
	global_store_dword v251, v38, s[100:101] offset:1536
	v_mov_b32_e32 v39, s2
	v_fmac_f32_e32 v39, s3, v64
	v_readlane_b32 s2, v26, 47
	v_readlane_b32 s3, v31, 63
	v_sub_f32_e32 v38, s69, v38
	v_fmac_f32_e32 v39, s2, v63
	v_readlane_b32 s2, v27, 7
	v_mul_f32_e32 v38, 0x3fb8aa3b, v38
	v_exp_f32_e32 v38, v38
	v_fmac_f32_e32 v39, s2, v62
	v_readlane_b32 s2, v27, 31
	v_and_b32_e32 v62, 0xffff0000, v17
	s_nop 0
	v_fmac_f32_e32 v39, s2, v61
	v_readlane_b32 s2, v27, 55
	v_lshlrev_b32_e32 v61, 16, v17
	v_sub_f32_e32 v17, s29, v79
	v_fmac_f32_e32 v39, s2, v60
	v_readlane_b32 s2, v28, 15
	v_and_b32_e32 v60, 0xffff0000, v16
	v_mul_f32_e32 v17, 0x3fb8aa3b, v17
	v_fmac_f32_e32 v39, s2, v59
	v_readlane_b32 s2, v28, 39
	v_lshlrev_b32_e32 v59, 16, v16
	v_sub_f32_e32 v16, s30, v68
	v_fmac_f32_e32 v39, s2, v58
	v_readlane_b32 s2, v28, 63
	v_and_b32_e32 v58, 0xffff0000, v15
	v_mul_f32_e32 v16, 0x3fb8aa3b, v16
	v_fmac_f32_e32 v39, s2, v57
	v_readlane_b32 s2, v29, 23
	v_lshlrev_b32_e32 v57, 16, v15
	v_sub_f32_e32 v15, s36, v66
	v_fmac_f32_e32 v39, s2, v56
	v_readlane_b32 s2, v29, 47
	v_and_b32_e32 v56, 0xffff0000, v14
	v_mul_f32_e32 v15, 0x3fb8aa3b, v15
	v_fmac_f32_e32 v39, s2, v55
	v_readlane_b32 s2, v30, 7
	v_lshlrev_b32_e32 v55, 16, v14
	v_sub_f32_e32 v14, s54, v65
	v_fmac_f32_e32 v39, s2, v54
	v_readlane_b32 s2, v30, 31
	v_mul_f32_e32 v14, 0x3fb8aa3b, v14
	v_exp_f32_e32 v14, v14
	v_fmac_f32_e32 v39, s2, v53
	v_readlane_b32 s2, v30, 55
	v_exp_f32_e32 v15, v15
	v_exp_f32_e32 v16, v16
	v_fmac_f32_e32 v39, s2, v52
	v_readlane_b32 s2, v31, 15
	v_exp_f32_e32 v17, v17
	v_lshlrev_b32_e32 v52, 16, v43
	v_fmac_f32_e32 v39, s2, v34
	v_readlane_b32 s2, v31, 39
	v_and_b32_e32 v43, 0xffff0000, v43
	v_lshlrev_b32_e32 v53, 16, v44
	v_pk_mul_f32 v[50:51], v[50:51], s[2:3]
	v_and_b32_e32 v44, 0xffff0000, v44
	v_add_f32_e32 v34, v39, v50
	v_add_f32_e32 v34, v34, v51
	v_min_f32_e32 v39, 0, v34
	v_mul_f32_e64 v34, |v34|, s72
	v_exp_f32_e32 v34, v34
	v_lshlrev_b32_e32 v50, 16, v49
	v_and_b32_e32 v49, 0xffff0000, v49
	v_lshlrev_b32_e32 v51, 16, v42
	v_add_f32_e32 v34, 1.0, v34
	v_cmp_gt_f32_e32 vcc, s78, v34
	v_and_b32_e32 v42, 0xffff0000, v42
	v_lshlrev_b32_e32 v54, 16, v45
	v_cndmask_b32_e64 v40, 0, 32, vcc
	v_ldexp_f32 v34, v34, v40
	v_log_f32_e32 v34, v34
	v_and_b32_e32 v45, 0xffff0000, v45
; __device__ __forceinline__ unsigned pk2(float lo, float hi) { return cvtpk(lo, hi); }
; __device__ __forceinline__ float lo16(unsigned w) { return __uint_as_float(w << 16); }
; template <bool PHC>
; __device__ __forceinline__ void gla_pair(const KPD& kp, int l, int pair, unsigned char* lds, int tid, int lane, int wave, v4u& pz0, v4u& pz1, v4u& pw0, v4u& pw1, int next_pair) {
;     ...
; #pragma unroll
;     for (int c = 0; c < 24; ++c) {
;         float pre = __int_as_float(__builtin_amdgcn_readlane(bvv, c));
; #pragma unroll
;         for (int r = 0; r < 16; ++r) pre += z[r] * __int_as_float(__builtin_amdgcn_readlane(wvv[(24 * r + c) >> 6], (24 * r + c) & 63));
;         const float la = (fminf(pre, 0.f) - __logf(1.f + __expf(-fabsf(pre)))) * (1.f / 16.f);
;         const float inc = wave_incl_scan(la);
;         const float total = __int_as_float(__builtin_amdgcn_readlane(__float_as_int(inc), 63));
;         bc[c] = dir ? (total - inc + la) : inc; tot[c] = total;
;     }
;     float qv[24], kv[24];
; #pragma unroll
;     for (int i = 0; i < 3; ++i) {
;         qv[8 * i] = lo16(qraw[i].x); qv[8 * i + 1] = hi16(qraw[i].x); qv[8 * i + 2] = lo16(qraw[i].y); qv[8 * i + 3] = hi16(qraw[i].y);
;         qv[8 * i + 4] = lo16(qraw[i].z); qv[8 * i + 5] = hi16(qraw[i].z); qv[8 * i + 6] = lo16(qraw[i].w); qv[8 * i + 7] = hi16(qraw[i].w);
;         kv[8 * i] = lo16(kraw[i].x); kv[8 * i + 1] = hi16(kraw[i].x); kv[8 * i + 2] = lo16(kraw[i].y); kv[8 * i + 3] = hi16(kraw[i].y);
;         kv[8 * i + 4] = lo16(kraw[i].z); kv[8 * i + 5] = hi16(kraw[i].z); kv[8 * i + 6] = lo16(kraw[i].w); kv[8 * i + 7] = hi16(kraw[i].w); }
;     const size_t stbase = (size_t)((dir * 4 + b) * NCH + n);
;     if constexpr (!PHC) {
;         bf16* Vr = (bf16*)L;
;         bf16* KE = (bf16*)(L + 13312);
;         { unsigned kw[12];
; #pragma unroll
;           for (int i = 0; i < 12; ++i) kw[i] = pk2(kv[2 * i] * __expf(tot[2 * i] - bc[2 * i]), kv[2 * i + 1] * __expf(tot[2 * i + 1] - bc[2 * i + 1]));
;           v4u* ko = (v4u*)(KE + (dir * 64 + lane) * 56 + d0);
; #pragma unroll
;           for (int i = 0; i < 3; ++i) ko[i] = (v4u){kw[4 * i], kw[4 * i + 1], kw[4 * i + 2], kw[4 * i + 3]}; }
;         if (lane == 0) {
; #pragma unroll
;             for (int c = 0; c < 24; ++c) DEC[stbase * 192 + h * 48 + d0 + c] = __expf(tot[c]);
;         }
	s_add_i32 s2, s52, s41
	s_mulk_i32 s2, 0x84
	v_mul_f32_e32 v40, 0x3f317217, v34
	v_fma_f32 v40, v34, s87, -v40
	v_fmac_f32_e32 v40, 0x3377d1cf, v34
	v_fmac_f32_e32 v40, 0x3f317217, v34
	v_cmp_lt_f32_e64 s[10:11], |v34|, s97
	s_add_i32 s2, s2, s53
	s_ashr_i32 s3, s2, 31
	v_cndmask_b32_e64 v34, v34, v40, s[10:11]
	v_cndmask_b32_e32 v40, 0, v222, vcc
	v_sub_f32_e32 v34, v34, v40
	v_sub_f32_e32 v34, v39, v34
	v_mul_f32_e32 v39, 0x3d800000, v34
	v_mov_b32_e32 v40, v35
	v_mul_f32_e32 v38, v38, v61
	v_mov_b32_dpp v39, v39 row_shr:1 row_mask:0xf bank_mask:0xf bound_ctrl:1
	v_fmac_f32_e32 v39, 0x3d800000, v34
	s_nop 1
	v_add_f32_dpp v39, v39, v39 row_shr:2 row_mask:0xf bank_mask:0xf bound_ctrl:1
	s_nop 1
	v_add_f32_dpp v39, v39, v39 row_shr:4 row_mask:0xf bank_mask:0xf bound_ctrl:1
	s_nop 1
	v_add_f32_dpp v39, v39, v39 row_shr:8 row_mask:0xf bank_mask:0xf bound_ctrl:1
	s_nop 1
	v_mov_b32_dpp v40, v39 row_bcast:15 row_mask:0xa bank_mask:0xf
	v_add_f32_e32 v39, v39, v40
	v_mov_b32_e32 v40, v35
	s_nop 1
	v_mov_b32_dpp v40, v39 row_bcast:31 row_mask:0xc bank_mask:0xf
	v_add_f32_e32 v39, v39, v40
	s_nop 0
	v_readlane_b32 s72, v39, 63
	s_nop 1
	v_sub_f32_e32 v40, s72, v39
	v_fmac_f32_e32 v40, 0x3d800000, v34
	v_cndmask_b32_e64 v34, v40, v39, s[0:1]
	global_store_dword v251, v34, s[100:101] offset:1792
	v_lshlrev_b32_e32 v39, 16, v46
	v_and_b32_e32 v40, 0xffff0000, v46
	v_mul_f32_e32 v14, v14, v39
	v_mul_f32_e32 v15, v15, v40
	v_cvt_pk_bf16_f32 v14, v14, v15
	v_sub_f32_e32 v15, s34, v67
	v_mul_f32_e32 v15, 0x3fb8aa3b, v15
	v_exp_f32_e32 v15, v15
	v_and_b32_e32 v46, 0xffff0000, v47
	v_mul_f32_e32 v16, v16, v46
	v_lshlrev_b32_e32 v47, 16, v48
	v_mul_f32_e32 v15, v15, v41
	v_cvt_pk_bf16_f32 v15, v15, v16
	v_sub_f32_e32 v16, s28, v69
	v_mul_f32_e32 v16, 0x3fb8aa3b, v16
	v_exp_f32_e32 v16, v16
	v_and_b32_e32 v48, 0xffff0000, v48
	v_mul_f32_e32 v17, v17, v48
	v_sub_f32_e32 v39, s35, v83
	v_mul_f32_e32 v16, v16, v47
	v_cvt_pk_bf16_f32 v16, v16, v17
	v_sub_f32_e32 v17, s31, v81
	v_mul_f32_e32 v17, 0x3fb8aa3b, v17
	v_mul_f32_e32 v39, 0x3fb8aa3b, v39
	v_exp_f32_e32 v17, v17
	v_exp_f32_e32 v39, v39
	v_sub_f32_e32 v40, s55, v87
	v_mul_f32_e32 v40, 0x3fb8aa3b, v40
	v_mul_f32_e32 v17, v17, v50
	v_mul_f32_e32 v39, v39, v49
	v_cvt_pk_bf16_f32 v17, v17, v39
	v_sub_f32_e32 v39, s37, v85
	v_mul_f32_e32 v39, 0x3fb8aa3b, v39
	v_exp_f32_e32 v39, v39
	v_exp_f32_e32 v40, v40
	v_sub_f32_e32 v34, s72, v34
	v_mul_f32_e32 v34, 0x3fb8aa3b, v34
	v_mul_f32_e32 v39, v39, v51
	v_mul_f32_e32 v40, v40, v42
	v_cvt_pk_bf16_f32 v42, v39, v40
	v_sub_f32_e32 v39, s56, v89
	v_sub_f32_e32 v40, s57, v91
	v_mul_f32_e32 v39, 0x3fb8aa3b, v39
	v_mul_f32_e32 v40, 0x3fb8aa3b, v40
	v_exp_f32_e32 v39, v39
	v_exp_f32_e32 v40, v40
	v_exp_f32_e32 v34, v34
	v_mul_f32_e32 v39, v39, v52
	v_mul_f32_e32 v40, v40, v43
	v_cvt_pk_bf16_f32 v43, v39, v40
	v_sub_f32_e32 v39, s59, v93
	v_sub_f32_e32 v40, s60, v94
	v_mul_f32_e32 v39, 0x3fb8aa3b, v39
	v_mul_f32_e32 v40, 0x3fb8aa3b, v40
	v_exp_f32_e32 v39, v39
	v_exp_f32_e32 v40, v40
	v_mul_f32_e32 v34, v34, v62
	v_cvt_pk_bf16_f32 v49, v38, v34
	v_mul_f32_e32 v39, v39, v53
	v_mul_f32_e32 v40, v40, v44
	v_cvt_pk_bf16_f32 v44, v39, v40
	v_sub_f32_e32 v39, s61, v95
	v_sub_f32_e32 v40, s62, v96
	v_mul_f32_e32 v39, 0x3fb8aa3b, v39
	v_mul_f32_e32 v40, 0x3fb8aa3b, v40
	v_exp_f32_e32 v39, v39
	v_exp_f32_e32 v40, v40
	v_mul_f32_e32 v39, v39, v54
	v_mul_f32_e32 v40, v40, v45
	v_cvt_pk_bf16_f32 v45, v39, v40
	v_sub_f32_e32 v39, s63, v97
	v_sub_f32_e32 v40, s64, v98
	v_mul_f32_e32 v39, 0x3fb8aa3b, v39
	v_mul_f32_e32 v40, 0x3fb8aa3b, v40
	v_exp_f32_e32 v39, v39
	v_exp_f32_e32 v40, v40
	v_mul_f32_e32 v39, v39, v55
	v_mul_f32_e32 v40, v40, v56
	v_cvt_pk_bf16_f32 v46, v39, v40
	v_sub_f32_e32 v39, s65, v99
	v_sub_f32_e32 v40, s66, v100
	v_mul_f32_e32 v39, 0x3fb8aa3b, v39
	v_mul_f32_e32 v40, 0x3fb8aa3b, v40
	v_exp_f32_e32 v39, v39
	v_exp_f32_e32 v40, v40
	v_mul_f32_e32 v39, v39, v57
	v_mul_f32_e32 v40, v40, v58
	v_cvt_pk_bf16_f32 v47, v39, v40
	v_sub_f32_e32 v39, s67, v101
	v_sub_f32_e32 v40, s68, v102
	v_mul_f32_e32 v39, 0x3fb8aa3b, v39
	v_mul_f32_e32 v40, 0x3fb8aa3b, v40
	v_exp_f32_e32 v39, v39
	v_exp_f32_e32 v40, v40
	v_mul_f32_e32 v39, v39, v59
	v_mul_f32_e32 v40, v40, v60
	v_cvt_pk_bf16_f32 v48, v39, v40
	ds_write_b128 v122, v[14:17] offset:13312
	ds_write_b128 v122, v[42:45] offset:13328
	ds_write_b128 v122, v[46:49] offset:13344
	s_and_saveexec_b64 s[10:11], s[4:5]
	s_cbranch_execz .LBB0_266
	s_mul_i32 s13, s2, 0x300
	s_mul_hi_i32 s12, s2, 0x300
	s_add_u32 s13, s50, s13
	s_addc_u32 s12, s49, s12
	s_lshl_b32 s49, s51, 2
	v_mul_f32_e32 v14, s54, v223
	v_mul_f32_e32 v15, s36, v223
	v_mul_f32_e32 v16, s34, v223
	v_mul_f32_e32 v17, s30, v223
	s_add_u32 s13, s13, s49
	v_exp_f32_e32 v14, v14
	v_exp_f32_e32 v15, v15
	v_exp_f32_e32 v16, v16
	v_exp_f32_e32 v17, v17
	s_addc_u32 s12, s12, 0
	s_lshl_b32 s49, s40, 2
	s_add_u32 s50, s13, s49
	s_addc_u32 s51, s12, 0
	v_mov_b32_e32 v34, 0x19b00000
	global_store_dwordx4 v34, v[14:17], s[50:51]
	s_add_u32 s12, s50, 0x19b00000
	s_addc_u32 s13, s51, 0
	v_mul_f32_e32 v14, s28, v223
	v_mul_f32_e32 v15, s29, v223
	v_mul_f32_e32 v16, s31, v223
	v_mul_f32_e32 v17, s35, v223
	v_exp_f32_e32 v14, v14
	v_exp_f32_e32 v15, v15
	v_exp_f32_e32 v16, v16
	v_exp_f32_e32 v17, v17
	global_store_dwordx4 v35, v[14:17], s[12:13] offset:16
	s_nop 1
	v_mul_f32_e32 v14, s37, v223
	v_mul_f32_e32 v15, s55, v223
	v_mul_f32_e32 v16, s56, v223
	v_mul_f32_e32 v17, s57, v223
	v_exp_f32_e32 v14, v14
	v_exp_f32_e32 v15, v15
	v_exp_f32_e32 v16, v16
	v_exp_f32_e32 v17, v17
	global_store_dwordx4 v35, v[14:17], s[12:13] offset:32
	s_nop 1
	v_mul_f32_e32 v14, s59, v223
	v_mul_f32_e32 v15, s60, v223
	v_mul_f32_e32 v16, s61, v223
	v_mul_f32_e32 v17, s62, v223
	v_exp_f32_e32 v14, v14
	v_exp_f32_e32 v15, v15
	v_exp_f32_e32 v16, v16
	v_exp_f32_e32 v17, v17
	global_store_dwordx4 v35, v[14:17], s[12:13] offset:48
	s_nop 1
	v_mul_f32_e32 v14, s63, v223
	v_mul_f32_e32 v15, s64, v223
	v_mul_f32_e32 v16, s65, v223
	v_mul_f32_e32 v17, s66, v223
	v_exp_f32_e32 v14, v14
	v_exp_f32_e32 v15, v15
	v_exp_f32_e32 v16, v16
	v_exp_f32_e32 v17, v17
	global_store_dwordx4 v35, v[14:17], s[12:13] offset:64
	s_nop 1
	v_mul_f32_e32 v14, s67, v223
	v_mul_f32_e32 v15, s68, v223
	v_mul_f32_e32 v16, s69, v223
	v_mul_f32_e32 v17, s72, v223
	v_exp_f32_e32 v14, v14
	v_exp_f32_e32 v15, v15
	v_exp_f32_e32 v16, v16
	v_exp_f32_e32 v17, v17
	global_store_dwordx4 v35, v[14:17], s[12:13] offset:80

; template <bool PHC>
; __device__ __forceinline__ void gla_pair(const KPD& kp, int l, int pair, unsigned char* lds, int tid, int lane, int wave, v4u& pz0, v4u& pz1, v4u& pw0, v4u& pw1, int next_pair) {
;     ...
;     const int h = item & 3, sc = item >> 2; int b, n, rowbase; chunk_coords(sc, b, n, rowbase);
;     unsigned char* L = lds + half * 69632;
;     const bf16* P = (const bf16*)(kp.ws() + WS_P);
;     float* ST = (float*)(kp.ws() + WS_ST); float* DEC = (float*)(kp.ws() + WS_DEC);
;     const int dir = w4 >> 1, d0 = 24 * (w4 & 1);
;     const bf16* prow = P + (size_t)(rowbase + lane) * INP;
;     v4u vpre[3];
; #pragma unroll
;     for (int i = 0; i < 3; ++i) { const int idx = t4 + 256 * i; vpre[i] = *(const v4u*)(P + (size_t)(rowbase + idx / 12) * INP + C_GV + h * 96 + 8 * (idx % 12)); }
;     v2u spre[9];
;     if constexpr (PHC) { const bf16* SI = (const bf16*)(kp.ws() + WS_SI);
; #pragma unroll
;         for (int i = 0; i < 9; ++i) { const int idx = t4 + 256 * i; const int dd = idx / 1152, e = (idx % 1152) * 4;
;             spre[i] = *(const v2u*)(SI + ((size_t)((dd * 4 + b) * NCH + n) * 4 + h) * 4608 + e); }
;     }
;     float z[16];
;     { const v4u z0 = pz0, z1 = pz1;
;       z[0] = lo16(z0.x); z[1] = hi16(z0.x); z[2] = lo16(z0.y); z[3] = hi16(z0.y); z[4] = lo16(z0.z); z[5] = hi16(z0.z); z[6] = lo16(z0.w); z[7] = hi16(z0.w);
;       z[8] = lo16(z1.x); z[9] = hi16(z1.x); z[10] = lo16(z1.y); z[11] = hi16(z1.y); z[12] = lo16(z1.z); z[13] = hi16(z1.z); z[14] = lo16(z1.w); z[15] = hi16(z1.w); }
;     v4u qraw[3], kraw[3];
; #pragma unroll
;     for (int i = 0; i < 3; ++i) { qraw[i] = *((const v4u*)(prow + C_GQ + h * 48 + d0) + i); kraw[i] = *((const v4u*)(prow + C_GK + h * 48 + d0) + i); }
;     const int wvv[6] = {(int)pw0.x, (int)pw0.y, (int)pw0.z, (int)pw0.w, (int)pw1.x, (int)pw1.y};
;     const int bvv = (int)pw1.z;
;     float bc[24], tot[24];
; #pragma unroll
;     for (int c = 0; c < 24; ++c) {
;         float pre = __int_as_float(__builtin_amdgcn_readlane(bvv, c));
; #pragma unroll
;         for (int r = 0; r < 16; ++r) pre += z[r] * __int_as_float(__builtin_amdgcn_readlane(wvv[(24 * r + c) >> 6], (24 * r + c) & 63));
;         const float la = (fminf(pre, 0.f) - __logf(1.f + __expf(-fabsf(pre)))) * (1.f / 16.f);
;         const float inc = wave_incl_scan(la);
.LBB0_459:
	ds_read_b64 v[250:251], v204
	v_readfirstlane_b32 vcc_lo, v225
	s_lshl_b32 vcc_hi, s2, 2
	s_lshr_b32 vcc_lo, vcc_lo, 6
	s_and_b32 vcc_lo, vcc_lo, 3
	s_add_i32 vcc_lo, vcc_lo, vcc_hi
	s_mul_i32 vcc_lo, vcc_lo, 0x1800
	s_waitcnt lgkmcnt(0)
	v_readfirstlane_b32 s100, v250
	v_readfirstlane_b32 s101, v251
	v_mbcnt_lo_u32_b32 v250, -1, 0
	v_mbcnt_hi_u32_b32 v250, -1, v250
	s_add_u32 s100, s100, 0x3400000
	s_addc_u32 s101, s101, 0
	s_add_u32 s100, s100, vcc_lo
	s_addc_u32 s101, s101, 0
	v_lshlrev_b32_e32 v250, 2, v250
	v_add_u32_e32 v251, 0x1000, v250
	global_load_dword v226, v250, s[100:101]
	global_load_dword v227, v250, s[100:101] offset:256
	global_load_dword v228, v250, s[100:101] offset:512
	global_load_dword v229, v250, s[100:101] offset:768
	global_load_dword v230, v250, s[100:101] offset:1024
	global_load_dword v231, v250, s[100:101] offset:1280
	global_load_dword v232, v250, s[100:101] offset:1536
	global_load_dword v233, v250, s[100:101] offset:1792
	global_load_dword v234, v250, s[100:101] offset:2048
	global_load_dword v235, v250, s[100:101] offset:2304
	global_load_dword v236, v250, s[100:101] offset:2560
	global_load_dword v237, v250, s[100:101] offset:2816
	global_load_dword v238, v250, s[100:101] offset:3072
	global_load_dword v239, v250, s[100:101] offset:3328
	global_load_dword v240, v250, s[100:101] offset:3584
	global_load_dword v241, v250, s[100:101] offset:3840
	global_load_dword v242, v251, s[100:101]
	global_load_dword v243, v251, s[100:101] offset:256
	global_load_dword v244, v251, s[100:101] offset:512
	global_load_dword v245, v251, s[100:101] offset:768
	global_load_dword v246, v251, s[100:101] offset:1024
	global_load_dword v247, v251, s[100:101] offset:1280
	global_load_dword v248, v251, s[100:101] offset:1536
	global_load_dword v249, v251, s[100:101] offset:1792
	v_readlane_b32 s0, v253, 17
	s_add_i32 s3, s0, s3
	v_readlane_b32 s0, v254, 32
	s_add_i32 s59, s59, s0
	v_readlane_b32 s0, v254, 48
	v_readlane_b32 s1, v254, 49
	ds_read_b64 v[2:3], v204
	s_and_b64 s[0:1], s[0:1], exec
	s_cselect_b32 s0, s3, s59
	s_cmp_lt_i32 s0, s87
	s_cselect_b32 s77, s0, -1
	s_lshl_b32 s0, s9, 6
	s_and_b32 s10, s2, 3
	s_add_i32 s80, s8, s0
	s_waitcnt lgkmcnt(0)
	v_readfirstlane_b32 s0, v2
	v_readfirstlane_b32 s1, v3
	s_add_u32 s0, s0, 0x7800000
	s_addc_u32 s1, s1, 0
	ds_read_b64 v[2:3], v204
	s_waitcnt lgkmcnt(0)
	ds_read_b64 v[2:3], v204
	s_mul_i32 s78, s10, 0x60
	s_waitcnt lgkmcnt(0)
	v_add_u32_e32 v2, s80, v37
	v_mov_b64_e32 v[60:61], s[0:1]
	v_add_u32_e32 v4, s80, v82
	v_add_u32_e32 v10, s80, v95
	v_mad_i64_i32 v[2:3], s[0:1], v2, s33, v[60:61]
	s_lshl_b32 s8, s78, 1
	s_mov_b32 s9, s79
	v_mad_i64_i32 v[4:5], s[0:1], v4, s33, v[60:61]
	v_mad_i64_i32 v[10:11], s[0:1], v10, s33, v[60:61]
	v_lshl_add_u64 v[2:3], v[2:3], 0, s[8:9]
	v_lshl_add_u64 v[4:5], v[4:5], 0, s[8:9]
	v_mov_b32_e32 v55, v35
	v_lshl_add_u64 v[10:11], v[10:11], 0, s[8:9]
	v_mov_b32_e32 v57, v35
	v_lshl_add_u64 v[2:3], v[2:3], 0, v[34:35]
	v_lshl_add_u64 v[6:7], v[4:5], 0, v[54:55]
	v_lshl_add_u64 v[10:11], v[10:11], 0, v[56:57]
	global_load_dwordx4 v[2:5], v[2:3], off offset:768
	global_load_dwordx4 v[6:9], v[6:7], off offset:768
	s_mul_i32 s2, s81, 0x84
	global_load_dwordx4 v[10:13], v[10:11], off offset:768
	ds_read_b64 v[14:15], v204
	v_lshlrev_b32_e32 v16, 16, v49
	v_and_b32_e32 v17, 0xffff0000, v49
	v_lshlrev_b32_e32 v18, 16, v42
	v_and_b32_e32 v19, 0xffff0000, v42
	s_waitcnt lgkmcnt(0)
	v_readfirstlane_b32 s0, v14
	v_readfirstlane_b32 s1, v15
	s_add_u32 s0, s0, 0x1a000000
	s_addc_u32 s1, s1, 0
	s_add_i32 s2, s2, s97
	s_ashr_i32 s3, s2, 31
	s_lshl_b64 s[2:3], s[2:3], 2
	s_or_b32 s72, s2, s10
	s_mul_i32 s2, s3, 0x2400
	s_mul_hi_u32 s11, s72, 0x2400
	s_add_i32 s11, s11, s2
	v_lshlrev_b32_e32 v20, 16, v43
	v_and_b32_e32 v21, 0xffff0000, v43
	v_lshlrev_b32_e32 v22, 16, v44
	v_and_b32_e32 v23, 0xffff0000, v44
	v_lshlrev_b32_e32 v24, 16, v45
	v_and_b32_e32 v25, 0xffff0000, v45
	v_lshlrev_b32_e32 v26, 16, v46
	v_and_b32_e32 v27, 0xffff0000, v46
	v_lshlrev_b32_e32 v28, 16, v47
	v_and_b32_e32 v29, 0xffff0000, v47
	v_lshlrev_b32_e32 v30, 16, v48
	v_and_b32_e32 v31, 0xffff0000, v48
	s_mov_b32 s12, 0xbfb8aa3b
	s_mov_b32 s13, 0x800000
	s_mulk_i32 s72, 0x2400
	s_mov_b32 s14, 0x3f317217
	s_mov_b32 s15, 0x7f800000
	v_mov_b32_e32 v59, v35
	s_add_u32 s2, s0, s72
	s_addc_u32 s3, s1, s11
	v_mov_b64_e32 v[14:15], s[0:1]
	global_load_dwordx2 v[62:63], v108, s[2:3]
	global_load_dwordx2 v[64:65], v109, s[2:3]
	global_load_dwordx2 v[66:67], v110, s[2:3]
	global_load_dwordx2 v[68:69], v111, s[2:3]
	s_add_u32 s2, s2, 0x1290000
	s_addc_u32 s3, s3, 0
	global_load_dwordx2 v[70:71], v115, s[2:3]
	s_cmp_lt_i32 s77, 0
	v_readlane_b32 s72, v88, 34
	v_readlane_b32 s73, v88, 58
	v_readlane_b32 s11, v91, 18
	s_nop 1
	v_mov_b32_e32 v40, s11
	v_readlane_b32 s11, v84, 18
	s_nop 1
	v_fmac_f32_e32 v40, s11, v18
	v_readlane_b32 s11, v84, 42
	s_nop 1
	v_fmac_f32_e32 v40, s11, v19
	v_readlane_b32 s11, v85, 2
	s_nop 1
	v_fmac_f32_e32 v40, s11, v20
	v_readlane_b32 s11, v85, 26
	s_nop 1
	v_fmac_f32_e32 v40, s11, v21
	v_readlane_b32 s11, v85, 50
	s_nop 1
	v_fmac_f32_e32 v40, s11, v22
	v_readlane_b32 s11, v86, 10
	s_nop 1
	v_fmac_f32_e32 v40, s11, v23
	v_readlane_b32 s11, v86, 34
	v_pk_mul_f32 v[32:33], v[16:17], s[72:73]
	s_nop 0
	v_fmac_f32_e32 v40, s11, v24
	v_readlane_b32 s11, v86, 58
	s_nop 1
	v_fmac_f32_e32 v40, s11, v25
	v_readlane_b32 s11, v83, 18
	v_readlane_b32 s0, v88, 35
	s_nop 0
	v_fmac_f32_e32 v40, s11, v26
	v_readlane_b32 s11, v83, 42
	v_readlane_b32 s1, v88, 59
	v_readlane_b32 s72, v88, 36
	v_fmac_f32_e32 v40, s11, v27
	v_readlane_b32 s11, v87, 2
	v_readlane_b32 s73, v88, 60
	s_nop 0
; template <bool PHC>
; __device__ __forceinline__ void gla_pair(const KPD& kp, int l, int pair, unsigned char* lds, int tid, int lane, int wave, v4u& pz0, v4u& pz1, v4u& pw0, v4u& pw1, int next_pair) {
;     ...
; #pragma unroll
;     for (int c = 0; c < 24; ++c) {
;         float pre = __int_as_float(__builtin_amdgcn_readlane(bvv, c));
; #pragma unroll
;         for (int r = 0; r < 16; ++r) pre += z[r] * __int_as_float(__builtin_amdgcn_readlane(wvv[(24 * r + c) >> 6], (24 * r + c) & 63));
;         const float la = (fminf(pre, 0.f) - __logf(1.f + __expf(-fabsf(pre)))) * (1.f / 16.f);
;         const float inc = wave_incl_scan(la);
;         const float total = __int_as_float(__builtin_amdgcn_readlane(__float_as_int(inc), 63));
;         bc[c] = dir ? (total - inc + la) : inc; tot[c] = total;
;     }
	v_fmac_f32_e32 v40, s11, v28
	v_readlane_b32 s11, v87, 26
	s_nop 1
	v_fmac_f32_e32 v40, s11, v29
	v_readlane_b32 s11, v87, 50
	s_nop 1
	v_fmac_f32_e32 v40, s11, v30
	v_readlane_b32 s11, v88, 10
	s_nop 1
	v_fmac_f32_e32 v40, s11, v31
	v_add_f32_e32 v32, v40, v32
	v_add_f32_e32 v178, v32, v33
	v_mul_f32_e64 v32, |v178|, s12
	v_exp_f32_e32 v32, v32
	v_readlane_b32 s11, v91, 20
	v_add_f32_e32 v32, 1.0, v32
	v_cmp_gt_f32_e32 vcc, s13, v32
	s_nop 1
	v_cndmask_b32_e64 v33, 0, 32, vcc
	v_ldexp_f32 v32, v32, v33
	v_log_f32_e32 v38, v32
	v_cndmask_b32_e32 v187, 0, v222, vcc
	v_mul_f32_e32 v32, 0x3f317217, v38
	v_fma_f32 v39, v38, s14, -v32
	v_pk_mul_f32 v[32:33], v[16:17], s[0:1]
	v_readlane_b32 s0, v91, 19
	v_fmac_f32_e32 v39, 0x3377d1cf, v38
	v_fmac_f32_e32 v39, 0x3f317217, v38
	v_mov_b32_e32 v40, s0
	v_readlane_b32 s0, v84, 19
	s_nop 1
	v_fmac_f32_e32 v40, s0, v18
	v_readlane_b32 s0, v84, 43
	s_nop 1
	v_fmac_f32_e32 v40, s0, v19
	v_readlane_b32 s0, v85, 3
	s_nop 1
	v_fmac_f32_e32 v40, s0, v20
	v_readlane_b32 s0, v85, 27
	s_nop 1
	v_fmac_f32_e32 v40, s0, v21
	v_readlane_b32 s0, v85, 51
	s_nop 1
	v_fmac_f32_e32 v40, s0, v22
	v_readlane_b32 s0, v86, 11
	s_nop 1
	v_fmac_f32_e32 v40, s0, v23
	v_readlane_b32 s0, v86, 35
	s_nop 1
	v_fmac_f32_e32 v40, s0, v24
	v_readlane_b32 s0, v86, 59
	s_nop 1
	v_fmac_f32_e32 v40, s0, v25
	v_readlane_b32 s0, v83, 19
	s_nop 1
	v_fmac_f32_e32 v40, s0, v26
	v_readlane_b32 s0, v83, 43
	s_nop 1
	v_fmac_f32_e32 v40, s0, v27
	v_readlane_b32 s0, v87, 3
	s_nop 1
	v_fmac_f32_e32 v40, s0, v28
	v_readlane_b32 s0, v87, 27
	s_nop 1
	v_fmac_f32_e32 v40, s0, v29
	v_readlane_b32 s0, v87, 51
	s_nop 1
	v_fmac_f32_e32 v40, s0, v30
	v_readlane_b32 s0, v88, 11
	s_nop 1
	v_fmac_f32_e32 v40, s0, v31
	v_add_f32_e32 v32, v40, v32
	v_add_f32_e32 v181, v32, v33
	v_mul_f32_e64 v32, |v181|, s12
	v_mov_b32_e32 v40, s11
	v_readlane_b32 s11, v84, 20
	v_exp_f32_e32 v32, v32
	v_cmp_lt_f32_e64 s[0:1], |v38|, s15
	v_fmac_f32_e32 v40, s11, v18
	v_readlane_b32 s11, v84, 44
	v_add_f32_e32 v32, 1.0, v32
	v_cndmask_b32_e64 v186, v38, v39, s[0:1]
	v_fmac_f32_e32 v40, s11, v19
	v_readlane_b32 s11, v85, 4
	v_cmp_gt_f32_e64 s[0:1], s13, v32
	s_nop 0
	v_fmac_f32_e32 v40, s11, v20
	v_readlane_b32 s11, v85, 28
	v_cndmask_b32_e64 v33, 0, 32, s[0:1]
	v_ldexp_f32 v32, v32, v33
	v_fmac_f32_e32 v40, s11, v21
	v_readlane_b32 s11, v85, 52
	v_log_f32_e32 v38, v32
	v_cndmask_b32_e64 v190, 0, v222, s[0:1]
	v_fmac_f32_e32 v40, s11, v22
	v_readlane_b32 s11, v86, 12
	v_mul_f32_e32 v32, 0x3f317217, v38
	v_fma_f32 v39, v38, s14, -v32
	v_fmac_f32_e32 v40, s11, v23
	v_readlane_b32 s11, v86, 36
	v_pk_mul_f32 v[32:33], v[16:17], s[72:73]
	v_fmac_f32_e32 v39, 0x3377d1cf, v38
	v_fmac_f32_e32 v40, s11, v24
	v_readlane_b32 s11, v86, 60
	v_fmac_f32_e32 v39, 0x3f317217, v38
	v_cmp_lt_f32_e64 vcc, |v38|, s15
	v_fmac_f32_e32 v40, s11, v25
	v_readlane_b32 s11, v83, 20
	v_cndmask_b32_e32 v189, v38, v39, vcc
	v_readlane_b32 s0, v88, 37
	v_fmac_f32_e32 v40, s11, v26
	v_readlane_b32 s11, v83, 44
	v_readlane_b32 s1, v88, 61
	s_nop 0
	v_fmac_f32_e32 v40, s11, v27
	v_readlane_b32 s11, v87, 4
	s_nop 1
	v_fmac_f32_e32 v40, s11, v28
	v_readlane_b32 s11, v87, 28
	s_nop 1
	v_fmac_f32_e32 v40, s11, v29
	v_readlane_b32 s11, v87, 52
	s_nop 1
	v_fmac_f32_e32 v40, s11, v30
	v_readlane_b32 s11, v88, 12
	s_nop 1
	v_fmac_f32_e32 v40, s11, v31
	v_add_f32_e32 v32, v40, v32
	v_add_f32_e32 v188, v32, v33
	v_mul_f32_e64 v32, |v188|, s12
	v_exp_f32_e32 v32, v32
	v_readlane_b32 s11, v91, 23
	v_add_f32_e32 v32, 1.0, v32
	v_cmp_gt_f32_e32 vcc, s13, v32
	s_nop 1
	v_cndmask_b32_e64 v33, 0, 32, vcc
	v_ldexp_f32 v32, v32, v33
	v_log_f32_e32 v38, v32
	v_cndmask_b32_e32 v193, 0, v222, vcc
	v_mul_f32_e32 v32, 0x3f317217, v38
	v_fma_f32 v39, v38, s14, -v32
	v_pk_mul_f32 v[32:33], v[16:17], s[0:1]
	v_readlane_b32 s0, v91, 21
	v_fmac_f32_e32 v39, 0x3377d1cf, v38
	v_fmac_f32_e32 v39, 0x3f317217, v38
	v_mov_b32_e32 v40, s0
	v_readlane_b32 s0, v84, 21
	s_nop 1
	v_fmac_f32_e32 v40, s0, v18
	v_readlane_b32 s0, v84, 45
	s_nop 1
	v_fmac_f32_e32 v40, s0, v19
	v_readlane_b32 s0, v85, 5
	s_nop 1
	v_fmac_f32_e32 v40, s0, v20
	v_readlane_b32 s0, v85, 29
	s_nop 1
	v_fmac_f32_e32 v40, s0, v21
	v_readlane_b32 s0, v85, 53
	s_nop 1
	v_fmac_f32_e32 v40, s0, v22
	v_readlane_b32 s0, v86, 13
	s_nop 1
	v_fmac_f32_e32 v40, s0, v23
	v_readlane_b32 s0, v86, 37
	s_nop 1
	v_fmac_f32_e32 v40, s0, v24
	v_readlane_b32 s0, v86, 61
	s_nop 1
	v_fmac_f32_e32 v40, s0, v25
	v_readlane_b32 s0, v83, 21
	s_nop 1
	v_fmac_f32_e32 v40, s0, v26
	v_readlane_b32 s0, v83, 45
	s_nop 1
	v_fmac_f32_e32 v40, s0, v27
	v_readlane_b32 s0, v87, 5
	s_nop 1
	v_fmac_f32_e32 v40, s0, v28
	v_readlane_b32 s0, v87, 29
	s_nop 1
	v_fmac_f32_e32 v40, s0, v29
	v_readlane_b32 s0, v87, 53
	s_nop 1
	v_fmac_f32_e32 v40, s0, v30
	v_readlane_b32 s0, v88, 13
	s_nop 1
	v_fmac_f32_e32 v40, s0, v31
	v_add_f32_e32 v32, v40, v32
	v_add_f32_e32 v191, v32, v33
	v_mul_f32_e64 v32, |v191|, s12
	v_exp_f32_e32 v32, v32
	v_cmp_lt_f32_e64 s[0:1], |v38|, s15
	v_add_f32_e32 v32, 1.0, v32
	v_cmp_gt_f32_e64 s[72:73], s13, v32
	v_cndmask_b32_e64 v192, v38, v39, s[0:1]
	v_readlane_b32 s0, v88, 38
	v_cndmask_b32_e64 v33, 0, 32, s[72:73]
	v_ldexp_f32 v32, v32, v33
	v_log_f32_e32 v38, v32
	v_readlane_b32 s1, v88, 62
	v_cndmask_b32_e64 v196, 0, v222, s[72:73]
	v_readlane_b32 s72, v88, 39
	v_mul_f32_e32 v32, 0x3f317217, v38
	v_fma_f32 v39, v38, s14, -v32
	v_pk_mul_f32 v[32:33], v[16:17], s[0:1]
	v_readlane_b32 s0, v91, 22
	v_fmac_f32_e32 v39, 0x3377d1cf, v38
	v_fmac_f32_e32 v39, 0x3f317217, v38
	v_mov_b32_e32 v40, s0
	v_readlane_b32 s0, v84, 22
	v_cmp_lt_f32_e64 vcc, |v38|, s15
	v_readlane_b32 s73, v88, 63
; template <bool PHC>
; __device__ __forceinline__ void gla_pair(const KPD& kp, int l, int pair, unsigned char* lds, int tid, int lane, int wave, v4u& pz0, v4u& pz1, v4u& pw0, v4u& pw1, int next_pair) {
;     ...
;     if constexpr (PHC) { const bf16* SI = (const bf16*)(kp.ws() + WS_SI);
; #pragma unroll
;         for (int i = 0; i < 9; ++i) { const int idx = t4 + 256 * i; const int dd = idx / 1152, e = (idx % 1152) * 4;
;             spre[i] = *(const v2u*)(SI + ((size_t)((dd * 4 + b) * NCH + n) * 4 + h) * 4608 + e); }
;     }
;     float z[16];
;     { const v4u z0 = pz0, z1 = pz1;
;       z[0] = lo16(z0.x); z[1] = hi16(z0.x); z[2] = lo16(z0.y); z[3] = hi16(z0.y); z[4] = lo16(z0.z); z[5] = hi16(z0.z); z[6] = lo16(z0.w); z[7] = hi16(z0.w);
;       z[8] = lo16(z1.x); z[9] = hi16(z1.x); z[10] = lo16(z1.y); z[11] = hi16(z1.y); z[12] = lo16(z1.z); z[13] = hi16(z1.z); z[14] = lo16(z1.w); z[15] = hi16(z1.w); }
;     v4u qraw[3], kraw[3];
; #pragma unroll
;     for (int i = 0; i < 3; ++i) { qraw[i] = *((const v4u*)(prow + C_GQ + h * 48 + d0) + i); kraw[i] = *((const v4u*)(prow + C_GK + h * 48 + d0) + i); }
;     const int wvv[6] = {(int)pw0.x, (int)pw0.y, (int)pw0.z, (int)pw0.w, (int)pw1.x, (int)pw1.y};
;     const int bvv = (int)pw1.z;
;     float bc[24], tot[24];
; #pragma unroll
;     for (int c = 0; c < 24; ++c) {
;         float pre = __int_as_float(__builtin_amdgcn_readlane(bvv, c));
; #pragma unroll
;         for (int r = 0; r < 16; ++r) pre += z[r] * __int_as_float(__builtin_amdgcn_readlane(wvv[(24 * r + c) >> 6], (24 * r + c) & 63));
;         const float la = (fminf(pre, 0.f) - __logf(1.f + __expf(-fabsf(pre)))) * (1.f / 16.f);
;         const float inc = wave_incl_scan(la);
;         const float total = __int_as_float(__builtin_amdgcn_readlane(__float_as_int(inc), 63));
;         bc[c] = dir ? (total - inc + la) : inc; tot[c] = total;
;     }
;     float qv[24], kv[24];
; #pragma unroll
;     for (int i = 0; i < 3; ++i) {
;         qv[8 * i] = lo16(qraw[i].x); qv[8 * i + 1] = hi16(qraw[i].x); qv[8 * i + 2] = lo16(qraw[i].y); qv[8 * i + 3] = hi16(qraw[i].y);
;         qv[8 * i + 4] = lo16(qraw[i].z); qv[8 * i + 5] = hi16(qraw[i].z); qv[8 * i + 6] = lo16(qraw[i].w); qv[8 * i + 7] = hi16(qraw[i].w);
;         kv[8 * i] = lo16(kraw[i].x); kv[8 * i + 1] = hi16(kraw[i].x); kv[8 * i + 2] = lo16(kraw[i].y); kv[8 * i + 3] = hi16(kraw[i].y);
	v_fmac_f32_e32 v40, s0, v18
	v_readlane_b32 s0, v84, 46
	v_cndmask_b32_e32 v195, v38, v39, vcc
	v_mov_b32_e32 v38, s11
	v_fmac_f32_e32 v40, s0, v19
	v_readlane_b32 s0, v85, 6
	v_readlane_b32 s11, v84, 23
	v_pk_mul_f32 v[16:17], v[16:17], s[72:73]
	v_fmac_f32_e32 v40, s0, v20
	v_readlane_b32 s0, v85, 30
	v_fmac_f32_e32 v38, s11, v18
	v_readlane_b32 s11, v84, 47
	v_fmac_f32_e32 v40, s0, v21
	v_readlane_b32 s0, v85, 54
	v_fmac_f32_e32 v38, s11, v19
	v_readlane_b32 s11, v85, 7
	v_fmac_f32_e32 v40, s0, v22
	v_readlane_b32 s0, v86, 14
	v_fmac_f32_e32 v38, s11, v20
	v_readlane_b32 s11, v85, 31
	v_fmac_f32_e32 v40, s0, v23
	v_readlane_b32 s0, v86, 38
	v_fmac_f32_e32 v38, s11, v21
	v_readlane_b32 s11, v85, 55
	v_fmac_f32_e32 v40, s0, v24
	v_readlane_b32 s0, v86, 62
	v_fmac_f32_e32 v38, s11, v22
	v_readlane_b32 s11, v86, 15
	v_fmac_f32_e32 v40, s0, v25
	v_readlane_b32 s0, v83, 22
	v_fmac_f32_e32 v38, s11, v23
	v_readlane_b32 s11, v86, 39
	v_fmac_f32_e32 v40, s0, v26
	v_readlane_b32 s0, v83, 46
	v_fmac_f32_e32 v38, s11, v24
	v_readlane_b32 s11, v86, 63
	v_fmac_f32_e32 v40, s0, v27
	v_readlane_b32 s0, v87, 6
	v_fmac_f32_e32 v38, s11, v25
	v_readlane_b32 s11, v83, 23
	v_fmac_f32_e32 v40, s0, v28
	v_readlane_b32 s0, v87, 30
	v_fmac_f32_e32 v38, s11, v26
	v_readlane_b32 s11, v83, 47
	v_fmac_f32_e32 v40, s0, v29
	v_readlane_b32 s0, v87, 54
	v_fmac_f32_e32 v38, s11, v27
	v_readlane_b32 s11, v87, 7
	v_fmac_f32_e32 v40, s0, v30
	v_readlane_b32 s0, v88, 14
	v_fmac_f32_e32 v38, s11, v28
	v_readlane_b32 s11, v87, 31
	v_fmac_f32_e32 v40, s0, v31
	v_add_f32_e32 v32, v40, v32
	v_add_f32_e32 v194, v32, v33
	v_fmac_f32_e32 v38, s11, v29
	v_readlane_b32 s11, v87, 55
	v_add_u32_e32 v18, s80, v80
	s_nop 0
	v_fmac_f32_e32 v38, s11, v30
	v_readlane_b32 s11, v88, 15
	s_nop 1
	v_fmac_f32_e32 v38, s11, v31
	v_add_f32_e32 v16, v38, v16
	v_add_f32_e32 v38, v16, v17
	v_mul_f32_e64 v16, |v38|, s12
	v_exp_f32_e32 v16, v16
	s_nop 0
	v_add_f32_e32 v16, 1.0, v16
	v_cmp_gt_f32_e32 vcc, s13, v16
	v_add_u32_e32 v16, s81, v89
	s_movk_i32 s0, 0x84
	v_mul_lo_u32 v16, v16, s0
	v_add_u32_e32 v16, s97, v16
	v_ashrrev_i32_e32 v17, 31, v16
	v_lshlrev_b64 v[16:17], 2, v[16:17]
	v_or_b32_e32 v16, s10, v16
	s_movk_i32 s10, 0x2400
	v_mad_u64_u32 v[14:15], s[0:1], v16, s10, v[14:15]
	v_mad_i32_i24 v15, v17, s10, v15
	v_lshl_add_u64 v[14:15], v[14:15], 0, v[58:59]
	global_load_dwordx2 v[72:73], v112, s[2:3]
	global_load_dwordx2 v[74:75], v113, s[2:3]
	global_load_dwordx2 v[76:77], v114, s[2:3]
	global_load_dwordx2 v[78:79], v[14:15], off
	v_mad_i64_i32 v[14:15], s[0:1], v18, s33, v[60:61]
	v_lshl_add_u64 v[14:15], v[14:15], 0, s[78:79]
	s_waitcnt vmcnt(12)
	v_mov_b32_e32 v55, v226
	v_mov_b32_e32 v57, v227
	s_mov_b32 s97, s79
	v_lshl_add_u64 v[30:31], v[14:15], 0, s[96:97]
	global_load_dwordx4 v[26:29], v[30:31], off offset:16
	global_load_dwordx4 v[50:53], v[30:31], off
	global_load_dwordx4 v[14:17], v[30:31], off offset:416
	global_load_dwordx4 v[22:25], v[30:31], off offset:400
	global_load_dwordx4 v[18:21], v[30:31], off offset:32
	global_load_dwordx4 v[30:33], v[30:31], off offset:384
	v_mov_b32_e32 v59, v228
	v_mov_b32_e32 v128, v229
	v_mov_b32_e32 v129, v230
	v_mov_b32_e32 v130, v231
	v_mov_b32_e32 v131, v232
	s_waitcnt vmcnt(0)
	v_lshlrev_b32_e32 v149, 16, v30
	v_and_b32_e32 v30, 0xffff0000, v30
	v_lshlrev_b32_e32 v150, 16, v31
	v_and_b32_e32 v31, 0xffff0000, v31
	v_mov_b32_e32 v132, v233
	v_lshlrev_b32_e32 v152, 16, v33
	v_and_b32_e32 v33, 0xffff0000, v33
	v_lshlrev_b32_e32 v153, 16, v26
	v_and_b32_e32 v26, 0xffff0000, v26
	v_mov_b32_e32 v133, v234
	v_lshlrev_b32_e32 v151, 16, v32
	v_and_b32_e32 v32, 0xffff0000, v32
	v_lshlrev_b32_e32 v155, 16, v28
	v_and_b32_e32 v28, 0xffff0000, v28
	v_mul_f32_e32 v28, 0x3e13cd3a, v28
	v_lshlrev_b32_e32 v156, 16, v29
	v_and_b32_e32 v29, 0xffff0000, v29
	v_mul_f32_e32 v29, 0x3e13cd3a, v29
	v_mov_b32_e32 v134, v235
	v_and_b32_e32 v158, 0xffff0000, v22
	v_lshlrev_b32_e32 v159, 16, v23
	v_lshlrev_b32_e32 v154, 16, v27
	v_and_b32_e32 v27, 0xffff0000, v27
	v_mov_b32_e32 v135, v236
	v_lshlrev_b32_e32 v157, 16, v22
	v_mul_f32_e32 v22, 0x3fb8aa3b, v132
	v_lshlrev_b32_e32 v161, 16, v24
	v_and_b32_e32 v162, 0xffff0000, v24
	v_exp_f32_e32 v22, v22
	v_mul_f32_e32 v24, 0xbfb8aa3b, v132
	v_exp_f32_e32 v24, v24
	v_mov_b32_e32 v136, v237
	v_lshlrev_b32_e32 v165, 16, v18
	v_and_b32_e32 v160, 0xffff0000, v23
	v_mul_f32_e32 v23, 0xbfb8aa3b, v131
	v_exp_f32_e32 v23, v23
	v_and_b32_e32 v164, 0xffff0000, v25
	v_mov_b32_e32 v137, v238
	v_lshlrev_b32_e32 v167, 16, v19
	v_and_b32_e32 v168, 0xffff0000, v19
	v_mul_f32_e32 v19, 0xbfb8aa3b, v59
	v_exp_f32_e32 v19, v19
	v_lshlrev_b32_e32 v163, 16, v25
	v_mul_f32_e32 v25, 0x3fb8aa3b, v135
	v_exp_f32_e32 v25, v25
	v_mov_b32_e32 v138, v239
	v_and_b32_e32 v166, 0xffff0000, v18
	v_and_b32_e32 v170, 0xffff0000, v20
	v_lshlrev_b32_e32 v171, 16, v21
	v_mov_b32_e32 v139, v240
	v_lshlrev_b32_e32 v173, 16, v14
	v_and_b32_e32 v174, 0xffff0000, v14
	v_mul_f32_e32 v14, 0x3fb8aa3b, v55
	v_exp_f32_e32 v14, v14
	v_lshlrev_b32_e32 v169, 16, v20
	v_mul_f32_e32 v20, 0xbfb8aa3b, v128
	v_exp_f32_e32 v20, v20
	v_mov_b32_e32 v140, v241
	v_and_b32_e32 v176, 0xffff0000, v15
	v_lshlrev_b32_e32 v177, 16, v16
	v_and_b32_e32 v172, 0xffff0000, v21
	v_mul_f32_e32 v21, 0x3fb8aa3b, v131
	v_exp_f32_e32 v21, v21
	v_mov_b32_e32 v141, v242
	v_lshlrev_b32_e32 v175, 16, v15
	v_mul_f32_e32 v15, 0x3fb8aa3b, v57
	v_exp_f32_e32 v15, v15
	v_lshlrev_b32_e32 v179, 16, v17
	v_and_b32_e32 v180, 0xffff0000, v17
	v_mul_f32_e32 v17, 0x3fb8aa3b, v59
	v_exp_f32_e32 v17, v17
	v_mov_b32_e32 v142, v243
	v_and_b32_e32 v178, 0xffff0000, v16
	v_mov_b32_e32 v143, v244
	v_mov_b32_e32 v144, v245
; __device__ __forceinline__ unsigned pk2(float lo, float hi) { return cvtpk(lo, hi); }
; template <bool PHC>
; __device__ __forceinline__ void gla_pair(const KPD& kp, int l, int pair, unsigned char* lds, int tid, int lane, int wave, v4u& pz0, v4u& pz1, v4u& pw0, v4u& pw1, int next_pair) {
;     ...
;         const float qs = 0.14433756729740643f;
;         { unsigned qw[12], kw[12];
; #pragma unroll
;           for (int i = 0; i < 12; ++i) { qw[i] = pk2(qv[2 * i] * qs * __expf(bc[2 * i]), qv[2 * i + 1] * qs * __expf(bc[2 * i + 1])); kw[i] = pk2(kv[2 * i] * __expf(-bc[2 * i]), kv[2 * i + 1] * __expf(-bc[2 * i + 1])); }
;           v4u* qo = (v4u*)(AC + lane * 168 + 64 + dir * 48 + d0); v4u* ko = (v4u*)(KI + (dir * 64 + lane) * 56 + d0);
; #pragma unroll
;           for (int i = 0; i < 3; ++i) { qo[i] = (v4u){qw[4 * i], qw[4 * i + 1], qw[4 * i + 2], qw[4 * i + 3]}; ko[i] = (v4u){kw[4 * i], kw[4 * i + 1], kw[4 * i + 2], kw[4 * i + 3]}; } }
; #pragma unroll
;         for (int i = 0; i < 3; ++i) { const int idx = t4 + 256 * i; const int t = idx / 12, ch = idx % 12; *(v4u*)(Vr + t * 104 + 8 * ch) = vpre[i]; }
; #pragma unroll
;         for (int i = 0; i < 9; ++i) { const int idx = t4 + 256 * i; const int dd = idx / 1152, e = (idx % 1152) * 4, d = e / 96, v = e % 96;
;             *(v2u*)(SB + (dd * 48 + d) * 104 + v) = spre[i]; }
;         __syncthreads();
	v_mov_b32_e32 v145, v246
	v_mov_b32_e32 v146, v247
	v_lshlrev_b32_e32 v148, 16, v53
	v_and_b32_e32 v53, 0xffff0000, v53
	v_mov_b32_e32 v39, v248
	v_lshlrev_b32_e32 v147, 16, v52
	v_and_b32_e32 v52, 0xffff0000, v52
	v_mov_b32_e32 v38, v249
	v_lshlrev_b32_e32 v40, 16, v50
	v_and_b32_e32 v41, 0xffff0000, v50
	v_mul_f32_e32 v16, 0x3e13cd3a, v40
	v_mul_f32_e32 v14, v16, v14
	v_mul_f32_e32 v16, 0x3e13cd3a, v41
	v_mul_f32_e32 v15, v16, v15
	v_cvt_pk_bf16_f32 v14, v14, v15
	v_mul_f32_e32 v15, 0xbfb8aa3b, v57
	v_mul_f32_e32 v16, 0xbfb8aa3b, v55
	v_exp_f32_e32 v15, v15
	v_exp_f32_e32 v16, v16
	v_lshlrev_b32_e32 v50, 16, v51
	v_and_b32_e32 v51, 0xffff0000, v51
	v_mul_f32_e32 v15, v15, v30
	v_mul_f32_e32 v16, v16, v149
	v_cvt_pk_bf16_f32 v18, v16, v15
	v_mul_f32_e32 v15, 0x3e13cd3a, v50
	v_mul_f32_e32 v15, v15, v17
	v_mul_f32_e32 v17, 0x3fb8aa3b, v128
	v_exp_f32_e32 v17, v17
	v_mul_f32_e32 v16, 0x3e13cd3a, v51
	v_mul_f32_e32 v30, 0xbfb8aa3b, v136
	v_exp_f32_e32 v30, v30
	v_mul_f32_e32 v16, v16, v17
	v_cvt_pk_bf16_f32 v15, v15, v16
	v_mul_f32_e32 v16, v19, v150
	v_mul_f32_e32 v17, v20, v31
	v_cvt_pk_bf16_f32 v19, v16, v17
	v_mul_f32_e32 v16, 0x3fb8aa3b, v129
	v_exp_f32_e32 v16, v16
	v_mul_f32_e32 v17, 0x3fb8aa3b, v130
	v_exp_f32_e32 v17, v17
	v_mul_f32_e32 v20, 0x3e13cd3a, v147
	v_mul_f32_e32 v16, v20, v16
	v_mul_f32_e32 v20, 0x3e13cd3a, v52
	v_mul_f32_e32 v17, v20, v17
	v_mul_f32_e32 v20, 0xbfb8aa3b, v129
	v_cvt_pk_bf16_f32 v16, v16, v17
	v_mul_f32_e32 v17, 0xbfb8aa3b, v130
	v_exp_f32_e32 v20, v20
	v_exp_f32_e32 v17, v17
	v_mul_f32_e32 v31, 0xbfb8aa3b, v139
	v_exp_f32_e32 v31, v31
	v_mul_f32_e32 v20, v20, v151
	v_mul_f32_e32 v17, v17, v32
	v_cvt_pk_bf16_f32 v20, v20, v17
	v_mul_f32_e32 v17, 0x3e13cd3a, v148
	v_mul_f32_e32 v17, v17, v21
	v_mul_f32_e32 v21, 0x3e13cd3a, v53
	v_mul_f32_e32 v21, v21, v22
	v_cvt_pk_bf16_f32 v17, v17, v21
	v_mul_f32_e32 v21, v23, v152
	v_mul_f32_e32 v22, v24, v33
	v_cvt_pk_bf16_f32 v21, v21, v22
	v_mul_f32_e32 v22, 0x3fb8aa3b, v133
	v_exp_f32_e32 v22, v22
	v_mul_f32_e32 v23, 0x3fb8aa3b, v134
	v_exp_f32_e32 v23, v23
	v_mul_f32_e32 v24, 0x3e13cd3a, v153
	v_mul_f32_e32 v22, v24, v22
	v_mul_f32_e32 v24, 0x3e13cd3a, v26
	v_mul_f32_e32 v23, v24, v23
	v_cvt_pk_bf16_f32 v22, v22, v23
	v_mul_f32_e32 v23, 0xbfb8aa3b, v134
	v_mul_f32_e32 v24, 0xbfb8aa3b, v133
	v_exp_f32_e32 v23, v23
	v_exp_f32_e32 v24, v24
	v_mul_f32_e32 v32, 0xbfb8aa3b, v140
	v_exp_f32_e32 v32, v32
	v_mul_f32_e32 v23, v23, v158
	v_mul_f32_e32 v24, v24, v157
	v_cvt_pk_bf16_f32 v26, v24, v23
	v_mul_f32_e32 v23, 0x3e13cd3a, v154
	v_mul_f32_e32 v23, v23, v25
	v_mul_f32_e32 v25, 0x3fb8aa3b, v136
	v_mul_f32_e32 v24, 0x3e13cd3a, v27
	v_exp_f32_e32 v25, v25
	v_mul_f32_e32 v27, 0xbfb8aa3b, v135
	v_exp_f32_e32 v27, v27
	v_mul_f32_e32 v33, 0x3fb8aa3b, v143
	v_mul_f32_e32 v24, v24, v25
	v_cvt_pk_bf16_f32 v23, v23, v24
	v_mul_f32_e32 v24, v27, v159
	v_mul_f32_e32 v25, v30, v160
	v_cvt_pk_bf16_f32 v27, v24, v25
	v_mul_f32_e32 v24, 0x3fb8aa3b, v137
	v_mul_f32_e32 v25, 0x3fb8aa3b, v138
	v_exp_f32_e32 v24, v24
	v_exp_f32_e32 v25, v25
	v_mul_f32_e32 v30, 0x3e13cd3a, v155
	v_exp_f32_e32 v33, v33
	v_mul_f32_e32 v24, v30, v24
	v_mul_f32_e32 v25, v28, v25
	v_mul_f32_e32 v28, 0xbfb8aa3b, v137
	v_cvt_pk_bf16_f32 v24, v24, v25
	v_mul_f32_e32 v25, 0xbfb8aa3b, v138
	v_exp_f32_e32 v28, v28
	v_exp_f32_e32 v25, v25
	v_mul_f32_e32 v30, 0x3fb8aa3b, v139
	v_exp_f32_e32 v30, v30
	v_mul_f32_e32 v28, v28, v161
	v_mul_f32_e32 v25, v25, v162
	v_cvt_pk_bf16_f32 v28, v28, v25
	v_mul_f32_e32 v25, 0x3e13cd3a, v156
	v_mul_f32_e32 v25, v25, v30
	v_mul_f32_e32 v30, 0x3fb8aa3b, v140
	v_exp_f32_e32 v30, v30
	v_mul_f32_e32 v40, 0xbfb8aa3b, v143
	v_exp_f32_e32 v40, v40
	v_mul_f32_e32 v41, 0xbfb8aa3b, v144
	v_mul_f32_e32 v29, v29, v30
	v_cvt_pk_bf16_f32 v25, v25, v29
	v_mul_f32_e32 v29, v31, v163
	v_mul_f32_e32 v30, v32, v164
	v_cvt_pk_bf16_f32 v29, v29, v30
	v_mul_f32_e32 v30, 0x3fb8aa3b, v141
	v_exp_f32_e32 v30, v30
	v_mul_f32_e32 v31, 0x3fb8aa3b, v142
	v_exp_f32_e32 v31, v31
	v_mul_f32_e32 v32, 0x3e13cd3a, v165
	v_mul_f32_e32 v30, v32, v30
	v_mul_f32_e32 v32, 0x3e13cd3a, v166
	v_mul_f32_e32 v31, v32, v31
	v_cvt_pk_bf16_f32 v30, v30, v31
	v_mul_f32_e32 v31, 0xbfb8aa3b, v142
	v_mul_f32_e32 v32, 0xbfb8aa3b, v141
	v_exp_f32_e32 v31, v31
	v_exp_f32_e32 v32, v32
	v_exp_f32_e32 v41, v41
	v_readlane_b32 s0, v255, 9
	v_mul_f32_e32 v31, v31, v174
	v_mul_f32_e32 v32, v32, v173
	v_cvt_pk_bf16_f32 v50, v32, v31
	v_mul_f32_e32 v31, 0x3e13cd3a, v167
	v_mul_f32_e32 v31, v31, v33
	v_mul_f32_e32 v33, 0x3fb8aa3b, v144
	v_exp_f32_e32 v33, v33
	v_mul_f32_e32 v32, 0x3e13cd3a, v168
	v_readlane_b32 s1, v255, 10
	v_mul_f32_e32 v32, v32, v33
	v_cvt_pk_bf16_f32 v31, v31, v32
	v_mul_f32_e32 v32, v40, v175
	v_mul_f32_e32 v33, v41, v176
	v_cvt_pk_bf16_f32 v51, v32, v33
	v_mul_f32_e32 v32, 0x3fb8aa3b, v145
	v_exp_f32_e32 v32, v32
	v_mul_f32_e32 v33, 0x3fb8aa3b, v146
	v_exp_f32_e32 v33, v33
	v_mul_f32_e32 v40, 0x3e13cd3a, v169
	v_mul_f32_e32 v32, v40, v32
	v_mul_f32_e32 v40, 0x3e13cd3a, v170
	v_mul_f32_e32 v33, v40, v33
	v_cvt_pk_bf16_f32 v32, v32, v33
	v_mul_f32_e32 v33, 0xbfb8aa3b, v146
	v_mul_f32_e32 v40, 0xbfb8aa3b, v145
	v_exp_f32_e32 v33, v33
	v_exp_f32_e32 v40, v40
	v_mul_f32_e32 v41, 0x3fb8aa3b, v39
	v_exp_f32_e32 v41, v41
	v_mul_f32_e32 v33, v33, v178
	v_mul_f32_e32 v40, v40, v177
	v_cvt_pk_bf16_f32 v52, v40, v33
	v_mul_f32_e32 v33, 0x3e13cd3a, v171
	v_mul_f32_e32 v33, v33, v41
	v_mul_f32_e32 v41, 0x3fb8aa3b, v38
	v_mul_f32_e32 v39, 0xbfb8aa3b, v39
	v_mul_f32_e32 v38, 0xbfb8aa3b, v38
	v_exp_f32_e32 v39, v39
	v_exp_f32_e32 v38, v38
	v_exp_f32_e32 v41, v41
	v_mul_f32_e32 v40, 0x3e13cd3a, v172
	v_mul_f32_e32 v39, v39, v179
	v_mul_f32_e32 v38, v38, v180
	v_cvt_pk_bf16_f32 v53, v39, v38
	v_mul_f32_e32 v40, v40, v41
	v_cvt_pk_bf16_f32 v33, v33, v40
	ds_write_b128 v90, v[14:17] offset:128
	ds_write_b128 v92, v[18:21] offset:54784
	ds_write_b128 v90, v[22:25] offset:144
	ds_write_b128 v92, v[26:29] offset:54800
	ds_write_b128 v90, v[30:33] offset:160
	ds_write_b128 v92, v[50:53] offset:54816
	ds_write_b128 v116, v[2:5] offset:21504
	ds_write_b128 v117, v[6:9] offset:21504
	ds_write_b128 v118, v[10:13] offset:21504
	ds_write_b64 v93, v[62:63] offset:34816
	ds_write_b64 v94, v[64:65] offset:34816
	ds_write_b64 v96, v[66:67] offset:34816
	ds_write_b64 v97, v[68:69] offset:34816
	ds_write_b64 v98, v[78:79] offset:34816
	ds_write_b64 v99, v[72:73] offset:44800
	ds_write_b64 v100, v[74:75] offset:44800
	ds_write_b64 v101, v[76:77] offset:44800
	ds_write_b64 v102, v[70:71] offset:44800
	s_waitcnt lgkmcnt(0)
	s_barrier
; __device__ __forceinline__ unsigned cvtpk(float lo, float hi) { unsigned r; asm("v_cvt_pk_bf16_f32 %0, %1, %2" : "=v"(r) : "v"(lo), "v"(hi)); return r; }
; template <bool PHC>
; __device__ __forceinline__ void gla_pair(const KPD& kp, int l, int pair, unsigned char* lds, int tid, int lane, int wave, v4u& pz0, v4u& pz1, v4u& pw0, v4u& pw1, int next_pair) {
;     ...
;         __syncthreads();
;         { const int rt = w4 >> 1, ct = w4 & 1, r32 = lane & 31, hi = lane >> 5;
;           f32x16 af, ab;
; #pragma unroll
;           for (int r = 0; r < 16; ++r) { af[r] = 0.f; ab[r] = 0.f; }
; #pragma unroll
;           for (int ks = 0; ks < 3; ++ks) {
;               const bf16x8 a0 = *(const bf16x8*)(AC + (32 * rt + r32) * 168 + 64 + 16 * ks + 8 * hi);
;               const bf16x8 b0 = *(const bf16x8*)(KI + (32 * ct + r32) * 56 + 16 * ks + 8 * hi);
;               af = __builtin_amdgcn_mfma_f32_32x32x16_bf16(a0, b0, af, 0, 0, 0);
;               const bf16x8 a1 = *(const bf16x8*)(AC + (32 * rt + r32) * 168 + 112 + 16 * ks + 8 * hi);
;               const bf16x8 b1 = *(const bf16x8*)(KI + (64 + 32 * ct + r32) * 56 + 16 * ks + 8 * hi);
;               ab = __builtin_amdgcn_mfma_f32_32x32x16_bf16(a1, b1, ab, 0, 0, 0); }
;           const int j = 32 * ct + r32;
; #pragma unroll
;           for (int r = 0; r < 16; ++r) { const int i = 32 * rt + (r & 3) + 8 * (r >> 2) + 4 * hi;
;               const float val = ((j <= i) ? af[r] : 0.f) + ((j >= i) ? ab[r] : 0.f);
;               AC[i * 168 + j] = (bf16)(cvtpk(val, val) & 0xffffu); } }
;         const int fr = lane & 15, fq = lane >> 4;
;         unsigned short gpre[4][6];
; #pragma unroll
;         for (int r = 0; r < 4; ++r)
; #pragma unroll
;             for (int ct = 0; ct < 6; ++ct) gpre[r][ct] = P[(size_t)(rowbase + 16 * w4 + 4 * fq + r) * INP + C_GG + h * 96 + 16 * ct + fr];
;         __syncthreads();
;         if (next_pair >= 0) gla_prefetch(pz0, pz1, pw0, pw1, kp, l, next_pair, lane, wave);
	ds_read_b128 v[2:5], v103 offset:128
	ds_read_b128 v[6:9], v104 offset:54784
	ds_read_b128 v[50:53], v103 offset:160
	ds_read_b128 v[62:65], v104 offset:54816
	s_waitcnt lgkmcnt(2)
	v_mfma_f32_32x32x16_bf16 v[2:17], v[2:5], v[6:9], 0
	ds_read_b128 v[18:21], v103 offset:224
	ds_read_b128 v[22:25], v104 offset:61952
	ds_read_b128 v[66:69], v103 offset:192
	ds_read_b128 v[70:73], v104 offset:54848
	s_waitcnt lgkmcnt(2)
	v_mfma_f32_32x32x16_bf16 v[18:33], v[18:21], v[22:25], 0
	v_mfma_f32_32x32x16_bf16 v[2:17], v[50:53], v[62:65], v[2:17]
	ds_read_b128 v[50:53], v103 offset:256
	ds_read_b128 v[62:65], v104 offset:61984
	ds_read_b128 v[74:77], v103 offset:288
	ds_read_b128 v[128:131], v104 offset:62016
	s_waitcnt lgkmcnt(2)
	v_mfma_f32_32x32x16_bf16 v[18:33], v[50:53], v[62:65], v[18:33]
	v_add_u32_e32 v64, s80, v105
	v_add_u32_e32 v62, 1, v64
	v_mfma_f32_32x32x16_bf16 v[2:17], v[66:69], v[70:73], v[2:17]
	v_lshlrev_b32_e32 v66, 1, v36
	v_mov_b32_e32 v67, v35
	s_waitcnt lgkmcnt(0)
	v_mfma_f32_32x32x16_bf16 v[18:33], v[74:77], v[128:131], v[18:33]
	s_nop 7
	v_cndmask_b32_e64 v2, v2, 0, s[6:7]
	s_nop 2
	v_cndmask_b32_e64 v18, v18, 0, s[0:1]
	v_mad_i64_i32 v[50:51], s[0:1], v64, s33, v[60:61]
	v_mad_i64_i32 v[52:53], s[0:1], v62, s33, v[60:61]
	v_add_f32_e32 v2, v2, v18
	v_lshl_add_u64 v[50:51], v[50:51], 0, s[8:9]
	v_lshl_add_u64 v[52:53], v[52:53], 0, s[8:9]
	v_cvt_pk_bf16_f32 v2, v2, v2
	ds_write_b16 v119, v2
	v_lshl_add_u64 v[50:51], v[50:51], 0, v[66:67]
	v_lshl_add_u64 v[68:69], v[52:53], 0, v[66:67]
	v_add_u32_e32 v52, 2, v64
	global_load_ushort v136, v[50:51], off offset:1536
	global_load_ushort v135, v[50:51], off offset:1568
	global_load_ushort v134, v[50:51], off offset:1600
	global_load_ushort v133, v[50:51], off offset:1632
	global_load_ushort v131, v[50:51], off offset:1664
	global_load_ushort v129, v[50:51], off offset:1696
	global_load_ushort v128, v[68:69], off offset:1536
	global_load_ushort v79, v[68:69], off offset:1568
	v_mad_i64_i32 v[50:51], s[0:1], v52, s33, v[60:61]
	v_lshl_add_u64 v[50:51], v[50:51], 0, s[8:9]
	v_lshl_add_u64 v[138:139], v[50:51], 0, v[66:67]
	v_add_u32_e32 v50, 3, v64
	v_mad_i64_i32 v[60:61], s[0:1], v50, s33, v[60:61]
	v_lshl_add_u64 v[60:61], v[60:61], 0, s[8:9]
	global_load_ushort v78, v[68:69], off offset:1600
	global_load_ushort v77, v[68:69], off offset:1632
	global_load_ushort v76, v[68:69], off offset:1664
	global_load_ushort v75, v[68:69], off offset:1696
	global_load_ushort v74, v[138:139], off offset:1536
	global_load_ushort v73, v[138:139], off offset:1568
	global_load_ushort v72, v[138:139], off offset:1600
	global_load_ushort v71, v[138:139], off offset:1632
	v_lshl_add_u64 v[140:141], v[60:61], 0, v[66:67]
	global_load_ushort v70, v[138:139], off offset:1664
	global_load_ushort v69, v[138:139], off offset:1696
	global_load_ushort v68, v[140:141], off offset:1536
	global_load_ushort v61, v[140:141], off offset:1568
	global_load_ushort v60, v[140:141], off offset:1600
	global_load_ushort v59, v[140:141], off offset:1632
	global_load_ushort v57, v[140:141], off offset:1664
	global_load_ushort v55, v[140:141], off offset:1696
	v_readlane_b32 s0, v255, 11
	v_readlane_b32 s1, v255, 12
	s_nop 1
	v_cndmask_b32_e64 v2, v3, 0, s[0:1]
	v_cndmask_b32_e64 v3, 0, v19, s[6:7]
	v_add_f32_e32 v2, v2, v3
	v_readlane_b32 s0, v255, 13
	v_cvt_pk_bf16_f32 v2, v2, v2
	v_readlane_b32 s1, v255, 14
	ds_write_b16 v119, v2 offset:336
	s_nop 0
	v_cndmask_b32_e64 v2, v4, 0, s[0:1]
	v_readlane_b32 s0, v255, 15
	v_readlane_b32 s1, v255, 16
	s_nop 1
	v_cndmask_b32_e64 v3, v20, 0, s[0:1]
	v_add_f32_e32 v2, v2, v3
	v_cvt_pk_bf16_f32 v2, v2, v2
	ds_write_b16 v119, v2 offset:672
	v_cndmask_b32_e64 v2, v5, 0, s[16:17]
	v_cndmask_b32_e64 v3, v21, 0, s[18:19]
	v_add_f32_e32 v2, v2, v3
	v_cvt_pk_bf16_f32 v2, v2, v2
	ds_write_b16 v119, v2 offset:1008
	v_cndmask_b32_e64 v2, v6, 0, s[20:21]
	v_cndmask_b32_e64 v3, v22, 0, s[22:23]
	v_add_f32_e32 v2, v2, v3
	v_cvt_pk_bf16_f32 v2, v2, v2
	ds_write_b16 v119, v2 offset:2688
	v_cndmask_b32_e64 v2, v7, 0, s[24:25]
	v_cndmask_b32_e64 v3, v23, 0, s[26:27]
	v_add_f32_e32 v2, v2, v3
	v_cvt_pk_bf16_f32 v2, v2, v2
	ds_write_b16 v119, v2 offset:3024
	v_cndmask_b32_e64 v2, v8, 0, s[28:29]
	v_cndmask_b32_e64 v3, v24, 0, s[30:31]
	v_add_f32_e32 v2, v2, v3
	v_cvt_pk_bf16_f32 v2, v2, v2
	ds_write_b16 v119, v2 offset:3360
	v_cndmask_b32_e64 v2, v9, 0, s[34:35]
	v_cndmask_b32_e64 v3, v25, 0, s[36:37]
	v_add_f32_e32 v2, v2, v3
	v_cvt_pk_bf16_f32 v2, v2, v2
	ds_write_b16 v119, v2 offset:3696
	v_cndmask_b32_e64 v2, v10, 0, s[38:39]
	v_cndmask_b32_e64 v3, v26, 0, s[40:41]
	v_add_f32_e32 v2, v2, v3
	v_cvt_pk_bf16_f32 v2, v2, v2
	ds_write_b16 v119, v2 offset:5376
	v_cndmask_b32_e64 v2, v11, 0, s[42:43]
	v_cndmask_b32_e64 v3, v27, 0, s[44:45]
	v_add_f32_e32 v2, v2, v3
	v_cvt_pk_bf16_f32 v2, v2, v2
	ds_write_b16 v119, v2 offset:5712
	v_cndmask_b32_e64 v2, v12, 0, s[46:47]
	v_cndmask_b32_e64 v3, v28, 0, s[48:49]
	v_add_f32_e32 v2, v2, v3
	v_cvt_pk_bf16_f32 v2, v2, v2
	ds_write_b16 v119, v2 offset:6048
	v_cndmask_b32_e64 v2, v13, 0, s[50:51]
	v_cndmask_b32_e64 v3, v29, 0, s[52:53]
	v_add_f32_e32 v2, v2, v3
	v_cvt_pk_bf16_f32 v2, v2, v2
	ds_write_b16 v119, v2 offset:6384
	v_cndmask_b32_e64 v2, v14, 0, s[54:55]
	v_cndmask_b32_e64 v3, v30, 0, s[56:57]
	v_add_f32_e32 v2, v2, v3
	v_cvt_pk_bf16_f32 v2, v2, v2
	ds_write_b16 v119, v2 offset:8064
	v_cndmask_b32_e64 v2, v15, 0, s[84:85]
	v_cndmask_b32_e64 v3, v31, 0, s[60:61]
	v_add_f32_e32 v2, v2, v3
	v_cvt_pk_bf16_f32 v2, v2, v2
	ds_write_b16 v119, v2 offset:8400
	v_cndmask_b32_e64 v2, v16, 0, s[62:63]
	v_cndmask_b32_e64 v3, v32, 0, s[64:65]
	v_add_f32_e32 v2, v2, v3
	v_cvt_pk_bf16_f32 v2, v2, v2
	ds_write_b16 v119, v2 offset:8736
	v_cndmask_b32_e64 v2, v17, 0, s[66:67]
	v_cndmask_b32_e64 v3, v33, 0, s[68:69]
	v_add_f32_e32 v2, v2, v3
	v_cvt_pk_bf16_f32 v2, v2, v2
	ds_write_b16 v119, v2 offset:9072
	s_waitcnt lgkmcnt(0)
	s_barrier
	s_cbranch_scc1 .LBB0_465
	s_lshl_b32 s2, s77, 1
	s_add_i32 s2, s2, s89
	s_ashr_i32 s9, s2, 2
	s_cmpk_gt_i32 s9, 0x1ff
	s_mov_b64 s[0:1], -1
	s_cbranch_scc0 .LBB0_462
	s_lshl_b32 s0, s9, 6
	s_bfe_u32 s3, s2, 0x20002
	s_and_b32 s8, s0, 0xffffff00
	s_mov_b64 s[0:1], 0

; __global__ void __launch_bounds__(512, 2) fwd_kernel(KP kparg) {
;     extern __shared__ __attribute__((aligned(16))) unsigned char lds[];
;     int tid = threadIdx.x, lane = tid & 63, wave = __builtin_amdgcn_readfirstlane(tid >> 6);
	.amdhsa_kernel _Z10fwd_kernel2KP
		.amdhsa_group_segment_fixed_size 0
		.amdhsa_private_segment_fixed_size 0
		.amdhsa_kernarg_size 448
		.amdhsa_user_sgpr_count 2
		.amdhsa_user_sgpr_dispatch_ptr 0
		.amdhsa_user_sgpr_queue_ptr 0
		.amdhsa_user_sgpr_kernarg_segment_ptr 1
		.amdhsa_user_sgpr_dispatch_id 0
		.amdhsa_user_sgpr_kernarg_preload_length 0
		.amdhsa_user_sgpr_kernarg_preload_offset 0
		.amdhsa_user_sgpr_private_segment_size 0
		.amdhsa_uses_dynamic_stack 0
		.amdhsa_enable_private_segment 0
		.amdhsa_system_sgpr_workgroup_id_x 1
		.amdhsa_system_sgpr_workgroup_id_y 0
		.amdhsa_system_sgpr_workgroup_id_z 0
		.amdhsa_system_sgpr_workgroup_info 0
		.amdhsa_system_vgpr_workitem_id 0
		.amdhsa_next_free_vgpr 256
		.amdhsa_next_free_sgpr 102
		.amdhsa_accum_offset 256
		.amdhsa_reserve_vcc 1
		.amdhsa_float_round_mode_32 0
		.amdhsa_float_round_mode_16_64 0
		.amdhsa_float_denorm_mode_32 3
		.amdhsa_float_denorm_mode_16_64 3
		.amdhsa_dx10_clamp 1
		.amdhsa_ieee_mode 1
		.amdhsa_fp16_overflow 0
		.amdhsa_tg_split 0
		.amdhsa_exception_fp_ieee_invalid_op 0
		.amdhsa_exception_fp_denorm_src 0
		.amdhsa_exception_fp_ieee_div_zero 0
		.amdhsa_exception_fp_ieee_overflow 0
		.amdhsa_exception_fp_ieee_underflow 0
		.amdhsa_exception_fp_ieee_inexact 0
		.amdhsa_exception_int_div_zero 0
	.end_amdhsa_kernel

; __global__ void __launch_bounds__(512, 2) fwd_kernel(KP kparg) {
;     extern __shared__ __attribute__((aligned(16))) unsigned char lds[];
;     int tid = threadIdx.x, lane = tid & 63, wave = __builtin_amdgcn_readfirstlane(tid >> 6);
amdhsa.kernels:
  - .agpr_count:     0
    .args:
      - .offset:         0
        .size:           192
        .value_kind:     by_value
      - .offset:         192
        .size:           4
        .value_kind:     hidden_block_count_x
      - .offset:         196
        .size:           4
        .value_kind:     hidden_block_count_y
      - .offset:         200
        .size:           4
        .value_kind:     hidden_block_count_z
      - .offset:         204
        .size:           2
        .value_kind:     hidden_group_size_x
      - .offset:         206
        .size:           2
        .value_kind:     hidden_group_size_y
      - .offset:         208
        .size:           2
        .value_kind:     hidden_group_size_z
      - .offset:         210
        .size:           2
        .value_kind:     hidden_remainder_x
      - .offset:         212
        .size:           2
        .value_kind:     hidden_remainder_y
      - .offset:         214
        .size:           2
        .value_kind:     hidden_remainder_z
      - .offset:         232
        .size:           8
        .value_kind:     hidden_global_offset_x
      - .offset:         240
        .size:           8
        .value_kind:     hidden_global_offset_y
      - .offset:         248
        .size:           8
        .value_kind:     hidden_global_offset_z
      - .offset:         256
        .size:           2
        .value_kind:     hidden_grid_dims
      - .offset:         312
        .size:           4
        .value_kind:     hidden_dynamic_lds_size
    .group_segment_fixed_size: 0
    .kernarg_segment_align: 8
    .kernarg_segment_size: 448
    .language:       OpenCL C
    .language_version:
      - 2
      - 0
    .max_flat_workgroup_size: 512
    .name:           _Z10fwd_kernel2KP
    .private_segment_fixed_size: 0
    .sgpr_count:     108
    .sgpr_spill_count: 172
    .symbol:         _Z10fwd_kernel2KP.kd
    .uniform_work_group_size: 1
    .uses_dynamic_stack: false
    .vgpr_count:     256
    .vgpr_spill_count: 0
    .wavefront_size: 64
